# stack8: stack7 + in-proj epilogue: rope cos/sin loads hoisted (q and k heads), gelu constant folding
# speedup vs baseline: 1.0089x; 1.0089x over previous
; #define WAIT_V0() asm volatile("s_waitcnt vmcnt(0)" ::: "memory")
; #define G_STAGE_A(Ap, buf, kt) do { const char* ab_ = (const char*)(Ap) + (size_t)(kt) * 128; \
;       _Pragma("unroll") for (int i = 0; i < 4; ++i) \
;         __builtin_amdgcn_global_load_lds((const unsigned*)(ab_ + soff[i]), (LDSP unsigned*)(G_SA(buf) + wid * 1024 + i * 8192), 16, 0, 0); } while (0)
; #define G_STAGE_B(Bp, buf, kt) do { const char* bb_ = (const char*)(Bp) + (size_t)(kt) * 128; \
;       _Pragma("unroll") for (int i = 0; i < 4; ++i) \
;         __builtin_amdgcn_global_load_lds((const unsigned*)(bb_ + soff[i]), (LDSP unsigned*)(G_SB(buf) + wid * 1024 + i * 8192), 16, 0, 0); } while (0)
; #define G_RDA(AF, buf, ks, mh) do { _Pragma("unroll") for (int m = 0; m < 4; ++m) AF[m] = *(const LDSP bf16x8*)(G_SA(buf) + aoff + ((mh) * 4 + m) * 2048 + (ks) * 1024); } while (0)
; #define G_RDB(BF, buf, ks) do { _Pragma("unroll") for (int n = 0; n < 4; ++n) BF[n] = *(const LDSP bf16x8*)(G_SB(buf) + boff + n * 2048 + (ks) * 1024); } while (0)
; #define G_MMA(AF, BF, mh) do { __builtin_amdgcn_s_setprio(1); \
;             _Pragma("unroll") for (int m = 0; m < 4; ++m) _Pragma("unroll") for (int n = 0; n < 4; ++n) \
;                 acc[(mh) * 4 + m][n] = __builtin_amdgcn_mfma_f32_16x16x32_bf16(BF[n], AF[m], acc[(mh) * 4 + m][n], 0, 0, 0); \
;             __builtin_amdgcn_s_setprio(0); } while (0)
; template <int EK>
; DI void gemm_stream(const Params& p, int l, const bf16_t* __restrict__ A, const bf16_t* __restrict__ Bt, int M, int N, int K, ldsp_t shm) {
;     ...
;         for (int t = 0; t < nt; ++t) {
;             const int cur = t & 1;
;             G_RDA(Aa, cur, 0, 0); G_RDB(Bk0, cur, 0);
;             if (t + 1 < nt) G_STAGE_B(Bb, cur ^ 1, t + 1);
;             else if (has_next) G_STAGE_B(Bb2, cur ^ 1, 0);
;             G_SB0();
;             if (t > 0) G_MMA(Ab_, Bk1, 1);
;             G_SB0();
;             if (t + 1 < nt) G_STAGE_A(Ab, cur ^ 1, t + 1);
;             else if (has_next) G_STAGE_A(Ab2, cur ^ 1, 0);
;             G_RDA(Ab_, cur, 0, 1);
;             G_MMA(Aa, Bk0, 0); G_SB0();
;             G_RDA(Aa, cur, 1, 0); G_RDB(Bk1, cur, 1);
;             G_MMA(Ab_, Bk0, 1); G_SB0();
;             G_RDA(Ab_, cur, 1, 1);
;             G_MMA(Aa, Bk1, 0); G_SB0();
;             asm volatile("s_waitcnt lgkmcnt(0)" ::: "memory");
;             WAIT_V0(); __syncthreads();
.LBB0_269:
	v_add_u32_e32 v80, 0x12000, v218
	v_add_u32_e32 v132, 0x12800, v218
	v_add_u32_e32 v136, 0x13000, v218
	v_add_u32_e32 v140, 0x13800, v218
	ds_read_b128 v[80:83], v80
	ds_read_b128 v[132:135], v132
	ds_read_b128 v[136:139], v136
	ds_read_b128 v[140:143], v140
	s_setprio 1
	s_waitcnt lgkmcnt(0)
	v_mfma_f32_16x16x32_bf16 v[20:23], v[164:167], v[180:183], v[20:23]
	v_mfma_f32_16x16x32_bf16 v[24:27], v[168:171], v[180:183], v[24:27]
	v_mfma_f32_16x16x32_bf16 v[28:31], v[172:175], v[180:183], v[28:31]
	v_mfma_f32_16x16x32_bf16 v[44:47], v[172:175], v[184:187], v[44:47]
	v_mfma_f32_16x16x32_bf16 v[48:51], v[160:163], v[176:179], v[48:51]
	v_mfma_f32_16x16x32_bf16 v[52:55], v[164:167], v[176:179], v[52:55]
	v_mfma_f32_16x16x32_bf16 v[56:59], v[168:171], v[176:179], v[56:59]
	v_mfma_f32_16x16x32_bf16 v[60:63], v[172:175], v[176:179], v[60:63]
	v_mfma_f32_16x16x32_bf16 v[0:3], v[160:163], v[188:191], v[0:3]
	v_mfma_f32_16x16x32_bf16 v[4:7], v[164:167], v[188:191], v[4:7]
	v_mfma_f32_16x16x32_bf16 v[8:11], v[168:171], v[188:191], v[8:11]
	v_mfma_f32_16x16x32_bf16 v[12:15], v[172:175], v[188:191], v[12:15]
	v_mfma_f32_16x16x32_bf16 v[16:19], v[160:163], v[180:183], v[16:19]
	v_mfma_f32_16x16x32_bf16 v[32:35], v[160:163], v[184:187], v[32:35]
	v_mfma_f32_16x16x32_bf16 v[36:39], v[164:167], v[184:187], v[36:39]
	v_mfma_f32_16x16x32_bf16 v[40:43], v[168:171], v[184:187], v[40:43]
	s_setprio 0
	v_add_u32_e32 v144, 0x10400, v218
	v_add_u32_e32 v148, 0x10c00, v218
	v_add_u32_e32 v152, 0x11400, v218
	v_add_u32_e32 v156, 0x11c00, v218
	v_add_u32_e32 v176, 0x18400, v219
	v_add_u32_e32 v180, 0x18c00, v219
	v_add_u32_e32 v184, 0x19400, v219
	v_add_u32_e32 v188, 0x19c00, v219
	ds_read_b128 v[144:147], v144
	ds_read_b128 v[148:151], v148
	ds_read_b128 v[152:155], v152
	ds_read_b128 v[156:159], v156
	ds_read_b128 v[176:179], v176
	ds_read_b128 v[180:183], v180
	ds_read_b128 v[184:187], v184
	ds_read_b128 v[188:191], v188
	s_setprio 1
	v_mfma_f32_16x16x32_bf16 v[128:131], v[160:163], v[80:83], v[128:131]
	v_mfma_f32_16x16x32_bf16 v[124:127], v[164:167], v[80:83], v[124:127]
	v_mfma_f32_16x16x32_bf16 v[120:123], v[168:171], v[80:83], v[120:123]
	v_mfma_f32_16x16x32_bf16 v[116:119], v[172:175], v[80:83], v[116:119]
	v_mfma_f32_16x16x32_bf16 v[112:115], v[160:163], v[132:135], v[112:115]
	v_mfma_f32_16x16x32_bf16 v[194:197], v[164:167], v[132:135], v[108:111]
	v_mfma_f32_16x16x32_bf16 v[214:217], v[168:171], v[132:135], v[104:107]
	v_mfma_f32_16x16x32_bf16 v[132:135], v[172:175], v[132:135], v[100:103]
	v_mfma_f32_16x16x32_bf16 v[220:223], v[160:163], v[136:139], v[96:99]
	v_mfma_f32_16x16x32_bf16 v[224:227], v[164:167], v[136:139], v[92:95]
	v_mfma_f32_16x16x32_bf16 v[228:231], v[168:171], v[136:139], v[88:91]
	v_mfma_f32_16x16x32_bf16 v[136:139], v[172:175], v[136:139], v[84:87]
	v_mfma_f32_16x16x32_bf16 v[160:163], v[160:163], v[140:143], v[64:67]
	v_mfma_f32_16x16x32_bf16 v[164:167], v[164:167], v[140:143], v[68:71]
	v_mfma_f32_16x16x32_bf16 v[168:171], v[168:171], v[140:143], v[76:79]
	v_mfma_f32_16x16x32_bf16 v[140:143], v[172:175], v[140:143], v[72:75]
	s_setprio 0
	v_add_u32_e32 v64, 0x12400, v218
	v_add_u32_e32 v68, 0x12c00, v218
	ds_read_b128 v[64:67], v64
	ds_read_b128 v[172:175], v68
	v_add_u32_e32 v68, 0x13400, v218
	v_add_u32_e32 v69, 0x13c00, v218
	ds_read_b128 v[232:235], v68
	ds_read_b128 v[236:239], v69
	s_setprio 1
	s_waitcnt lgkmcnt(0)
	v_mfma_f32_16x16x32_bf16 v[240:243], v[176:179], v[144:147], v[0:3]
	v_mfma_f32_16x16x32_bf16 v[244:247], v[180:183], v[144:147], v[4:7]
	v_mfma_f32_16x16x32_bf16 v[248:251], v[184:187], v[144:147], v[8:11]
	v_mfma_f32_16x16x32_bf16 v[144:147], v[188:191], v[144:147], v[12:15]
	v_mfma_f32_16x16x32_bf16 v[108:111], v[176:179], v[152:155], v[32:35]
	v_mfma_f32_16x16x32_bf16 v[104:107], v[180:183], v[152:155], v[36:39]
	v_mfma_f32_16x16x32_bf16 v[100:103], v[184:187], v[152:155], v[40:43]
	v_mfma_f32_16x16x32_bf16 v[96:99], v[188:191], v[152:155], v[44:47]
	v_mfma_f32_16x16x32_bf16 v[92:95], v[176:179], v[156:159], v[48:51]
	v_mfma_f32_16x16x32_bf16 v[88:91], v[180:183], v[156:159], v[52:55]
	v_mfma_f32_16x16x32_bf16 v[84:87], v[184:187], v[156:159], v[56:59]
	v_mfma_f32_16x16x32_bf16 v[80:83], v[188:191], v[156:159], v[60:63]
	v_mfma_f32_16x16x32_bf16 v[210:213], v[176:179], v[148:151], v[16:19]
	v_mfma_f32_16x16x32_bf16 v[204:207], v[180:183], v[148:151], v[20:23]
	v_mfma_f32_16x16x32_bf16 v[198:201], v[184:187], v[148:151], v[24:27]
	v_mfma_f32_16x16x32_bf16 v[148:151], v[188:191], v[148:151], v[28:31]
	s_setprio 0
	s_waitcnt lgkmcnt(0)
	s_waitcnt vmcnt(0)
	s_waitcnt vmcnt(0)
	s_barrier
; #define G_STAGE_B(Bp, buf, kt) do { const char* bb_ = (const char*)(Bp) + (size_t)(kt) * 128; \
;       _Pragma("unroll") for (int i = 0; i < 4; ++i) \
;         __builtin_amdgcn_global_load_lds((const unsigned*)(bb_ + soff[i]), (LDSP unsigned*)(G_SB(buf) + wid * 1024 + i * 8192), 16, 0, 0); } while (0)
; #define G_MMA(AF, BF, mh) do { __builtin_amdgcn_s_setprio(1); \
;             _Pragma("unroll") for (int m = 0; m < 4; ++m) _Pragma("unroll") for (int n = 0; n < 4; ++n) \
;                 acc[(mh) * 4 + m][n] = __builtin_amdgcn_mfma_f32_16x16x32_bf16(BF[n], AF[m], acc[(mh) * 4 + m][n], 0, 0, 0); \
;             __builtin_amdgcn_s_setprio(0); } while (0)
; template <int EK>
; DI void gemm_stream(const Params& p, int l, const bf16_t* __restrict__ A, const bf16_t* __restrict__ Bt, int M, int N, int K, ldsp_t shm) {
;     ...
;         G_MMA(Ab_, Bk1, 1);
;         G_SB0();
;         {
;             int tid2 = threadIdx.x, pme = pm, pne = pn;
;             asm volatile("" : "+v"(tid2), "+s"(pme), "+s"(pne));
;             TileCtx tc;
;             tc.wid = tid2 >> 6; tc.lane = tid2 & 63; tc.wr = tc.wid >> 2; tc.wc = tc.wid & 3; tc.fr = tc.lane & 15; tc.fq = tc.lane >> 4; tc.l = l;
;             tc.brow = pme * 256; tc.bcol = pne * 256; tc.pn = pne;
;             ldsp_t ex = shm + G_STAGE_B + tc.wid * 8192;
;             if (EK == 0 || EK == 2) {
;                 const int cond = tc.brow < NLAT ? (tc.brow >> 12) : 4;
;                 const float* ssp = p.ss + ((size_t)(l * 2 + (EK == 0 ? 0 : 1)) * NTOK + tc.brow + tc.wr * 128 + tc.fr) * 16 + tc.fq * 4;
;                 const float* shw = (EK == 0 ? p.shw_in + ((size_t)l * 5 + cond) * IN_DIM : p.shw_ff1 + ((size_t)l * 5 + cond) * FF) + tc.bcol + tc.wc * 64 + tc.fq * 4;
;                 f32x4 shv[4];
; #pragma unroll
;                 for (int n = 0; n < 4; ++n) shv[n] = *(const f32x4*)(shw + n * 16);
; #pragma unroll
;                 for (int m = 0; m < 8; ++m) {
;                     const f32x4 pp = *(const f32x4*)(ssp + m * 256);
;                     float sq = pp[0] + pp[1] + pp[2] + pp[3];
;                     sq += __shfl_xor(sq, 16);
;                     sq += __shfl_xor(sq, 32);
;                     const float rstd = rsqrtf(sq * (1.f / DM) + EPS);
; #pragma unroll
;                     for (int n = 0; n < 4; ++n) acc[m][n] = acc[m][n] * rstd + shv[n];
;                 }
	s_setprio 1
	v_mfma_f32_16x16x32_bf16 v[76:79], v[176:179], v[64:67], v[128:131]
	v_mfma_f32_16x16x32_bf16 v[72:75], v[180:183], v[64:67], v[124:127]
	v_mfma_f32_16x16x32_bf16 v[68:71], v[184:187], v[64:67], v[120:123]
	v_mfma_f32_16x16x32_bf16 v[64:67], v[188:191], v[64:67], v[116:119]
	v_mfma_f32_16x16x32_bf16 v[60:63], v[176:179], v[172:175], v[112:115]
	v_mfma_f32_16x16x32_bf16 v[56:59], v[180:183], v[172:175], v[194:197]
	v_mfma_f32_16x16x32_bf16 v[52:55], v[184:187], v[172:175], v[214:217]
	v_mfma_f32_16x16x32_bf16 v[48:51], v[188:191], v[172:175], v[132:135]
	v_mfma_f32_16x16x32_bf16 v[28:31], v[176:179], v[232:235], v[220:223]
	v_mfma_f32_16x16x32_bf16 v[24:27], v[180:183], v[232:235], v[224:227]
	v_mfma_f32_16x16x32_bf16 v[20:23], v[184:187], v[232:235], v[228:231]
	v_mfma_f32_16x16x32_bf16 v[16:19], v[188:191], v[232:235], v[136:139]
	v_mfma_f32_16x16x32_bf16 v[12:15], v[176:179], v[236:239], v[160:163]
	v_mfma_f32_16x16x32_bf16 v[8:11], v[180:183], v[236:239], v[164:167]
	v_mfma_f32_16x16x32_bf16 v[4:7], v[184:187], v[236:239], v[168:171]
	v_mfma_f32_16x16x32_bf16 v[0:3], v[188:191], v[236:239], v[140:143]
	s_setprio 0
	v_mov_b32_e32 v172, v252
	s_lshl_b32 s41, s31, 8
	s_min_i32 s4, s41, 0x4000
	s_lshl_b32 s6, s98, 8
	s_ashr_i32 s4, s4, 12
	s_ashr_i32 s5, s41, 31
	s_add_u32 s7, s45, s41
	v_ashrrev_i32_e32 v174, 1, v172
	v_and_b32_e32 v169, 15, v172
	s_addc_u32 s5, s48, s5
	v_and_b32_e32 v112, 0xffffff80, v174
	v_ashrrev_i32_e32 v113, 31, v112
	v_or_b32_e32 v32, s7, v169
	v_mov_b32_e32 v33, s5
	s_ashr_i32 s5, s4, 31
	v_lshl_add_u64 v[32:33], v[32:33], 0, v[112:113]
	s_add_u32 s4, s44, s4
	v_lshlrev_b64 v[114:115], 6, v[32:33]
	s_addc_u32 s5, s49, s5
	v_mov_b64_e32 v[32:33], s[76:77]
	v_mov_b32_e32 v34, 0x1c00
	s_mul_i32 s7, s5, 0x1c00
	v_mad_u64_u32 v[32:33], s[4:5], s4, v34, v[32:33]
	v_ashrrev_i32_e32 v166, 6, v172
	v_add_u32_e32 v33, s7, v33
	s_ashr_i32 s7, s6, 31
	v_and_b32_e32 v171, 3, v166
	s_lshl_b64 s[4:5], s[6:7], 2
	v_xor_b32_e32 v230, 16, v202
	v_lshl_add_u64 v[32:33], v[32:33], 0, s[4:5]
	v_lshlrev_b32_e32 v192, 8, v171
	v_cmp_lt_i32_e32 vcc, v230, v203
	v_lshl_add_u64 v[32:33], v[32:33], 0, v[192:193]
	v_and_b32_e32 v192, 48, v172
	v_lshl_add_u64 v[114:115], s[74:75], 0, v[114:115]
	v_cndmask_b32_e32 v113, v202, v230, vcc
	v_cmp_lt_i32_e32 vcc, v209, v203
	v_lshl_add_u64 v[32:33], v[32:33], 0, v[192:193]
	v_lshl_add_u64 v[164:165], v[114:115], 0, v[192:193]
	v_cndmask_b32_e32 v114, v202, v209, vcc
	global_load_dwordx4 v[44:47], v[32:33], off
	global_load_dwordx4 v[40:43], v[32:33], off offset:64
	global_load_dwordx4 v[36:39], v[32:33], off offset:128
	s_nop 0
	global_load_dwordx4 v[32:35], v[32:33], off offset:192
	v_lshlrev_b32_e32 v168, 2, v114
	global_load_dwordx4 v[114:117], v[164:165], off
	global_load_dwordx4 v[118:121], v[164:165], off offset:1024
	global_load_dwordx4 v[178:181], v[164:165], off offset:2048
	global_load_dwordx4 v[130:133], v[164:165], off offset:3072
	v_mov_b32_e32 v190, s29
	v_mov_b32_e32 v191, 0
	v_lshl_add_u64 v[190:191], v[164:165], 0, v[190:191]
	global_load_dwordx4 v[182:185], v[190:191], off
	global_load_dwordx4 v[186:189], v[190:191], off offset:1024
	global_load_dwordx4 v[232:235], v[190:191], off offset:2048
	global_load_dwordx4 v[236:239], v[190:191], off offset:3072
	v_lshlrev_b32_e32 v113, 2, v113
	s_mov_b32 s4, 0x358637bd
	v_mov_b64_e32 v[162:163], s[4:5]
	s_mov_b32 s8, 0x3a800000
	v_bfe_u32 v173, v172, 4, 2
	v_and_b32_e32 v170, 63, v172
	v_lshlrev_b32_e32 v175, 2, v173
	s_cmp_gt_i32 s98, 1
	s_waitcnt vmcnt(7)
	v_mov_b32_e32 v123, v114
	s_waitcnt vmcnt(6)
	v_mov_b32_e32 v122, v118
	v_mov_b32_e32 v114, v119
	v_pk_add_f32 v[114:115], v[122:123], v[114:115]
	v_mov_b32_e32 v118, v120
	v_mov_b32_e32 v119, v116
	v_pk_add_f32 v[114:115], v[118:119], v[114:115]
	v_mov_b32_e32 v116, v121
	v_pk_add_f32 v[114:115], v[116:117], v[114:115]
	ds_bpermute_b32 v117, v113, v115
	ds_bpermute_b32 v116, v113, v114
	s_waitcnt lgkmcnt(0)
	v_pk_add_f32 v[114:115], v[114:115], v[116:117]
	ds_bpermute_b32 v117, v168, v115
	ds_bpermute_b32 v116, v168, v114
	s_waitcnt lgkmcnt(0)
	v_pk_add_f32 v[114:115], v[114:115], v[116:117]
	s_nop 0
	v_pk_fma_f32 v[114:115], v[114:115], s[8:9], v[162:163] op_sel_hi:[1,0,0]
	s_nop 0
	v_mul_f32_e32 v116, 0x4b800000, v115
	v_cmp_gt_f32_e64 s[4:5], s92, v115
	v_cmp_gt_f32_e32 vcc, s92, v114
	s_nop 0
	v_cndmask_b32_e64 v115, v115, v116, s[4:5]
	v_rsq_f32_e32 v115, v115
	s_nop 0
	v_mul_f32_e32 v116, 0x45800000, v115
	v_cndmask_b32_e64 v116, v115, v116, s[4:5]
	v_mul_f32_e32 v115, 0x4b800000, v114
	v_cndmask_b32_e32 v114, v114, v115, vcc
	v_rsq_f32_e32 v114, v114
	v_pk_fma_f32 v[158:159], v[242:243], v[116:117], v[46:47] op_sel_hi:[1,0,1]
	v_pk_fma_f32 v[160:161], v[240:241], v[116:117], v[44:45] op_sel_hi:[1,0,1]
	v_pk_fma_f32 v[154:155], v[246:247], v[116:117], v[42:43] op_sel_hi:[1,0,1]
	v_mul_f32_e32 v115, 0x45800000, v114
	v_cndmask_b32_e32 v114, v114, v115, vcc
	v_pk_fma_f32 v[156:157], v[244:245], v[116:117], v[40:41] op_sel_hi:[1,0,1]
	v_pk_fma_f32 v[216:217], v[250:251], v[116:117], v[38:39] op_sel_hi:[1,0,1]
	v_pk_fma_f32 v[152:153], v[248:249], v[116:117], v[36:37] op_sel_hi:[1,0,1]
	v_pk_fma_f32 v[146:147], v[146:147], v[116:117], v[34:35] op_sel_hi:[1,0,1]
	v_pk_fma_f32 v[214:215], v[144:145], v[116:117], v[32:33] op_sel_hi:[1,0,1]
	v_pk_fma_f32 v[140:141], v[212:213], v[114:115], v[46:47] op_sel_hi:[1,0,1]
	v_pk_fma_f32 v[144:145], v[210:211], v[114:115], v[44:45] op_sel_hi:[1,0,1]
	v_pk_fma_f32 v[138:139], v[206:207], v[114:115], v[42:43] op_sel_hi:[1,0,1]
	v_pk_fma_f32 v[142:143], v[204:205], v[114:115], v[40:41] op_sel_hi:[1,0,1]
	v_pk_fma_f32 v[126:127], v[200:201], v[114:115], v[38:39] op_sel_hi:[1,0,1]
	v_pk_fma_f32 v[128:129], v[198:199], v[114:115], v[36:37] op_sel_hi:[1,0,1]
	v_pk_fma_f32 v[120:121], v[150:151], v[114:115], v[34:35] op_sel_hi:[1,0,1]
	v_pk_fma_f32 v[124:125], v[148:149], v[114:115], v[32:33] op_sel_hi:[1,0,1]
	s_waitcnt vmcnt(4)
; template <int EK>
; DI void gemm_stream(const Params& p, int l, const bf16_t* __restrict__ A, const bf16_t* __restrict__ Bt, int M, int N, int K, ldsp_t shm) {
;     ...
; #pragma unroll
;                 for (int m = 0; m < 8; ++m) {
;                     const f32x4 pp = *(const f32x4*)(ssp + m * 256);
;                     float sq = pp[0] + pp[1] + pp[2] + pp[3];
;                     sq += __shfl_xor(sq, 16);
;                     sq += __shfl_xor(sq, 32);
;                     const float rstd = rsqrtf(sq * (1.f / DM) + EPS);
; #pragma unroll
;                     for (int n = 0; n < 4; ++n) acc[m][n] = acc[m][n] * rstd + shv[n];
;                 }
	v_mov_b64_e32 v[114:115], v[178:179]
	v_mov_b64_e32 v[116:117], v[180:181]
	v_mov_b32_e32 v119, v114
	v_mov_b32_e32 v118, v130
	v_mov_b32_e32 v114, v131
	v_pk_add_f32 v[114:115], v[118:119], v[114:115]
	v_mov_b32_e32 v118, v132
	v_mov_b32_e32 v119, v116
	v_pk_add_f32 v[114:115], v[118:119], v[114:115]
	v_mov_b32_e32 v116, v133
	v_pk_add_f32 v[114:115], v[116:117], v[114:115]
	ds_bpermute_b32 v117, v113, v115
	ds_bpermute_b32 v116, v113, v114
	s_waitcnt lgkmcnt(0)
	v_pk_add_f32 v[114:115], v[114:115], v[116:117]
	ds_bpermute_b32 v117, v168, v115
	ds_bpermute_b32 v116, v168, v114
	s_waitcnt lgkmcnt(0)
	v_pk_add_f32 v[114:115], v[114:115], v[116:117]
	s_nop 0
	v_pk_fma_f32 v[148:149], v[114:115], s[8:9], v[162:163] op_sel_hi:[1,0,0]
	s_nop 0
	v_mul_f32_e32 v114, 0x4b800000, v149
	v_cmp_gt_f32_e64 s[4:5], s92, v149
	v_cmp_gt_f32_e32 vcc, s92, v148
	s_nop 0
	v_cndmask_b32_e64 v114, v149, v114, s[4:5]
	v_rsq_f32_e32 v114, v114
	s_nop 0
	v_mul_f32_e32 v115, 0x45800000, v114
	v_cndmask_b32_e64 v116, v114, v115, s[4:5]
	v_pk_fma_f32 v[132:133], v[110:111], v[116:117], v[46:47] op_sel_hi:[1,0,1]
	v_pk_fma_f32 v[136:137], v[108:109], v[116:117], v[44:45] op_sel_hi:[1,0,1]
	v_pk_fma_f32 v[130:131], v[106:107], v[116:117], v[42:43] op_sel_hi:[1,0,1]
	v_pk_fma_f32 v[134:135], v[104:105], v[116:117], v[40:41] op_sel_hi:[1,0,1]
	v_pk_fma_f32 v[118:119], v[102:103], v[116:117], v[38:39] op_sel_hi:[1,0,1]
	v_pk_fma_f32 v[122:123], v[100:101], v[116:117], v[36:37] op_sel_hi:[1,0,1]
	v_pk_fma_f32 v[114:115], v[98:99], v[116:117], v[34:35] op_sel_hi:[1,0,1]
	v_pk_fma_f32 v[116:117], v[96:97], v[116:117], v[32:33] op_sel_hi:[1,0,1]
	v_mul_f32_e32 v96, 0x4b800000, v148
	v_cndmask_b32_e32 v96, v148, v96, vcc
	v_rsq_f32_e32 v96, v96
	s_nop 0
	v_mul_f32_e32 v97, 0x45800000, v96
	v_cndmask_b32_e32 v104, v96, v97, vcc
	v_pk_fma_f32 v[98:99], v[94:95], v[104:105], v[46:47] op_sel_hi:[1,0,1]
	v_pk_fma_f32 v[102:103], v[92:93], v[104:105], v[44:45] op_sel_hi:[1,0,1]
	v_pk_fma_f32 v[96:97], v[90:91], v[104:105], v[42:43] op_sel_hi:[1,0,1]
	v_pk_fma_f32 v[100:101], v[88:89], v[104:105], v[40:41] op_sel_hi:[1,0,1]
	v_pk_fma_f32 v[92:93], v[86:87], v[104:105], v[38:39] op_sel_hi:[1,0,1]
	v_pk_fma_f32 v[94:95], v[84:85], v[104:105], v[36:37] op_sel_hi:[1,0,1]
	v_pk_fma_f32 v[88:89], v[82:83], v[104:105], v[34:35] op_sel_hi:[1,0,1]
	v_pk_fma_f32 v[90:91], v[80:81], v[104:105], v[32:33] op_sel_hi:[1,0,1]
	v_add_co_u32_e32 v104, vcc, s29, v164
	s_nop 1
	v_addc_co_u32_e32 v105, vcc, 0, v165, vcc
	s_waitcnt vmcnt(2)
	v_mov_b64_e32 v[80:81], v[182:183]
	v_mov_b64_e32 v[82:83], v[184:185]
	v_mov_b64_e32 v[84:85], v[186:187]
	v_mov_b64_e32 v[86:87], v[188:189]
	v_mov_b32_e32 v107, v80
	v_mov_b32_e32 v106, v84
	v_mov_b32_e32 v80, v85
	v_pk_add_f32 v[80:81], v[106:107], v[80:81]
	v_mov_b32_e32 v84, v86
	v_mov_b32_e32 v85, v82
	v_pk_add_f32 v[80:81], v[84:85], v[80:81]
	v_mov_b32_e32 v82, v87
	v_pk_add_f32 v[80:81], v[82:83], v[80:81]
	ds_bpermute_b32 v83, v113, v81
	ds_bpermute_b32 v82, v113, v80
	s_waitcnt lgkmcnt(0)
	v_pk_add_f32 v[80:81], v[80:81], v[82:83]
	ds_bpermute_b32 v83, v168, v81
	ds_bpermute_b32 v82, v168, v80
	s_waitcnt lgkmcnt(0)
	v_pk_add_f32 v[80:81], v[80:81], v[82:83]
	s_nop 0
	v_pk_fma_f32 v[106:107], v[80:81], s[8:9], v[162:163] op_sel_hi:[1,0,0]
	s_nop 0
	v_mul_f32_e32 v80, 0x4b800000, v107
	v_cmp_gt_f32_e64 s[4:5], s92, v107
	v_cmp_gt_f32_e32 vcc, s92, v106
	s_nop 0
	v_cndmask_b32_e64 v80, v107, v80, s[4:5]
	v_rsq_f32_e32 v80, v80
	s_nop 0
	v_mul_f32_e32 v81, 0x45800000, v80
	v_cndmask_b32_e64 v108, v80, v81, s[4:5]
	v_pk_fma_f32 v[80:81], v[74:75], v[108:109], v[42:43] op_sel_hi:[1,0,1]
	v_pk_fma_f32 v[74:75], v[64:65], v[108:109], v[32:33] op_sel_hi:[1,0,1]
	v_mul_f32_e32 v64, 0x4b800000, v106
	v_cndmask_b32_e32 v64, v106, v64, vcc
	v_rsq_f32_e32 v64, v64
	v_pk_fma_f32 v[82:83], v[78:79], v[108:109], v[46:47] op_sel_hi:[1,0,1]
	v_pk_fma_f32 v[86:87], v[76:77], v[108:109], v[44:45] op_sel_hi:[1,0,1]
	v_pk_fma_f32 v[84:85], v[72:73], v[108:109], v[40:41] op_sel_hi:[1,0,1]
	v_mul_f32_e32 v65, 0x45800000, v64
	v_cndmask_b32_e32 v106, v64, v65, vcc
	v_pk_fma_f32 v[76:77], v[70:71], v[108:109], v[38:39] op_sel_hi:[1,0,1]
	v_pk_fma_f32 v[78:79], v[68:69], v[108:109], v[36:37] op_sel_hi:[1,0,1]
	v_pk_fma_f32 v[72:73], v[66:67], v[108:109], v[34:35] op_sel_hi:[1,0,1]
	v_pk_fma_f32 v[68:69], v[62:63], v[106:107], v[46:47] op_sel_hi:[1,0,1]
	v_pk_fma_f32 v[70:71], v[60:61], v[106:107], v[44:45] op_sel_hi:[1,0,1]
	v_pk_fma_f32 v[64:65], v[58:59], v[106:107], v[42:43] op_sel_hi:[1,0,1]
	v_pk_fma_f32 v[66:67], v[56:57], v[106:107], v[40:41] op_sel_hi:[1,0,1]
	v_pk_fma_f32 v[60:61], v[54:55], v[106:107], v[38:39] op_sel_hi:[1,0,1]
	v_pk_fma_f32 v[62:63], v[52:53], v[106:107], v[36:37] op_sel_hi:[1,0,1]
	v_pk_fma_f32 v[56:57], v[50:51], v[106:107], v[34:35] op_sel_hi:[1,0,1]
	v_pk_fma_f32 v[58:59], v[48:49], v[106:107], v[32:33] op_sel_hi:[1,0,1]
	s_waitcnt vmcnt(0)
	v_mov_b64_e32 v[48:49], v[232:233]
	v_mov_b64_e32 v[50:51], v[234:235]
	v_mov_b64_e32 v[52:53], v[236:237]
	v_mov_b64_e32 v[54:55], v[238:239]
	v_mov_b32_e32 v105, v48
	v_mov_b32_e32 v104, v52
	v_mov_b32_e32 v48, v53
	v_pk_add_f32 v[48:49], v[104:105], v[48:49]
	v_mov_b32_e32 v52, v54
	v_mov_b32_e32 v53, v50
	v_pk_add_f32 v[48:49], v[52:53], v[48:49]
	v_mov_b32_e32 v50, v55
	v_pk_add_f32 v[48:49], v[50:51], v[48:49]
	ds_bpermute_b32 v51, v113, v49
	ds_bpermute_b32 v50, v113, v48
	s_waitcnt lgkmcnt(0)
	v_pk_add_f32 v[48:49], v[48:49], v[50:51]
	ds_bpermute_b32 v51, v168, v49
	ds_bpermute_b32 v50, v168, v48
	s_waitcnt lgkmcnt(0)
; DI unsigned pk2(float a, float b) { f32x2 v = {a, b}; bf2_t r = __builtin_convertvector(v, bf2_t); return __builtin_bit_cast(unsigned, r); }
;     static DI void run(const f32x4 (&acc)[8][4], const TileCtx& tc, const Params& p, ldsp_t wb) {
;     ...
;         } else if (BRK == 2) {
; #pragma unroll
;             for (int h = 0; h < 2; ++h) {
; #pragma unroll
;                 for (int mm = 0; mm < 4; ++mm) {
;                     const int m = h * 4 + mm;
; #pragma unroll
;                     for (int n = 0; n < 4; ++n) {
;                         u32x2 w; w[0] = pk2(gelu_tanh(acc[m][n][0]), gelu_tanh(acc[m][n][1])); w[1] = pk2(gelu_tanh(acc[m][n][2]), gelu_tanh(acc[m][n][3]));
;                         wave_put(wb, mm * 16 + fr, n, fq, w);
;                     }
; template <int EK>
; DI void gemm_stream(const Params& p, int l, const bf16_t* __restrict__ A, const bf16_t* __restrict__ Bt, int M, int N, int K, ldsp_t shm) {
;     ...
; #pragma unroll
;                 for (int m = 0; m < 8; ++m) {
;                     const f32x4 pp = *(const f32x4*)(ssp + m * 256);
;                     float sq = pp[0] + pp[1] + pp[2] + pp[3];
;                     sq += __shfl_xor(sq, 16);
;                     sq += __shfl_xor(sq, 32);
;                     const float rstd = rsqrtf(sq * (1.f / DM) + EPS);
; #pragma unroll
;                     for (int n = 0; n < 4; ++n) acc[m][n] = acc[m][n] * rstd + shv[n];
;                 }
	v_pk_add_f32 v[48:49], v[48:49], v[50:51]
	s_nop 0
	v_pk_fma_f32 v[148:149], v[48:49], s[8:9], v[162:163] op_sel_hi:[1,0,0]
	s_nop 0
	v_mul_f32_e32 v48, 0x4b800000, v149
	v_cmp_gt_f32_e64 s[4:5], s92, v149
	v_cmp_gt_f32_e32 vcc, s92, v148
	s_nop 0
	v_cndmask_b32_e64 v48, v149, v48, s[4:5]
	v_rsq_f32_e32 v48, v48
	s_nop 0
	v_mul_f32_e32 v49, 0x45800000, v48
	v_cndmask_b32_e64 v50, v48, v49, s[4:5]
	v_pk_fma_f32 v[108:109], v[30:31], v[50:51], v[46:47] op_sel_hi:[1,0,1]
	v_pk_fma_f32 v[110:111], v[28:29], v[50:51], v[44:45] op_sel_hi:[1,0,1]
	v_pk_fma_f32 v[104:105], v[26:27], v[50:51], v[42:43] op_sel_hi:[1,0,1]
	v_pk_fma_f32 v[106:107], v[24:25], v[50:51], v[40:41] op_sel_hi:[1,0,1]
	v_pk_fma_f32 v[52:53], v[22:23], v[50:51], v[38:39] op_sel_hi:[1,0,1]
	v_pk_fma_f32 v[54:55], v[20:21], v[50:51], v[36:37] op_sel_hi:[1,0,1]
	v_pk_fma_f32 v[48:49], v[18:19], v[50:51], v[34:35] op_sel_hi:[1,0,1]
	v_pk_fma_f32 v[50:51], v[16:17], v[50:51], v[32:33] op_sel_hi:[1,0,1]
	v_mul_f32_e32 v16, 0x4b800000, v148
	v_cndmask_b32_e32 v16, v148, v16, vcc
	v_rsq_f32_e32 v16, v16
	s_mov_b64 s[4:5], -1
	v_mul_f32_e32 v17, 0x45800000, v16
	v_cndmask_b32_e32 v16, v16, v17, vcc
	v_pk_fma_f32 v[22:23], v[0:1], v[16:17], v[32:33] op_sel_hi:[1,0,1]
	v_mov_b32_e32 v0, 0x10000
	v_pk_fma_f32 v[46:47], v[14:15], v[16:17], v[46:47] op_sel_hi:[1,0,1]
	v_pk_fma_f32 v[44:45], v[12:13], v[16:17], v[44:45] op_sel_hi:[1,0,1]
	v_pk_fma_f32 v[28:29], v[10:11], v[16:17], v[42:43] op_sel_hi:[1,0,1]
	v_pk_fma_f32 v[30:31], v[8:9], v[16:17], v[40:41] op_sel_hi:[1,0,1]
	v_pk_fma_f32 v[24:25], v[6:7], v[16:17], v[38:39] op_sel_hi:[1,0,1]
	v_pk_fma_f32 v[26:27], v[4:5], v[16:17], v[36:37] op_sel_hi:[1,0,1]
	v_pk_fma_f32 v[20:21], v[2:3], v[16:17], v[34:35] op_sel_hi:[1,0,1]
	v_lshl_add_u32 v176, v166, 13, v0
	s_cbranch_scc0 .LBB0_327
	s_cmp_lg_u32 s98, 2
	s_cbranch_scc0 .LBB0_272
	v_mov_b32_e32 v191, 0xc0135761
	v_lshlrev_b32_e32 v3, 3, v173
	v_lshlrev_b32_e32 v2, 7, v169
	v_and_b32_e32 v3, 8, v3
	v_add3_u32 v7, v176, v2, v3
	v_mul_f32_e32 v2, v160, v160
	v_mul_f32_e32 v3, v161, v161
	v_fmamk_f32 v2, v2, 0xbdd2d3e7, v191
	v_fmamk_f32 v3, v3, 0xbdd2d3e7, v191
	v_mul_f32_e32 v2, v160, v2
	v_mul_f32_e32 v3, v161, v3
	s_nop 0
	s_nop 0
	s_nop 0
	s_nop 0
	v_exp_f32_e32 v2, v2
	v_exp_f32_e32 v3, v3
	v_lshrrev_b32_e32 v1, 5, v170
	v_and_b32_e32 v6, 7, v172
	v_add_f32_e32 v2, 1.0, v2
	v_add_f32_e32 v3, 1.0, v3
	v_rcp_f32_e32 v2, v2
	v_rcp_f32_e32 v3, v3
	v_add_u32_e32 v10, s41, v112
	s_add_i32 s4, s6, 0xfffffd00
	v_ashrrev_i32_e32 v11, 31, v10
	v_pk_mul_f32 v[2:3], v[160:161], v[2:3]
	s_ashr_i32 s5, s4, 31
	v_cvt_pk_bf16_f32 v2, v2, v3
	v_mul_f32_e32 v3, v158, v158
	v_fmamk_f32 v3, v3, 0xbdd2d3e7, v191
	v_mul_f32_e32 v3, v158, v3
	s_nop 0
	s_nop 0
	v_exp_f32_e32 v3, v3
	v_lshlrev_b32_e32 v0, 6, v171
	s_lshl_b64 s[4:5], s[4:5], 1
	v_lshlrev_b32_e32 v192, 1, v0
	v_add_f32_e32 v3, 1.0, v3
	v_rcp_f32_e32 v4, v3
	v_mul_f32_e32 v3, v159, v159
	v_fmamk_f32 v3, v3, 0xbdd2d3e7, v191
	v_mul_f32_e32 v3, v159, v3
	s_nop 0
	s_nop 0
	v_exp_f32_e32 v3, v3
	v_mov_b32_e32 v19, v193
	v_mov_b32_e32 v17, v193
	v_mov_b32_e32 v15, v193
	v_add_f32_e32 v3, 1.0, v3
	v_rcp_f32_e32 v5, v3
	v_mov_b32_e32 v13, v193
	v_mov_b32_e32 v9, v193
	v_pk_mul_f32 v[4:5], v[158:159], v[4:5]
	s_nop 0
	v_cvt_pk_bf16_f32 v3, v4, v5
	v_bitop3_b32 v4, v1, v172, 7 bitop3:0x78
	v_lshl_add_u32 v32, v4, 4, v7
	ds_write_b64 v32, v[2:3]
	v_mul_f32_e32 v2, v156, v156
	v_mul_f32_e32 v3, v157, v157
	v_fmamk_f32 v2, v2, 0xbdd2d3e7, v191
	v_fmamk_f32 v3, v3, 0xbdd2d3e7, v191
	v_mul_f32_e32 v2, v156, v2
	v_mul_f32_e32 v3, v157, v3
	s_nop 0
	s_nop 0
	s_nop 0
	s_nop 0
	v_exp_f32_e32 v2, v2
	v_exp_f32_e32 v3, v3
	v_add_f32_e32 v2, 1.0, v2
	v_add_f32_e32 v3, 1.0, v3
	v_rcp_f32_e32 v2, v2
	v_rcp_f32_e32 v3, v3
	s_nop 0
	v_pk_mul_f32 v[2:3], v[156:157], v[2:3]
	s_nop 0
	v_cvt_pk_bf16_f32 v2, v2, v3
	v_mul_f32_e32 v3, v154, v154
	v_fmamk_f32 v3, v3, 0xbdd2d3e7, v191
	v_mul_f32_e32 v3, v154, v3
	s_nop 0
	s_nop 0
	v_exp_f32_e32 v3, v3
	s_nop 0
	v_add_f32_e32 v3, 1.0, v3
	v_rcp_f32_e32 v4, v3
	v_mul_f32_e32 v3, v155, v155
	v_fmamk_f32 v3, v3, 0xbdd2d3e7, v191
	v_mul_f32_e32 v3, v155, v3
	s_nop 0
	s_nop 0
	v_exp_f32_e32 v3, v3
	s_nop 0
	v_add_f32_e32 v3, 1.0, v3
	v_rcp_f32_e32 v5, v3
	s_nop 0
	v_pk_mul_f32 v[4:5], v[154:155], v[4:5]
	s_nop 0
	v_cvt_pk_bf16_f32 v3, v4, v5
	v_bitop3_b32 v4, v1, v6, 2 bitop3:0x36
	v_lshl_add_u32 v33, v4, 4, v7
	ds_write_b64 v33, v[2:3]
	v_mul_f32_e32 v2, v152, v152
	v_mul_f32_e32 v3, v153, v153
	v_fmamk_f32 v2, v2, 0xbdd2d3e7, v191
	v_fmamk_f32 v3, v3, 0xbdd2d3e7, v191
	v_mul_f32_e32 v2, v152, v2
	v_mul_f32_e32 v3, v153, v3
	s_nop 0
	s_nop 0
	s_nop 0
	s_nop 0
	v_exp_f32_e32 v2, v2
	v_exp_f32_e32 v3, v3
	v_add_f32_e32 v2, 1.0, v2
	v_add_f32_e32 v3, 1.0, v3
	v_rcp_f32_e32 v2, v2
	v_rcp_f32_e32 v3, v3
	s_nop 0
	v_pk_mul_f32 v[2:3], v[152:153], v[2:3]
	s_nop 0
	v_cvt_pk_bf16_f32 v2, v2, v3
	v_mul_f32_e32 v3, v216, v216
	v_fmamk_f32 v3, v3, 0xbdd2d3e7, v191
	v_mul_f32_e32 v3, v216, v3
	s_nop 0
	s_nop 0
	v_exp_f32_e32 v3, v3
	s_nop 0
	v_add_f32_e32 v3, 1.0, v3
	v_rcp_f32_e32 v4, v3
	v_mul_f32_e32 v3, v217, v217
	v_fmamk_f32 v3, v3, 0xbdd2d3e7, v191
	v_mul_f32_e32 v3, v217, v3
	s_nop 0
	s_nop 0
	v_exp_f32_e32 v3, v3
	s_nop 0
	v_add_f32_e32 v3, 1.0, v3
	v_rcp_f32_e32 v5, v3
	s_nop 0
	v_pk_mul_f32 v[4:5], v[216:217], v[4:5]
	s_nop 0
	v_cvt_pk_bf16_f32 v3, v4, v5
	v_bitop3_b32 v4, v1, v6, 4 bitop3:0x36
	v_lshl_add_u32 v34, v4, 4, v7
	ds_write_b64 v34, v[2:3]
	v_mul_f32_e32 v2, v214, v214
	v_mul_f32_e32 v3, v215, v215
	v_fmamk_f32 v2, v2, 0xbdd2d3e7, v191
	v_fmamk_f32 v3, v3, 0xbdd2d3e7, v191
	v_mul_f32_e32 v2, v214, v2
	v_mul_f32_e32 v3, v215, v3
; DI unsigned pk2(float a, float b) { f32x2 v = {a, b}; bf2_t r = __builtin_convertvector(v, bf2_t); return __builtin_bit_cast(unsigned, r); }
; DI float fexp2(float x) { return __builtin_amdgcn_exp2f(x); }
; DI float gelu_tanh(float x) {
;     const float y = 0.7978845608028654f * (x + 0.044715f * x * x * x);
;     return x * __builtin_amdgcn_rcpf(1.f + fexp2(-2.f * LOG2E * y));
; }
;     static DI void run(const f32x4 (&acc)[8][4], const TileCtx& tc, const Params& p, ldsp_t wb) {
;     ...
; #pragma unroll
;             for (int h = 0; h < 2; ++h) {
; #pragma unroll
;                 for (int mm = 0; mm < 4; ++mm) {
;                     const int m = h * 4 + mm;
; #pragma unroll
;                     for (int n = 0; n < 4; ++n) {
;                         u32x2 w; w[0] = pk2(gelu_tanh(acc[m][n][0]), gelu_tanh(acc[m][n][1])); w[1] = pk2(gelu_tanh(acc[m][n][2]), gelu_tanh(acc[m][n][3]));
;                         wave_put(wb, mm * 16 + fr, n, fq, w);
;                     }
;                 }
;                 wave_rows_store(wb, tc.lane, p.U + (size_t)(tc.brow + tc.wr * 128 + h * 64) * 1024 + (pn - 3) * 256 + wc * 64, 1024);
	s_nop 0
	s_nop 0
	s_nop 0
	s_nop 0
	v_exp_f32_e32 v2, v2
	v_exp_f32_e32 v3, v3
	v_bitop3_b32 v1, v1, v6, 6 bitop3:0x36
	v_lshl_add_u32 v35, v1, 4, v7
	v_add_f32_e32 v2, 1.0, v2
	v_add_f32_e32 v3, 1.0, v3
	v_rcp_f32_e32 v2, v2
	v_rcp_f32_e32 v3, v3
	v_mul_f32_e32 v1, v144, v144
	v_fmamk_f32 v1, v1, 0xbdd2d3e7, v191
	v_mul_f32_e32 v1, v144, v1
	v_pk_mul_f32 v[2:3], v[214:215], v[2:3]
	s_nop 0
	v_cvt_pk_bf16_f32 v2, v2, v3
	v_mul_f32_e32 v3, v146, v146
	v_fmamk_f32 v3, v3, 0xbdd2d3e7, v191
	v_mul_f32_e32 v3, v146, v3
	s_nop 0
	s_nop 0
	v_exp_f32_e32 v3, v3
	s_nop 0
	v_exp_f32_e32 v1, v1
	v_add_f32_e32 v3, 1.0, v3
	v_rcp_f32_e32 v4, v3
	v_mul_f32_e32 v3, v147, v147
	v_fmamk_f32 v3, v3, 0xbdd2d3e7, v191
	v_mul_f32_e32 v3, v147, v3
	s_nop 0
	s_nop 0
	v_exp_f32_e32 v3, v3
	v_add_f32_e32 v1, 1.0, v1
	v_add_f32_e32 v3, 1.0, v3
	v_rcp_f32_e32 v5, v3
	s_nop 0
	v_pk_mul_f32 v[4:5], v[146:147], v[4:5]
	s_nop 0
	v_cvt_pk_bf16_f32 v3, v4, v5
	ds_write_b64 v35, v[2:3]
	v_rcp_f32_e32 v2, v1
	v_mul_f32_e32 v1, v145, v145
	v_fmamk_f32 v1, v1, 0xbdd2d3e7, v191
	v_mul_f32_e32 v1, v145, v1
	s_nop 0
	s_nop 0
	v_exp_f32_e32 v1, v1
	s_nop 0
	v_add_f32_e32 v1, 1.0, v1
	v_rcp_f32_e32 v3, v1
	v_mul_f32_e32 v1, v140, v140
	v_fmamk_f32 v1, v1, 0xbdd2d3e7, v191
	v_mul_f32_e32 v1, v140, v1
	s_nop 0
	s_nop 0
	v_exp_f32_e32 v1, v1
	v_pk_mul_f32 v[2:3], v[144:145], v[2:3]
	v_add_f32_e32 v1, 1.0, v1
	v_rcp_f32_e32 v4, v1
	v_mul_f32_e32 v1, v141, v141
	v_fmamk_f32 v1, v1, 0xbdd2d3e7, v191
	v_mul_f32_e32 v1, v141, v1
	s_nop 0
	s_nop 0
	v_exp_f32_e32 v1, v1
	v_cvt_pk_bf16_f32 v2, v2, v3
	v_add_f32_e32 v1, 1.0, v1
	v_rcp_f32_e32 v5, v1
	v_mul_f32_e32 v1, v142, v142
	v_fmamk_f32 v1, v1, 0xbdd2d3e7, v191
	v_mul_f32_e32 v1, v142, v1
	s_nop 0
	s_nop 0
	v_exp_f32_e32 v1, v1
	v_pk_mul_f32 v[4:5], v[140:141], v[4:5]
	v_add_f32_e32 v1, 1.0, v1
	v_cvt_pk_bf16_f32 v3, v4, v5
	ds_write_b64 v32, v[2:3] offset:2048
	v_rcp_f32_e32 v2, v1
	v_mul_f32_e32 v1, v143, v143
	v_fmamk_f32 v1, v1, 0xbdd2d3e7, v191
	v_mul_f32_e32 v1, v143, v1
	s_nop 0
	s_nop 0
	v_exp_f32_e32 v1, v1
	s_nop 0
	v_add_f32_e32 v1, 1.0, v1
	v_rcp_f32_e32 v3, v1
	v_mul_f32_e32 v1, v138, v138
	v_fmamk_f32 v1, v1, 0xbdd2d3e7, v191
	v_mul_f32_e32 v1, v138, v1
	s_nop 0
	s_nop 0
	v_exp_f32_e32 v1, v1
	v_pk_mul_f32 v[2:3], v[142:143], v[2:3]
	v_add_f32_e32 v1, 1.0, v1
	v_rcp_f32_e32 v4, v1
	v_mul_f32_e32 v1, v139, v139
	v_fmamk_f32 v1, v1, 0xbdd2d3e7, v191
	v_mul_f32_e32 v1, v139, v1
	s_nop 0
	s_nop 0
	v_exp_f32_e32 v1, v1
	v_cvt_pk_bf16_f32 v2, v2, v3
	v_add_f32_e32 v1, 1.0, v1
	v_rcp_f32_e32 v5, v1
	v_mul_f32_e32 v1, v128, v128
	v_fmamk_f32 v1, v1, 0xbdd2d3e7, v191
	v_mul_f32_e32 v1, v128, v1
	s_nop 0
	s_nop 0
	v_exp_f32_e32 v1, v1
	v_pk_mul_f32 v[4:5], v[138:139], v[4:5]
	v_add_f32_e32 v1, 1.0, v1
	v_cvt_pk_bf16_f32 v3, v4, v5
	ds_write_b64 v33, v[2:3] offset:2048
	v_rcp_f32_e32 v2, v1
	v_mul_f32_e32 v1, v129, v129
	v_fmamk_f32 v1, v1, 0xbdd2d3e7, v191
	v_mul_f32_e32 v1, v129, v1
	s_nop 0
	s_nop 0
	v_exp_f32_e32 v1, v1
	s_nop 0
	v_add_f32_e32 v1, 1.0, v1
	v_rcp_f32_e32 v3, v1
	v_mul_f32_e32 v1, v126, v126
	v_fmamk_f32 v1, v1, 0xbdd2d3e7, v191
	v_mul_f32_e32 v1, v126, v1
	s_nop 0
	s_nop 0
	v_exp_f32_e32 v1, v1
	v_pk_mul_f32 v[2:3], v[128:129], v[2:3]
	v_add_f32_e32 v1, 1.0, v1
	v_rcp_f32_e32 v4, v1
	v_mul_f32_e32 v1, v127, v127
	v_fmamk_f32 v1, v1, 0xbdd2d3e7, v191
	v_mul_f32_e32 v1, v127, v1
	s_nop 0
	s_nop 0
	v_exp_f32_e32 v1, v1
	v_cvt_pk_bf16_f32 v2, v2, v3
	v_add_f32_e32 v1, 1.0, v1
	v_rcp_f32_e32 v5, v1
	v_mul_f32_e32 v1, v124, v124
	v_fmamk_f32 v1, v1, 0xbdd2d3e7, v191
	v_mul_f32_e32 v1, v124, v1
	s_nop 0
	s_nop 0
	v_exp_f32_e32 v1, v1
	v_pk_mul_f32 v[4:5], v[126:127], v[4:5]
	v_add_f32_e32 v1, 1.0, v1
	v_cvt_pk_bf16_f32 v3, v4, v5
	ds_write_b64 v34, v[2:3] offset:2048
	v_rcp_f32_e32 v2, v1
	v_mul_f32_e32 v1, v125, v125
	v_fmamk_f32 v1, v1, 0xbdd2d3e7, v191
	v_mul_f32_e32 v1, v125, v1
	s_nop 0
	s_nop 0
	v_exp_f32_e32 v1, v1
	s_nop 0
	v_add_f32_e32 v1, 1.0, v1
	v_rcp_f32_e32 v3, v1
	v_mul_f32_e32 v1, v120, v120
	v_fmamk_f32 v1, v1, 0xbdd2d3e7, v191
	v_mul_f32_e32 v1, v120, v1
	s_nop 0
	s_nop 0
	v_exp_f32_e32 v1, v1
	v_pk_mul_f32 v[2:3], v[124:125], v[2:3]
	v_add_f32_e32 v1, 1.0, v1
	v_rcp_f32_e32 v4, v1
	v_mul_f32_e32 v1, v121, v121
	v_fmamk_f32 v1, v1, 0xbdd2d3e7, v191
	v_mul_f32_e32 v1, v121, v1
	s_nop 0
	s_nop 0
	v_exp_f32_e32 v1, v1
	v_cvt_pk_bf16_f32 v2, v2, v3
	v_add_f32_e32 v1, 1.0, v1
	v_rcp_f32_e32 v5, v1
	v_mul_f32_e32 v1, v136, v136
	v_fmamk_f32 v1, v1, 0xbdd2d3e7, v191
	v_mul_f32_e32 v1, v136, v1
	s_nop 0
	s_nop 0
	v_exp_f32_e32 v1, v1
	v_pk_mul_f32 v[4:5], v[120:121], v[4:5]
	v_add_f32_e32 v1, 1.0, v1
	v_cvt_pk_bf16_f32 v3, v4, v5
	ds_write_b64 v35, v[2:3] offset:2048
	v_rcp_f32_e32 v2, v1
	v_mul_f32_e32 v1, v137, v137
	v_fmamk_f32 v1, v1, 0xbdd2d3e7, v191
	v_mul_f32_e32 v1, v137, v1
	s_nop 0
	s_nop 0
	v_exp_f32_e32 v1, v1
	s_nop 0
	v_add_f32_e32 v1, 1.0, v1
	v_rcp_f32_e32 v3, v1
	v_mul_f32_e32 v1, v132, v132
	v_fmamk_f32 v1, v1, 0xbdd2d3e7, v191
	v_mul_f32_e32 v1, v132, v1
	s_nop 0
	s_nop 0
	v_exp_f32_e32 v1, v1
	v_pk_mul_f32 v[2:3], v[136:137], v[2:3]
	v_add_f32_e32 v1, 1.0, v1
	v_rcp_f32_e32 v4, v1
	v_mul_f32_e32 v1, v133, v133
	v_fmamk_f32 v1, v1, 0xbdd2d3e7, v191
	v_mul_f32_e32 v1, v133, v1
	s_nop 0
	s_nop 0
	v_exp_f32_e32 v1, v1
	v_cvt_pk_bf16_f32 v2, v2, v3
	v_add_f32_e32 v1, 1.0, v1
	v_rcp_f32_e32 v5, v1
	v_mul_f32_e32 v1, v134, v134
	v_fmamk_f32 v1, v1, 0xbdd2d3e7, v191
	v_mul_f32_e32 v1, v134, v1
	s_nop 0
	s_nop 0
	v_exp_f32_e32 v1, v1
	v_pk_mul_f32 v[4:5], v[132:133], v[4:5]
	v_add_f32_e32 v1, 1.0, v1
	v_cvt_pk_bf16_f32 v3, v4, v5
	ds_write_b64 v32, v[2:3] offset:4096
	v_rcp_f32_e32 v2, v1
; DI unsigned pk2(float a, float b) { f32x2 v = {a, b}; bf2_t r = __builtin_convertvector(v, bf2_t); return __builtin_bit_cast(unsigned, r); }
; DI float fexp2(float x) { return __builtin_amdgcn_exp2f(x); }
; DI float gelu_tanh(float x) {
;     const float y = 0.7978845608028654f * (x + 0.044715f * x * x * x);
;     return x * __builtin_amdgcn_rcpf(1.f + fexp2(-2.f * LOG2E * y));
; }
;     static DI void run(const f32x4 (&acc)[8][4], const TileCtx& tc, const Params& p, ldsp_t wb) {
;     ...
; #pragma unroll
;             for (int h = 0; h < 2; ++h) {
; #pragma unroll
;                 for (int mm = 0; mm < 4; ++mm) {
;                     const int m = h * 4 + mm;
; #pragma unroll
;                     for (int n = 0; n < 4; ++n) {
;                         u32x2 w; w[0] = pk2(gelu_tanh(acc[m][n][0]), gelu_tanh(acc[m][n][1])); w[1] = pk2(gelu_tanh(acc[m][n][2]), gelu_tanh(acc[m][n][3]));
;                         wave_put(wb, mm * 16 + fr, n, fq, w);
;                     }
;                 }
;                 wave_rows_store(wb, tc.lane, p.U + (size_t)(tc.brow + tc.wr * 128 + h * 64) * 1024 + (pn - 3) * 256 + wc * 64, 1024);
	v_mul_f32_e32 v1, v135, v135
	v_fmamk_f32 v1, v1, 0xbdd2d3e7, v191
	v_mul_f32_e32 v1, v135, v1
	s_nop 0
	s_nop 0
	v_exp_f32_e32 v1, v1
	s_nop 0
	v_add_f32_e32 v1, 1.0, v1
	v_rcp_f32_e32 v3, v1
	v_mul_f32_e32 v1, v130, v130
	v_fmamk_f32 v1, v1, 0xbdd2d3e7, v191
	v_mul_f32_e32 v1, v130, v1
	s_nop 0
	s_nop 0
	v_exp_f32_e32 v1, v1
	v_pk_mul_f32 v[2:3], v[134:135], v[2:3]
	v_add_f32_e32 v1, 1.0, v1
	v_rcp_f32_e32 v4, v1
	v_mul_f32_e32 v1, v131, v131
	v_fmamk_f32 v1, v1, 0xbdd2d3e7, v191
	v_mul_f32_e32 v1, v131, v1
	s_nop 0
	s_nop 0
	v_exp_f32_e32 v1, v1
	v_cvt_pk_bf16_f32 v2, v2, v3
	v_add_f32_e32 v1, 1.0, v1
	v_rcp_f32_e32 v5, v1
	v_mul_f32_e32 v1, v122, v122
	v_fmamk_f32 v1, v1, 0xbdd2d3e7, v191
	v_mul_f32_e32 v1, v122, v1
	s_nop 0
	s_nop 0
	v_exp_f32_e32 v1, v1
	v_pk_mul_f32 v[4:5], v[130:131], v[4:5]
	v_add_f32_e32 v1, 1.0, v1
	v_cvt_pk_bf16_f32 v3, v4, v5
	ds_write_b64 v33, v[2:3] offset:4096
	v_rcp_f32_e32 v2, v1
	v_mul_f32_e32 v1, v123, v123
	v_fmamk_f32 v1, v1, 0xbdd2d3e7, v191
	v_mul_f32_e32 v1, v123, v1
	s_nop 0
	s_nop 0
	v_exp_f32_e32 v1, v1
	s_nop 0
	v_add_f32_e32 v1, 1.0, v1
	v_rcp_f32_e32 v3, v1
	v_mul_f32_e32 v1, v118, v118
	v_fmamk_f32 v1, v1, 0xbdd2d3e7, v191
	v_mul_f32_e32 v1, v118, v1
	s_nop 0
	s_nop 0
	v_exp_f32_e32 v1, v1
	v_pk_mul_f32 v[2:3], v[122:123], v[2:3]
	v_add_f32_e32 v1, 1.0, v1
	v_rcp_f32_e32 v4, v1
	v_mul_f32_e32 v1, v119, v119
	v_fmamk_f32 v1, v1, 0xbdd2d3e7, v191
	v_mul_f32_e32 v1, v119, v1
	s_nop 0
	s_nop 0
	v_exp_f32_e32 v1, v1
	v_cvt_pk_bf16_f32 v2, v2, v3
	v_add_f32_e32 v1, 1.0, v1
	v_rcp_f32_e32 v5, v1
	v_mul_f32_e32 v1, v116, v116
	v_fmamk_f32 v1, v1, 0xbdd2d3e7, v191
	v_mul_f32_e32 v1, v116, v1
	s_nop 0
	s_nop 0
	v_exp_f32_e32 v1, v1
	v_pk_mul_f32 v[4:5], v[118:119], v[4:5]
	v_add_f32_e32 v1, 1.0, v1
	v_cvt_pk_bf16_f32 v3, v4, v5
	ds_write_b64 v34, v[2:3] offset:4096
	v_rcp_f32_e32 v2, v1
	v_mul_f32_e32 v1, v117, v117
	v_fmamk_f32 v1, v1, 0xbdd2d3e7, v191
	v_mul_f32_e32 v1, v117, v1
	s_nop 0
	s_nop 0
	v_exp_f32_e32 v1, v1
	s_nop 0
	v_add_f32_e32 v1, 1.0, v1
	v_rcp_f32_e32 v3, v1
	v_mul_f32_e32 v1, v114, v114
	v_fmamk_f32 v1, v1, 0xbdd2d3e7, v191
	v_mul_f32_e32 v1, v114, v1
	s_nop 0
	s_nop 0
	v_exp_f32_e32 v1, v1
	v_pk_mul_f32 v[2:3], v[116:117], v[2:3]
	v_add_f32_e32 v1, 1.0, v1
	v_rcp_f32_e32 v4, v1
	v_mul_f32_e32 v1, v115, v115
	v_fmamk_f32 v1, v1, 0xbdd2d3e7, v191
	v_mul_f32_e32 v1, v115, v1
	s_nop 0
	s_nop 0
	v_exp_f32_e32 v1, v1
	v_cvt_pk_bf16_f32 v2, v2, v3
	v_add_f32_e32 v1, 1.0, v1
	v_rcp_f32_e32 v5, v1
	v_mul_f32_e32 v1, v102, v102
	v_fmamk_f32 v1, v1, 0xbdd2d3e7, v191
	v_mul_f32_e32 v1, v102, v1
	s_nop 0
	s_nop 0
	v_exp_f32_e32 v1, v1
	v_pk_mul_f32 v[4:5], v[114:115], v[4:5]
	v_add_f32_e32 v1, 1.0, v1
	v_cvt_pk_bf16_f32 v3, v4, v5
	ds_write_b64 v35, v[2:3] offset:4096
	v_rcp_f32_e32 v2, v1
	v_mul_f32_e32 v1, v103, v103
	v_fmamk_f32 v1, v1, 0xbdd2d3e7, v191
	v_mul_f32_e32 v1, v103, v1
	s_nop 0
	s_nop 0
	v_exp_f32_e32 v1, v1
	s_nop 0
	v_add_f32_e32 v1, 1.0, v1
	v_rcp_f32_e32 v3, v1
	v_mul_f32_e32 v1, v98, v98
	v_fmamk_f32 v1, v1, 0xbdd2d3e7, v191
	v_mul_f32_e32 v1, v98, v1
	s_nop 0
	s_nop 0
	v_exp_f32_e32 v1, v1
	v_pk_mul_f32 v[2:3], v[102:103], v[2:3]
	v_add_f32_e32 v1, 1.0, v1
	v_rcp_f32_e32 v4, v1
	v_mul_f32_e32 v1, v99, v99
	v_fmamk_f32 v1, v1, 0xbdd2d3e7, v191
	v_mul_f32_e32 v1, v99, v1
	s_nop 0
	s_nop 0
	v_exp_f32_e32 v1, v1
	v_cvt_pk_bf16_f32 v2, v2, v3
	v_add_f32_e32 v1, 1.0, v1
	v_rcp_f32_e32 v5, v1
	v_mul_f32_e32 v1, v100, v100
	v_fmamk_f32 v1, v1, 0xbdd2d3e7, v191
	v_mul_f32_e32 v1, v100, v1
	s_nop 0
	s_nop 0
	v_exp_f32_e32 v1, v1
	v_pk_mul_f32 v[4:5], v[98:99], v[4:5]
	v_add_f32_e32 v1, 1.0, v1
	v_cvt_pk_bf16_f32 v3, v4, v5
	ds_write_b64 v32, v[2:3] offset:6144
	v_rcp_f32_e32 v2, v1
	v_mul_f32_e32 v1, v101, v101
	v_fmamk_f32 v1, v1, 0xbdd2d3e7, v191
	v_mul_f32_e32 v1, v101, v1
	s_nop 0
	s_nop 0
	v_exp_f32_e32 v1, v1
	s_nop 0
	v_add_f32_e32 v1, 1.0, v1
	v_rcp_f32_e32 v3, v1
	v_mul_f32_e32 v1, v96, v96
	v_fmamk_f32 v1, v1, 0xbdd2d3e7, v191
	v_mul_f32_e32 v1, v96, v1
	s_nop 0
	s_nop 0
	v_exp_f32_e32 v1, v1
	v_pk_mul_f32 v[2:3], v[100:101], v[2:3]
	v_add_f32_e32 v1, 1.0, v1
	v_rcp_f32_e32 v4, v1
	v_mul_f32_e32 v1, v97, v97
	v_fmamk_f32 v1, v1, 0xbdd2d3e7, v191
	v_mul_f32_e32 v1, v97, v1
	s_nop 0
	s_nop 0
	v_exp_f32_e32 v1, v1
	v_cvt_pk_bf16_f32 v2, v2, v3
	v_add_f32_e32 v1, 1.0, v1
	v_rcp_f32_e32 v5, v1
	v_mul_f32_e32 v1, v94, v94
	v_fmamk_f32 v1, v1, 0xbdd2d3e7, v191
	v_mul_f32_e32 v1, v94, v1
	s_nop 0
	s_nop 0
	v_exp_f32_e32 v1, v1
	v_pk_mul_f32 v[4:5], v[96:97], v[4:5]
	v_add_f32_e32 v1, 1.0, v1
	v_cvt_pk_bf16_f32 v3, v4, v5
	ds_write_b64 v33, v[2:3] offset:6144
	v_rcp_f32_e32 v2, v1
	v_mul_f32_e32 v1, v95, v95
	v_fmamk_f32 v1, v1, 0xbdd2d3e7, v191
	v_mul_f32_e32 v1, v95, v1
	s_nop 0
	s_nop 0
	v_exp_f32_e32 v1, v1
	s_nop 0
	v_add_f32_e32 v1, 1.0, v1
	v_rcp_f32_e32 v3, v1
	v_mul_f32_e32 v1, v92, v92
	v_fmamk_f32 v1, v1, 0xbdd2d3e7, v191
	v_mul_f32_e32 v1, v92, v1
	s_nop 0
	s_nop 0
	v_exp_f32_e32 v1, v1
	v_pk_mul_f32 v[2:3], v[94:95], v[2:3]
	v_add_f32_e32 v1, 1.0, v1
	v_rcp_f32_e32 v4, v1
	v_mul_f32_e32 v1, v93, v93
	v_fmamk_f32 v1, v1, 0xbdd2d3e7, v191
	v_mul_f32_e32 v1, v93, v1
	s_nop 0
	s_nop 0
	v_exp_f32_e32 v1, v1
	v_cvt_pk_bf16_f32 v2, v2, v3
	v_add_f32_e32 v1, 1.0, v1
	v_rcp_f32_e32 v5, v1
	v_mul_f32_e32 v1, v90, v90
	v_fmamk_f32 v1, v1, 0xbdd2d3e7, v191
	v_mul_f32_e32 v1, v90, v1
	s_nop 0
	s_nop 0
	v_exp_f32_e32 v1, v1
	v_pk_mul_f32 v[4:5], v[92:93], v[4:5]
	v_add_f32_e32 v1, 1.0, v1
	v_cvt_pk_bf16_f32 v3, v4, v5
	ds_write_b64 v34, v[2:3] offset:6144
	v_rcp_f32_e32 v2, v1
	v_mul_f32_e32 v1, v91, v91
	v_fmamk_f32 v1, v1, 0xbdd2d3e7, v191
	v_mul_f32_e32 v1, v91, v1
	s_nop 0
	s_nop 0
	v_exp_f32_e32 v1, v1
	s_nop 0
	v_add_f32_e32 v1, 1.0, v1
	v_rcp_f32_e32 v3, v1
	v_mul_f32_e32 v1, v88, v88
	v_fmamk_f32 v1, v1, 0xbdd2d3e7, v191
	v_mul_f32_e32 v1, v88, v1
	s_nop 0
	s_nop 0
	v_exp_f32_e32 v1, v1
	v_pk_mul_f32 v[2:3], v[90:91], v[2:3]
	v_add_f32_e32 v1, 1.0, v1
	v_rcp_f32_e32 v4, v1
	v_mul_f32_e32 v1, v89, v89
	v_fmamk_f32 v1, v1, 0xbdd2d3e7, v191
	v_mul_f32_e32 v1, v89, v1
	s_nop 0
	s_nop 0
	v_exp_f32_e32 v1, v1
	v_cvt_pk_bf16_f32 v2, v2, v3
	v_add_f32_e32 v1, 1.0, v1
	v_rcp_f32_e32 v5, v1
	s_nop 0
	v_pk_mul_f32 v[4:5], v[88:89], v[4:5]
	s_nop 0
	v_cvt_pk_bf16_f32 v3, v4, v5
	ds_write_b64 v35, v[2:3] offset:6144
	v_lshlrev_b64 v[2:3], 11, v[10:11]
	v_lshl_add_u64 v[2:3], s[16:17], 0, v[2:3]
	v_lshl_add_u64 v[2:3], v[2:3], 0, s[4:5]
	v_lshrrev_b32_e32 v11, 3, v170
	v_lshl_add_u64 v[0:1], v[2:3], 0, v[192:193]
	v_xor_b32_e32 v2, v11, v170
	v_lshlrev_b32_e32 v2, 4, v2
	v_and_b32_e32 v2, 0x70, v2
	v_add_u32_e32 v43, v176, v2
	v_lshlrev_b32_e32 v2, 4, v170
	v_and_b32_e32 v18, 0x70, v2
	v_lshl_add_u32 v42, v11, 7, v43
	v_lshl_add_u64 v[162:163], v[0:1], 0, v[18:19]
	ds_read_b128 v[0:3], v42
	v_lshlrev_b32_e32 v16, 11, v11
	v_lshl_add_u64 v[4:5], v[162:163], 0, v[16:17]
	s_waitcnt lgkmcnt(0)
; DI unsigned pk2(float a, float b) { f32x2 v = {a, b}; bf2_t r = __builtin_convertvector(v, bf2_t); return __builtin_bit_cast(unsigned, r); }
; DI float fexp2(float x) { return __builtin_amdgcn_exp2f(x); }
; DI float gelu_tanh(float x) {
;     const float y = 0.7978845608028654f * (x + 0.044715f * x * x * x);
;     return x * __builtin_amdgcn_rcpf(1.f + fexp2(-2.f * LOG2E * y));
; }
;     static DI void run(const f32x4 (&acc)[8][4], const TileCtx& tc, const Params& p, ldsp_t wb) {
;     ...
; #pragma unroll
;             for (int h = 0; h < 2; ++h) {
; #pragma unroll
;                 for (int mm = 0; mm < 4; ++mm) {
;                     const int m = h * 4 + mm;
; #pragma unroll
;                     for (int n = 0; n < 4; ++n) {
;                         u32x2 w; w[0] = pk2(gelu_tanh(acc[m][n][0]), gelu_tanh(acc[m][n][1])); w[1] = pk2(gelu_tanh(acc[m][n][2]), gelu_tanh(acc[m][n][3]));
;                         wave_put(wb, mm * 16 + fr, n, fq, w);
;                     }
;                 }
;                 wave_rows_store(wb, tc.lane, p.U + (size_t)(tc.brow + tc.wr * 128 + h * 64) * 1024 + (pn - 3) * 256 + wc * 64, 1024);
	global_store_dwordx4 v[4:5], v[0:3], off
	v_or_b32_e32 v4, 8, v11
	v_lshl_add_u32 v41, v4, 7, v43
	ds_read_b128 v[0:3], v41
	v_lshlrev_b32_e32 v14, 11, v4
	v_lshl_add_u64 v[4:5], v[162:163], 0, v[14:15]
	s_waitcnt lgkmcnt(0)
	global_store_dwordx4 v[4:5], v[0:3], off
	v_or_b32_e32 v4, 16, v11
	v_lshl_add_u32 v40, v4, 7, v43
	ds_read_b128 v[0:3], v40
	v_lshlrev_b32_e32 v12, 11, v4
	v_lshl_add_u64 v[4:5], v[162:163], 0, v[12:13]
	s_waitcnt lgkmcnt(0)
	global_store_dwordx4 v[4:5], v[0:3], off
	v_or_b32_e32 v4, 24, v11
	v_lshl_add_u32 v39, v4, 7, v43
	ds_read_b128 v[0:3], v39
	v_lshlrev_b32_e32 v8, 11, v4
	v_lshl_add_u64 v[4:5], v[162:163], 0, v[8:9]
	s_waitcnt lgkmcnt(0)
	global_store_dwordx4 v[4:5], v[0:3], off
	s_nop 1
	v_or_b32_e32 v0, 32, v11
	v_lshl_add_u32 v38, v0, 7, v43
	ds_read_b128 v[4:7], v38
	v_lshlrev_b32_e32 v2, 11, v0
	v_mov_b32_e32 v3, v193
	v_lshl_add_u64 v[0:1], v[162:163], 0, v[2:3]
	s_waitcnt lgkmcnt(0)
	global_store_dwordx4 v[0:1], v[4:7], off
	v_or_b32_e32 v0, 40, v11
	v_lshl_add_u32 v37, v0, 7, v43
	ds_read_b128 v[148:151], v37
	v_lshlrev_b32_e32 v6, 11, v0
	v_mov_b32_e32 v7, v193
	v_lshl_add_u64 v[0:1], v[162:163], 0, v[6:7]
	v_mov_b32_e32 v5, v193
	s_waitcnt lgkmcnt(0)
	global_store_dwordx4 v[0:1], v[148:151], off
	v_or_b32_e32 v0, 48, v11
	v_lshl_add_u32 v36, v0, 7, v43
	ds_read_b128 v[148:151], v36
	v_lshlrev_b32_e32 v4, 11, v0
	v_lshl_add_u64 v[0:1], v[162:163], 0, v[4:5]
	s_waitcnt lgkmcnt(0)
	global_store_dwordx4 v[0:1], v[148:151], off
	v_or_b32_e32 v0, 56, v11
	v_lshl_add_u32 v11, v0, 7, v43
	v_mul_f32_e32 v43, v86, v86
	v_fmamk_f32 v43, v43, 0xbdd2d3e7, v191
	v_mul_f32_e32 v43, v86, v43
	s_nop 0
	s_nop 0
	ds_read_b128 v[148:151], v11
	v_exp_f32_e32 v43, v43
	v_lshlrev_b32_e32 v0, 11, v0
	v_mov_b32_e32 v1, v193
	v_lshl_add_u64 v[162:163], v[162:163], 0, v[0:1]
	v_add_f32_e32 v43, 1.0, v43
	s_waitcnt lgkmcnt(0)
	global_store_dwordx4 v[162:163], v[148:151], off
	s_nop 1
	v_rcp_f32_e32 v148, v43
	v_mul_f32_e32 v43, v87, v87
	v_fmamk_f32 v43, v43, 0xbdd2d3e7, v191
	v_mul_f32_e32 v43, v87, v43
	s_nop 0
	s_nop 0
	v_exp_f32_e32 v43, v43
	s_nop 0
	v_add_f32_e32 v43, 1.0, v43
	v_rcp_f32_e32 v149, v43
	v_mul_f32_e32 v43, v82, v82
	v_fmamk_f32 v43, v43, 0xbdd2d3e7, v191
	v_mul_f32_e32 v43, v82, v43
	s_nop 0
	s_nop 0
	v_exp_f32_e32 v43, v43
	v_pk_mul_f32 v[148:149], v[86:87], v[148:149]
	v_add_f32_e32 v43, 1.0, v43
	v_rcp_f32_e32 v150, v43
	v_mul_f32_e32 v43, v83, v83
	v_fmamk_f32 v43, v43, 0xbdd2d3e7, v191
	v_mul_f32_e32 v43, v83, v43
	s_nop 0
	s_nop 0
	v_exp_f32_e32 v43, v43
	v_cvt_pk_bf16_f32 v148, v148, v149
	v_add_f32_e32 v43, 1.0, v43
	v_rcp_f32_e32 v151, v43
	v_mul_f32_e32 v43, v84, v84
	v_fmamk_f32 v43, v43, 0xbdd2d3e7, v191
	v_mul_f32_e32 v43, v84, v43
	s_nop 0
	s_nop 0
	v_exp_f32_e32 v43, v43
	v_pk_mul_f32 v[150:151], v[82:83], v[150:151]
	v_add_f32_e32 v43, 1.0, v43
	v_cvt_pk_bf16_f32 v149, v150, v151
	ds_write_b64 v32, v[148:149]
	v_rcp_f32_e32 v148, v43
	v_mul_f32_e32 v43, v85, v85
	v_fmamk_f32 v43, v43, 0xbdd2d3e7, v191
	v_mul_f32_e32 v43, v85, v43
	s_nop 0
	s_nop 0
	v_exp_f32_e32 v43, v43
	s_nop 0
	v_add_f32_e32 v43, 1.0, v43
	v_rcp_f32_e32 v149, v43
	v_mul_f32_e32 v43, v80, v80
	v_fmamk_f32 v43, v43, 0xbdd2d3e7, v191
	v_mul_f32_e32 v43, v80, v43
	s_nop 0
	s_nop 0
	v_exp_f32_e32 v43, v43
	v_pk_mul_f32 v[148:149], v[84:85], v[148:149]
	v_add_f32_e32 v43, 1.0, v43
	v_rcp_f32_e32 v150, v43
	v_mul_f32_e32 v43, v81, v81
	v_fmamk_f32 v43, v43, 0xbdd2d3e7, v191
	v_mul_f32_e32 v43, v81, v43
	s_nop 0
	s_nop 0
	v_exp_f32_e32 v43, v43
	v_cvt_pk_bf16_f32 v148, v148, v149
	v_add_f32_e32 v43, 1.0, v43
	v_rcp_f32_e32 v151, v43
	v_mul_f32_e32 v43, v78, v78
	v_fmamk_f32 v43, v43, 0xbdd2d3e7, v191
	v_mul_f32_e32 v43, v78, v43
	s_nop 0
	s_nop 0
	v_exp_f32_e32 v43, v43
	v_pk_mul_f32 v[150:151], v[80:81], v[150:151]
	v_add_f32_e32 v43, 1.0, v43
	v_cvt_pk_bf16_f32 v149, v150, v151
	ds_write_b64 v33, v[148:149]
	v_rcp_f32_e32 v148, v43
	v_mul_f32_e32 v43, v79, v79
	v_fmamk_f32 v43, v43, 0xbdd2d3e7, v191
	v_mul_f32_e32 v43, v79, v43
	s_nop 0
	s_nop 0
	v_exp_f32_e32 v43, v43
	s_nop 0
	v_add_f32_e32 v43, 1.0, v43
	v_rcp_f32_e32 v149, v43
	v_mul_f32_e32 v43, v76, v76
	v_fmamk_f32 v43, v43, 0xbdd2d3e7, v191
	v_mul_f32_e32 v43, v76, v43
	s_nop 0
	s_nop 0
	v_exp_f32_e32 v43, v43
	v_pk_mul_f32 v[148:149], v[78:79], v[148:149]
	v_add_f32_e32 v43, 1.0, v43
	v_rcp_f32_e32 v150, v43
	v_mul_f32_e32 v43, v77, v77
	v_fmamk_f32 v43, v43, 0xbdd2d3e7, v191
	v_mul_f32_e32 v43, v77, v43
	s_nop 0
	s_nop 0
	v_exp_f32_e32 v43, v43
	v_cvt_pk_bf16_f32 v148, v148, v149
	v_add_f32_e32 v43, 1.0, v43
	v_rcp_f32_e32 v151, v43
	v_mul_f32_e32 v43, v74, v74
	v_fmamk_f32 v43, v43, 0xbdd2d3e7, v191
	v_mul_f32_e32 v43, v74, v43
	s_nop 0
	s_nop 0
	v_exp_f32_e32 v43, v43
	v_pk_mul_f32 v[150:151], v[76:77], v[150:151]
	v_add_f32_e32 v43, 1.0, v43
	v_cvt_pk_bf16_f32 v149, v150, v151
	ds_write_b64 v34, v[148:149]
	v_rcp_f32_e32 v148, v43
	v_mul_f32_e32 v43, v75, v75
	v_fmamk_f32 v43, v43, 0xbdd2d3e7, v191
	v_mul_f32_e32 v43, v75, v43
	s_nop 0
	s_nop 0
	v_exp_f32_e32 v43, v43
	s_nop 0
	v_add_f32_e32 v43, 1.0, v43
	v_rcp_f32_e32 v149, v43
	v_mul_f32_e32 v43, v72, v72
	v_fmamk_f32 v43, v43, 0xbdd2d3e7, v191
	v_mul_f32_e32 v43, v72, v43
	s_nop 0
	s_nop 0
	v_exp_f32_e32 v43, v43
	v_pk_mul_f32 v[148:149], v[74:75], v[148:149]
	v_add_f32_e32 v43, 1.0, v43
	v_rcp_f32_e32 v150, v43
	v_mul_f32_e32 v43, v73, v73
	v_fmamk_f32 v43, v43, 0xbdd2d3e7, v191
	v_mul_f32_e32 v43, v73, v43
	s_nop 0
	s_nop 0
	v_exp_f32_e32 v43, v43
	v_cvt_pk_bf16_f32 v148, v148, v149
	v_add_f32_e32 v43, 1.0, v43
	v_rcp_f32_e32 v151, v43
	v_mul_f32_e32 v43, v70, v70
	v_fmamk_f32 v43, v43, 0xbdd2d3e7, v191
; DI unsigned pk2(float a, float b) { f32x2 v = {a, b}; bf2_t r = __builtin_convertvector(v, bf2_t); return __builtin_bit_cast(unsigned, r); }
; DI float fexp2(float x) { return __builtin_amdgcn_exp2f(x); }
; DI float gelu_tanh(float x) {
;     const float y = 0.7978845608028654f * (x + 0.044715f * x * x * x);
;     return x * __builtin_amdgcn_rcpf(1.f + fexp2(-2.f * LOG2E * y));
; }
;     static DI void run(const f32x4 (&acc)[8][4], const TileCtx& tc, const Params& p, ldsp_t wb) {
;     ...
; #pragma unroll
;             for (int h = 0; h < 2; ++h) {
; #pragma unroll
;                 for (int mm = 0; mm < 4; ++mm) {
;                     const int m = h * 4 + mm;
; #pragma unroll
;                     for (int n = 0; n < 4; ++n) {
;                         u32x2 w; w[0] = pk2(gelu_tanh(acc[m][n][0]), gelu_tanh(acc[m][n][1])); w[1] = pk2(gelu_tanh(acc[m][n][2]), gelu_tanh(acc[m][n][3]));
;                         wave_put(wb, mm * 16 + fr, n, fq, w);
;                     }
;                 }
;                 wave_rows_store(wb, tc.lane, p.U + (size_t)(tc.brow + tc.wr * 128 + h * 64) * 1024 + (pn - 3) * 256 + wc * 64, 1024);
	v_mul_f32_e32 v43, v70, v43
	s_nop 0
	s_nop 0
	v_exp_f32_e32 v43, v43
	v_pk_mul_f32 v[150:151], v[72:73], v[150:151]
	v_add_f32_e32 v43, 1.0, v43
	v_cvt_pk_bf16_f32 v149, v150, v151
	ds_write_b64 v35, v[148:149]
	v_rcp_f32_e32 v148, v43
	v_mul_f32_e32 v43, v71, v71
	v_fmamk_f32 v43, v43, 0xbdd2d3e7, v191
	v_mul_f32_e32 v43, v71, v43
	s_nop 0
	s_nop 0
	v_exp_f32_e32 v43, v43
	s_nop 0
	v_add_f32_e32 v43, 1.0, v43
	v_rcp_f32_e32 v149, v43
	v_mul_f32_e32 v43, v68, v68
	v_fmamk_f32 v43, v43, 0xbdd2d3e7, v191
	v_mul_f32_e32 v43, v68, v43
	s_nop 0
	s_nop 0
	v_exp_f32_e32 v43, v43
	v_pk_mul_f32 v[148:149], v[70:71], v[148:149]
	v_add_f32_e32 v43, 1.0, v43
	v_rcp_f32_e32 v150, v43
	v_mul_f32_e32 v43, v69, v69
	v_fmamk_f32 v43, v43, 0xbdd2d3e7, v191
	v_mul_f32_e32 v43, v69, v43
	s_nop 0
	s_nop 0
	v_exp_f32_e32 v43, v43
	v_cvt_pk_bf16_f32 v148, v148, v149
	v_add_f32_e32 v43, 1.0, v43
	v_rcp_f32_e32 v151, v43
	v_mul_f32_e32 v43, v66, v66
	v_fmamk_f32 v43, v43, 0xbdd2d3e7, v191
	v_mul_f32_e32 v43, v66, v43
	s_nop 0
	s_nop 0
	v_exp_f32_e32 v43, v43
	v_pk_mul_f32 v[150:151], v[68:69], v[150:151]
	v_add_f32_e32 v43, 1.0, v43
	v_cvt_pk_bf16_f32 v149, v150, v151
	ds_write_b64 v32, v[148:149] offset:2048
	v_rcp_f32_e32 v148, v43
	v_mul_f32_e32 v43, v67, v67
	v_fmamk_f32 v43, v43, 0xbdd2d3e7, v191
	v_mul_f32_e32 v43, v67, v43
	s_nop 0
	s_nop 0
	v_exp_f32_e32 v43, v43
	s_nop 0
	v_add_f32_e32 v43, 1.0, v43
	v_rcp_f32_e32 v149, v43
	v_mul_f32_e32 v43, v64, v64
	v_fmamk_f32 v43, v43, 0xbdd2d3e7, v191
	v_mul_f32_e32 v43, v64, v43
	s_nop 0
	s_nop 0
	v_exp_f32_e32 v43, v43
	v_pk_mul_f32 v[148:149], v[66:67], v[148:149]
	v_add_f32_e32 v43, 1.0, v43
	v_rcp_f32_e32 v150, v43
	v_mul_f32_e32 v43, v65, v65
	v_fmamk_f32 v43, v43, 0xbdd2d3e7, v191
	v_mul_f32_e32 v43, v65, v43
	s_nop 0
	s_nop 0
	v_exp_f32_e32 v43, v43
	v_cvt_pk_bf16_f32 v148, v148, v149
	v_add_f32_e32 v43, 1.0, v43
	v_rcp_f32_e32 v151, v43
	v_mul_f32_e32 v43, v62, v62
	v_fmamk_f32 v43, v43, 0xbdd2d3e7, v191
	v_mul_f32_e32 v43, v62, v43
	s_nop 0
	s_nop 0
	v_exp_f32_e32 v43, v43
	v_pk_mul_f32 v[150:151], v[64:65], v[150:151]
	v_add_f32_e32 v43, 1.0, v43
	v_cvt_pk_bf16_f32 v149, v150, v151
	ds_write_b64 v33, v[148:149] offset:2048
	v_rcp_f32_e32 v148, v43
	v_mul_f32_e32 v43, v63, v63
	v_fmamk_f32 v43, v43, 0xbdd2d3e7, v191
	v_mul_f32_e32 v43, v63, v43
	s_nop 0
	s_nop 0
	v_exp_f32_e32 v43, v43
	s_nop 0
	v_add_f32_e32 v43, 1.0, v43
	v_rcp_f32_e32 v149, v43
	v_mul_f32_e32 v43, v60, v60
	v_fmamk_f32 v43, v43, 0xbdd2d3e7, v191
	v_mul_f32_e32 v43, v60, v43
	s_nop 0
	s_nop 0
	v_exp_f32_e32 v43, v43
	v_pk_mul_f32 v[148:149], v[62:63], v[148:149]
	v_add_f32_e32 v43, 1.0, v43
	v_rcp_f32_e32 v150, v43
	v_mul_f32_e32 v43, v61, v61
	v_fmamk_f32 v43, v43, 0xbdd2d3e7, v191
	v_mul_f32_e32 v43, v61, v43
	s_nop 0
	s_nop 0
	v_exp_f32_e32 v43, v43
	v_cvt_pk_bf16_f32 v148, v148, v149
	v_add_f32_e32 v43, 1.0, v43
	v_rcp_f32_e32 v151, v43
	v_mul_f32_e32 v43, v58, v58
	v_fmamk_f32 v43, v43, 0xbdd2d3e7, v191
	v_mul_f32_e32 v43, v58, v43
	s_nop 0
	s_nop 0
	v_exp_f32_e32 v43, v43
	v_pk_mul_f32 v[150:151], v[60:61], v[150:151]
	v_add_f32_e32 v43, 1.0, v43
	v_cvt_pk_bf16_f32 v149, v150, v151
	ds_write_b64 v34, v[148:149] offset:2048
	v_rcp_f32_e32 v148, v43
	v_mul_f32_e32 v43, v59, v59
	v_fmamk_f32 v43, v43, 0xbdd2d3e7, v191
	v_mul_f32_e32 v43, v59, v43
	s_nop 0
	s_nop 0
	v_exp_f32_e32 v43, v43
	s_nop 0
	v_add_f32_e32 v43, 1.0, v43
	v_rcp_f32_e32 v149, v43
	v_mul_f32_e32 v43, v56, v56
	v_fmamk_f32 v43, v43, 0xbdd2d3e7, v191
	v_mul_f32_e32 v43, v56, v43
	s_nop 0
	s_nop 0
	v_exp_f32_e32 v43, v43
	v_pk_mul_f32 v[148:149], v[58:59], v[148:149]
	v_add_f32_e32 v43, 1.0, v43
	v_rcp_f32_e32 v150, v43
	v_mul_f32_e32 v43, v57, v57
	v_fmamk_f32 v43, v43, 0xbdd2d3e7, v191
	v_mul_f32_e32 v43, v57, v43
	s_nop 0
	s_nop 0
	v_exp_f32_e32 v43, v43
	v_cvt_pk_bf16_f32 v148, v148, v149
	v_add_f32_e32 v43, 1.0, v43
	v_rcp_f32_e32 v151, v43
	v_mul_f32_e32 v43, v110, v110
	v_fmamk_f32 v43, v43, 0xbdd2d3e7, v191
	v_mul_f32_e32 v43, v110, v43
	s_nop 0
	s_nop 0
	v_exp_f32_e32 v43, v43
	v_pk_mul_f32 v[150:151], v[56:57], v[150:151]
	v_add_f32_e32 v43, 1.0, v43
	v_cvt_pk_bf16_f32 v149, v150, v151
	ds_write_b64 v35, v[148:149] offset:2048
	v_rcp_f32_e32 v148, v43
	v_mul_f32_e32 v43, v111, v111
	v_fmamk_f32 v43, v43, 0xbdd2d3e7, v191
	v_mul_f32_e32 v43, v111, v43
	s_nop 0
	s_nop 0
	v_exp_f32_e32 v43, v43
	s_nop 0
	v_add_f32_e32 v43, 1.0, v43
	v_rcp_f32_e32 v149, v43
	v_mul_f32_e32 v43, v108, v108
	v_fmamk_f32 v43, v43, 0xbdd2d3e7, v191
	v_mul_f32_e32 v43, v108, v43
	s_nop 0
	s_nop 0
	v_exp_f32_e32 v43, v43
	v_pk_mul_f32 v[148:149], v[110:111], v[148:149]
	v_add_f32_e32 v43, 1.0, v43
	v_rcp_f32_e32 v150, v43
	v_mul_f32_e32 v43, v109, v109
	v_fmamk_f32 v43, v43, 0xbdd2d3e7, v191
	v_mul_f32_e32 v43, v109, v43
	s_nop 0
	s_nop 0
	v_exp_f32_e32 v43, v43
	v_cvt_pk_bf16_f32 v148, v148, v149
	v_add_f32_e32 v43, 1.0, v43
	v_rcp_f32_e32 v151, v43
	v_mul_f32_e32 v43, v106, v106
	v_fmamk_f32 v43, v43, 0xbdd2d3e7, v191
	v_mul_f32_e32 v43, v106, v43
	s_nop 0
	s_nop 0
	v_exp_f32_e32 v43, v43
	v_pk_mul_f32 v[150:151], v[108:109], v[150:151]
	v_add_f32_e32 v43, 1.0, v43
	v_cvt_pk_bf16_f32 v149, v150, v151
	ds_write_b64 v32, v[148:149] offset:4096
	v_rcp_f32_e32 v148, v43
	v_mul_f32_e32 v43, v107, v107
	v_fmamk_f32 v43, v43, 0xbdd2d3e7, v191
	v_mul_f32_e32 v43, v107, v43
	s_nop 0
	s_nop 0
	v_exp_f32_e32 v43, v43
	s_nop 0
	v_add_f32_e32 v43, 1.0, v43
	v_rcp_f32_e32 v149, v43
	v_mul_f32_e32 v43, v104, v104
	v_fmamk_f32 v43, v43, 0xbdd2d3e7, v191
	v_mul_f32_e32 v43, v104, v43
	s_nop 0
	s_nop 0
	v_exp_f32_e32 v43, v43
	v_pk_mul_f32 v[148:149], v[106:107], v[148:149]
	v_add_f32_e32 v43, 1.0, v43
; DI unsigned pk2(float a, float b) { f32x2 v = {a, b}; bf2_t r = __builtin_convertvector(v, bf2_t); return __builtin_bit_cast(unsigned, r); }
; DI float fexp2(float x) { return __builtin_amdgcn_exp2f(x); }
; DI float gelu_tanh(float x) {
;     const float y = 0.7978845608028654f * (x + 0.044715f * x * x * x);
;     return x * __builtin_amdgcn_rcpf(1.f + fexp2(-2.f * LOG2E * y));
; }
;     static DI void run(const f32x4 (&acc)[8][4], const TileCtx& tc, const Params& p, ldsp_t wb) {
;     ...
; #pragma unroll
;             for (int h = 0; h < 2; ++h) {
; #pragma unroll
;                 for (int mm = 0; mm < 4; ++mm) {
;                     const int m = h * 4 + mm;
; #pragma unroll
;                     for (int n = 0; n < 4; ++n) {
;                         u32x2 w; w[0] = pk2(gelu_tanh(acc[m][n][0]), gelu_tanh(acc[m][n][1])); w[1] = pk2(gelu_tanh(acc[m][n][2]), gelu_tanh(acc[m][n][3]));
;                         wave_put(wb, mm * 16 + fr, n, fq, w);
;                     }
;                 }
;                 wave_rows_store(wb, tc.lane, p.U + (size_t)(tc.brow + tc.wr * 128 + h * 64) * 1024 + (pn - 3) * 256 + wc * 64, 1024);
	v_rcp_f32_e32 v150, v43
	v_mul_f32_e32 v43, v105, v105
	v_fmamk_f32 v43, v43, 0xbdd2d3e7, v191
	v_mul_f32_e32 v43, v105, v43
	s_nop 0
	s_nop 0
	v_exp_f32_e32 v43, v43
	v_cvt_pk_bf16_f32 v148, v148, v149
	v_add_f32_e32 v43, 1.0, v43
	v_rcp_f32_e32 v151, v43
	v_mul_f32_e32 v43, v54, v54
	v_fmamk_f32 v43, v43, 0xbdd2d3e7, v191
	v_mul_f32_e32 v43, v54, v43
	s_nop 0
	s_nop 0
	v_exp_f32_e32 v43, v43
	v_pk_mul_f32 v[150:151], v[104:105], v[150:151]
	v_add_f32_e32 v43, 1.0, v43
	v_cvt_pk_bf16_f32 v149, v150, v151
	ds_write_b64 v33, v[148:149] offset:4096
	v_rcp_f32_e32 v148, v43
	v_mul_f32_e32 v43, v55, v55
	v_fmamk_f32 v43, v43, 0xbdd2d3e7, v191
	v_mul_f32_e32 v43, v55, v43
	s_nop 0
	s_nop 0
	v_exp_f32_e32 v43, v43
	s_nop 0
	v_add_f32_e32 v43, 1.0, v43
	v_rcp_f32_e32 v149, v43
	v_mul_f32_e32 v43, v52, v52
	v_fmamk_f32 v43, v43, 0xbdd2d3e7, v191
	v_mul_f32_e32 v43, v52, v43
	s_nop 0
	s_nop 0
	v_exp_f32_e32 v43, v43
	v_pk_mul_f32 v[148:149], v[54:55], v[148:149]
	v_add_f32_e32 v43, 1.0, v43
	v_rcp_f32_e32 v150, v43
	v_mul_f32_e32 v43, v53, v53
	v_fmamk_f32 v43, v43, 0xbdd2d3e7, v191
	v_mul_f32_e32 v43, v53, v43
	s_nop 0
	s_nop 0
	v_exp_f32_e32 v43, v43
	v_cvt_pk_bf16_f32 v148, v148, v149
	v_add_f32_e32 v43, 1.0, v43
	v_rcp_f32_e32 v151, v43
	v_mul_f32_e32 v43, v50, v50
	v_fmamk_f32 v43, v43, 0xbdd2d3e7, v191
	v_mul_f32_e32 v43, v50, v43
	s_nop 0
	s_nop 0
	v_exp_f32_e32 v43, v43
	v_pk_mul_f32 v[150:151], v[52:53], v[150:151]
	v_add_f32_e32 v43, 1.0, v43
	v_cvt_pk_bf16_f32 v149, v150, v151
	ds_write_b64 v34, v[148:149] offset:4096
	v_rcp_f32_e32 v148, v43
	v_mul_f32_e32 v43, v51, v51
	v_fmamk_f32 v43, v43, 0xbdd2d3e7, v191
	v_mul_f32_e32 v43, v51, v43
	s_nop 0
	s_nop 0
	v_exp_f32_e32 v43, v43
	s_nop 0
	v_add_f32_e32 v43, 1.0, v43
	v_rcp_f32_e32 v149, v43
	v_mul_f32_e32 v43, v48, v48
	v_fmamk_f32 v43, v43, 0xbdd2d3e7, v191
	v_mul_f32_e32 v43, v48, v43
	s_nop 0
	s_nop 0
	v_exp_f32_e32 v43, v43
	v_pk_mul_f32 v[148:149], v[50:51], v[148:149]
	v_add_f32_e32 v43, 1.0, v43
	v_rcp_f32_e32 v150, v43
	v_mul_f32_e32 v43, v49, v49
	v_fmamk_f32 v43, v43, 0xbdd2d3e7, v191
	v_mul_f32_e32 v43, v49, v43
	s_nop 0
	s_nop 0
	v_exp_f32_e32 v43, v43
	v_cvt_pk_bf16_f32 v148, v148, v149
	v_add_f32_e32 v43, 1.0, v43
	v_rcp_f32_e32 v151, v43
	v_mul_f32_e32 v43, v44, v44
	v_fmamk_f32 v43, v43, 0xbdd2d3e7, v191
	v_mul_f32_e32 v43, v44, v43
	s_nop 0
	s_nop 0
	v_exp_f32_e32 v43, v43
	v_pk_mul_f32 v[150:151], v[48:49], v[150:151]
	v_add_f32_e32 v43, 1.0, v43
	v_cvt_pk_bf16_f32 v149, v150, v151
	ds_write_b64 v35, v[148:149] offset:4096
	v_rcp_f32_e32 v148, v43
	v_mul_f32_e32 v43, v45, v45
	v_fmamk_f32 v43, v43, 0xbdd2d3e7, v191
	v_mul_f32_e32 v43, v45, v43
	s_nop 0
	s_nop 0
	v_exp_f32_e32 v43, v43
	s_nop 0
	v_add_f32_e32 v43, 1.0, v43
	v_rcp_f32_e32 v149, v43
	v_mul_f32_e32 v43, v46, v46
	v_fmamk_f32 v43, v43, 0xbdd2d3e7, v191
	v_mul_f32_e32 v43, v46, v43
	s_nop 0
	s_nop 0
	v_exp_f32_e32 v43, v43
	v_pk_mul_f32 v[148:149], v[44:45], v[148:149]
	v_add_f32_e32 v43, 1.0, v43
	v_rcp_f32_e32 v150, v43
	v_mul_f32_e32 v43, v47, v47
	v_fmamk_f32 v43, v43, 0xbdd2d3e7, v191
	v_mul_f32_e32 v43, v47, v43
	s_nop 0
	s_nop 0
	v_exp_f32_e32 v43, v43
	v_cvt_pk_bf16_f32 v148, v148, v149
	v_add_f32_e32 v43, 1.0, v43
	v_rcp_f32_e32 v151, v43
	s_nop 0
	v_pk_mul_f32 v[150:151], v[46:47], v[150:151]
	s_nop 0
	v_cvt_pk_bf16_f32 v149, v150, v151
	ds_write_b64 v32, v[148:149] offset:6144
	v_mul_f32_e32 v32, v30, v30
	v_fmamk_f32 v32, v32, 0xbdd2d3e7, v191
	v_mul_f32_e32 v32, v30, v32
	s_nop 0
	s_nop 0
	v_exp_f32_e32 v32, v32
	s_nop 0
	v_add_f32_e32 v32, 1.0, v32
	v_rcp_f32_e32 v148, v32
	v_mul_f32_e32 v32, v31, v31
	v_fmamk_f32 v32, v32, 0xbdd2d3e7, v191
	v_mul_f32_e32 v32, v31, v32
	s_nop 0
	s_nop 0
	v_exp_f32_e32 v32, v32
	s_nop 0
	v_add_f32_e32 v32, 1.0, v32
	v_rcp_f32_e32 v149, v32
	v_mul_f32_e32 v32, v28, v28
	v_fmamk_f32 v32, v32, 0xbdd2d3e7, v191
	v_mul_f32_e32 v32, v28, v32
	s_nop 0
	s_nop 0
	v_exp_f32_e32 v32, v32
	v_pk_mul_f32 v[148:149], v[30:31], v[148:149]
	v_add_f32_e32 v32, 1.0, v32
	v_rcp_f32_e32 v150, v32
	v_mul_f32_e32 v32, v29, v29
	v_fmamk_f32 v32, v32, 0xbdd2d3e7, v191
	v_mul_f32_e32 v32, v29, v32
	s_nop 0
	s_nop 0
	v_exp_f32_e32 v32, v32
	v_cvt_pk_bf16_f32 v148, v148, v149
	v_add_f32_e32 v32, 1.0, v32
	v_rcp_f32_e32 v151, v32
	v_mul_f32_e32 v32, v26, v26
	v_fmamk_f32 v32, v32, 0xbdd2d3e7, v191
	v_mul_f32_e32 v32, v26, v32
	v_pk_mul_f32 v[150:151], v[28:29], v[150:151]
	s_nop 0
	v_cvt_pk_bf16_f32 v149, v150, v151
	ds_write_b64 v33, v[148:149] offset:6144
	v_mul_f32_e32 v33, v27, v27
	v_fmamk_f32 v33, v33, 0xbdd2d3e7, v191
	v_mul_f32_e32 v33, v27, v33
	s_nop 0
	s_nop 0
	s_nop 0
	v_exp_f32_e32 v32, v32
	v_exp_f32_e32 v33, v33
	v_add_f32_e32 v32, 1.0, v32
	v_add_f32_e32 v33, 1.0, v33
	v_rcp_f32_e32 v32, v32
	v_rcp_f32_e32 v33, v33
	s_nop 0
	v_pk_mul_f32 v[32:33], v[26:27], v[32:33]
	s_nop 0
	v_cvt_pk_bf16_f32 v32, v32, v33
	v_mul_f32_e32 v33, v24, v24
	v_fmamk_f32 v33, v33, 0xbdd2d3e7, v191
	v_mul_f32_e32 v33, v24, v33
	s_nop 0
	s_nop 0
	v_exp_f32_e32 v33, v33
	s_nop 0
	v_add_f32_e32 v33, 1.0, v33
	v_rcp_f32_e32 v148, v33
	v_mul_f32_e32 v33, v25, v25
	v_fmamk_f32 v33, v33, 0xbdd2d3e7, v191
	v_mul_f32_e32 v33, v25, v33
	s_nop 0
	s_nop 0
	v_exp_f32_e32 v33, v33
	s_nop 0
	v_add_f32_e32 v33, 1.0, v33
	v_rcp_f32_e32 v149, v33
	s_nop 0
	v_pk_mul_f32 v[148:149], v[24:25], v[148:149]
	s_nop 0
	v_cvt_pk_bf16_f32 v33, v148, v149
	ds_write_b64 v34, v[32:33] offset:6144
	v_mul_f32_e32 v32, v22, v22
	v_mul_f32_e32 v33, v23, v23
	v_fmamk_f32 v32, v32, 0xbdd2d3e7, v191
	v_fmamk_f32 v33, v33, 0xbdd2d3e7, v191
	v_mul_f32_e32 v32, v22, v32
	v_mul_f32_e32 v33, v23, v33
	s_nop 0
	s_nop 0
	s_nop 0
	s_nop 0
	v_exp_f32_e32 v32, v32
	v_exp_f32_e32 v33, v33
	v_add_f32_e32 v32, 1.0, v32
	v_add_f32_e32 v33, 1.0, v33
	v_rcp_f32_e32 v32, v32
	v_rcp_f32_e32 v33, v33
	s_nop 0
	v_pk_mul_f32 v[32:33], v[22:23], v[32:33]
	s_nop 0
	v_cvt_pk_bf16_f32 v32, v32, v33
	v_mul_f32_e32 v33, v20, v20
	v_fmamk_f32 v33, v33, 0xbdd2d3e7, v191
	v_mul_f32_e32 v33, v20, v33
	s_nop 0
	s_nop 0
	v_exp_f32_e32 v33, v33
	s_nop 0
	v_add_f32_e32 v33, 1.0, v33
	v_rcp_f32_e32 v148, v33
	v_mul_f32_e32 v33, v21, v21
	v_fmamk_f32 v33, v33, 0xbdd2d3e7, v191
	v_mul_f32_e32 v33, v21, v33
	s_nop 0
	s_nop 0
	v_exp_f32_e32 v33, v33
	s_nop 0
	v_add_f32_e32 v33, 1.0, v33
	v_rcp_f32_e32 v149, v33
	s_nop 0
	v_pk_mul_f32 v[148:149], v[20:21], v[148:149]
	s_nop 0
	v_cvt_pk_bf16_f32 v33, v148, v149
	ds_write_b64 v35, v[32:33] offset:6144
	v_or_b32_e32 v32, 64, v10
	v_ashrrev_i32_e32 v33, 31, v32
	v_lshlrev_b64 v[32:33], 11, v[32:33]
	v_lshl_add_u64 v[32:33], s[16:17], 0, v[32:33]
	v_lshl_add_u64 v[32:33], v[32:33], 0, s[4:5]
	v_lshl_add_u64 v[32:33], v[32:33], 0, v[192:193]
	v_lshl_add_u64 v[148:149], v[32:33], 0, v[18:19]
	ds_read_b128 v[32:35], v42
	v_lshl_add_u64 v[16:17], v[148:149], 0, v[16:17]
	v_lshl_add_u64 v[14:15], v[148:149], 0, v[14:15]
	v_lshl_add_u64 v[12:13], v[148:149], 0, v[12:13]
	v_lshl_add_u64 v[8:9], v[148:149], 0, v[8:9]
	s_waitcnt lgkmcnt(0)
; #define LDSP __attribute__((address_space(3)))
; DI void wave_rows_store(ldsp_t wb, int lane, bf16_t* dst0, size_t ld) {
; #pragma unroll
;     for (int i = 0; i < 8; ++i) {
;         const int row = i * 8 + (lane >> 3), ch = lane & 7;
;         const u32x4 v = *(const LDSP u32x4*)(wb + row * 128 + ((ch ^ (row & 7)) << 4));
;         *(u32x4*)(dst0 + (size_t)row * ld + ch * 8) = v;
;     }
; }
	global_store_dwordx4 v[16:17], v[32:35], off
	ds_read_b128 v[16:19], v41
	v_lshl_add_u64 v[2:3], v[148:149], 0, v[2:3]
	v_lshl_add_u64 v[0:1], v[148:149], 0, v[0:1]
	s_mov_b64 s[4:5], 0
	s_waitcnt lgkmcnt(0)
	global_store_dwordx4 v[14:15], v[16:19], off
	ds_read_b128 v[14:17], v40
	s_waitcnt lgkmcnt(0)
	global_store_dwordx4 v[12:13], v[14:17], off
	ds_read_b128 v[12:15], v39
	s_waitcnt lgkmcnt(0)
	global_store_dwordx4 v[8:9], v[12:15], off
	ds_read_b128 v[12:15], v38
	s_waitcnt lgkmcnt(0)
	global_store_dwordx4 v[2:3], v[12:15], off
	ds_read_b128 v[12:15], v37
	v_lshl_add_u64 v[2:3], v[148:149], 0, v[6:7]
	ds_read_b128 v[6:9], v36
	s_waitcnt lgkmcnt(1)
	global_store_dwordx4 v[2:3], v[12:15], off
	v_lshl_add_u64 v[2:3], v[148:149], 0, v[4:5]
	s_waitcnt lgkmcnt(0)
	global_store_dwordx4 v[2:3], v[6:9], off
	ds_read_b128 v[2:5], v11
	s_waitcnt lgkmcnt(0)
	global_store_dwordx4 v[0:1], v[2:5], off

;     static DI void run(const f32x4 (&acc)[8][4], const TileCtx& tc, const Params& p, ldsp_t wb) {
;     ...
;             const float* gn = (isq ? p.q_norm_g : p.k_norm_g) + l * 64;
;             f32x4 gv[4];
; #pragma unroll
;             for (int n = 0; n < 4; ++n) gv[n] = *(const f32x4*)(gn + n * 16 + fq * 4);
;             const float osc = isq ? 0.125f * LOG2E : 1.f;
;             const bool lat = tc.brow < NLAT;
; #pragma unroll
;             for (int h = 0; h < 2; ++h) {
; #pragma unroll
;                 for (int mm = 0; mm < 4; ++mm) { __builtin_amdgcn_sched_barrier(0);
;                     const int m = h * 4 + mm;
;                     const int row = tc.brow + tc.wr * 128 + m * 16 + fr;
;                     float ss = 0.f;
; #pragma unroll
;                     for (int n = 0; n < 4; ++n)
; #pragma unroll
;                         for (int j = 0; j < 4; ++j) ss += acc[m][n][j] * acc[m][n][j];
;                     ss += __shfl_xor(ss, 16);
;                     ss += __shfl_xor(ss, 32);
;                     const float rstd = rsqrtf(ss * (1.f / 64.f) + EPS) * osc;
;                     const int t = row & 4095;
; #pragma unroll
;                     for (int ax = 0; ax < 2; ++ax) {
;                         f32x4 x1 = acc[m][2 * ax] * rstd * gv[2 * ax], x2 = acc[m][2 * ax + 1] * rstd * gv[2 * ax + 1];
;                         if (lat) {
;                             const int pos = ax == 0 ? (t >> 6) : (t & 63);
;                             const f32x4 cs = *(const f32x4*)(p.rope + pos * 16 + fq * 4), sn = *(const f32x4*)(p.rope + 1024 + pos * 16 + fq * 4);
;                             const f32x4 o1 = x1 * cs - x2 * sn, o2 = x2 * cs + x1 * sn;
;                             x1 = o1; x2 = o2;
;                         }
.LBB0_283:
	s_andn2_saveexec_b64 s[6:7], s[4:5]
	s_cbranch_execz .LBB0_325
	v_readlane_b32 s4, v255, 5
	v_lshlrev_b32_e32 v32, 2, v175
	v_readlane_b32 s5, v255, 6
	s_nop 4
	global_load_dwordx4 v[12:15], v32, s[4:5]
	global_load_dwordx4 v[8:11], v32, s[4:5] offset:64
	global_load_dwordx4 v[4:7], v32, s[4:5] offset:128
	global_load_dwordx4 v[0:3], v32, s[4:5] offset:192
	v_add_u32_e32 v228, s41, v174
	v_and_b32_e32 v228, 0xf80, v228
	v_add_u32_e32 v228, v228, v32
	v_lshl_add_u32 v229, v169, 6, v32
	global_load_dwordx4 v[220:223], v228, s[18:19]
	global_load_dwordx4 v[224:227], v228, s[68:69]
	global_load_dwordx4 v[232:235], v229, s[18:19]
	global_load_dwordx4 v[236:239], v229, s[68:69]
	global_load_dwordx4 v[240:243], v229, s[18:19] offset:1024
	global_load_dwordx4 v[244:247], v229, s[68:69] offset:1024
	global_load_dwordx4 v[248:251], v229, s[18:19] offset:2048
	global_load_dwordx4 v[204:207], v229, s[68:69] offset:2048
	global_load_dwordx4 v[210:213], v229, s[18:19] offset:3072
	global_load_dwordx4 v[194:197], v229, s[68:69] offset:3072
	s_cmp_lt_i32 s31, 64
	s_cselect_b64 s[8:9], -1, 0
	s_cmp_gt_i32 s31, 63
	s_cselect_b64 s[34:35], -1, 0
	v_mul_f32_e32 v33, v161, v161
	v_fmac_f32_e32 v33, v160, v160
	v_fmac_f32_e32 v33, v158, v158
	v_fmac_f32_e32 v33, v159, v159
	v_fmac_f32_e32 v33, v156, v156
	v_fmac_f32_e32 v33, v157, v157
	v_fmac_f32_e32 v33, v154, v154
	v_fmac_f32_e32 v33, v155, v155
	v_pk_mul_f32 v[18:19], v[152:153], v[152:153]
	v_pk_mul_f32 v[16:17], v[216:217], v[216:217]
	v_add_f32_e32 v18, v18, v33
	v_add_f32_e32 v18, v19, v18
	v_add_f32_e32 v16, v16, v18
	v_add_f32_e32 v33, v17, v16
	v_pk_mul_f32 v[18:19], v[214:215], v[214:215]
	v_pk_mul_f32 v[16:17], v[146:147], v[146:147]
	v_add_f32_e32 v18, v18, v33
	v_add_f32_e32 v18, v19, v18
	v_add_f32_e32 v16, v16, v18
	v_add_f32_e32 v16, v17, v16
	ds_bpermute_b32 v17, v113, v16
	s_waitcnt lgkmcnt(0)
	v_add_f32_e32 v16, v16, v17
	ds_bpermute_b32 v17, v168, v16
	s_waitcnt lgkmcnt(0)
	v_add_f32_e32 v16, v16, v17
	v_fmamk_f32 v16, v16, 0x3c800000, v208
	v_cmp_gt_f32_e32 vcc, s92, v16
	v_mul_f32_e32 v17, 0x4b800000, v16
	s_nop 0
	v_cndmask_b32_e32 v16, v16, v17, vcc
	v_rsq_f32_e32 v16, v16
	s_nop 0
	v_mul_f32_e32 v17, 0x45800000, v16
	v_cndmask_b32_e32 v34, v16, v17, vcc
	v_pk_mul_f32 v[16:17], v[160:161], v[34:35] op_sel_hi:[1,0]
	v_pk_mul_f32 v[18:19], v[158:159], v[34:35] op_sel_hi:[1,0]
	v_pk_mul_f32 v[38:39], v[156:157], v[34:35] op_sel_hi:[1,0]
	v_pk_mul_f32 v[36:37], v[154:155], v[34:35] op_sel_hi:[1,0]
	s_waitcnt vmcnt(13)
	v_pk_mul_f32 v[18:19], v[14:15], v[18:19]
	v_pk_mul_f32 v[16:17], v[12:13], v[16:17]
	s_waitcnt vmcnt(12)
	v_pk_mul_f32 v[36:37], v[10:11], v[36:37]
	v_pk_mul_f32 v[38:39], v[8:9], v[38:39]
	s_and_b64 vcc, exec, s[34:35]
	s_cbranch_vccnz .LBB0_286
	v_add_u32_e32 v33, s41, v174
	v_and_b32_e32 v192, 0xf80, v33
	v_mov_b32_e32 v33, v193
	v_lshl_add_u64 v[40:41], s[18:19], 0, v[192:193]
	v_lshl_add_u64 v[40:41], v[40:41], 0, v[32:33]
	v_lshl_add_u64 v[148:149], s[68:69], 0, v[192:193]
	v_lshl_add_u64 v[148:149], v[148:149], 0, v[32:33]
	s_waitcnt vmcnt(0)
	v_mov_b64_e32 v[40:41], v[220:221]
	v_mov_b64_e32 v[42:43], v[222:223]
	v_pk_mul_f32 v[162:163], v[36:37], v[42:43]
	v_pk_mul_f32 v[164:165], v[38:39], v[40:41]
	v_pk_mul_f32 v[42:43], v[18:19], v[42:43]
	v_pk_mul_f32 v[40:41], v[16:17], v[40:41]
	v_mov_b64_e32 v[148:149], v[224:225]
	v_mov_b64_e32 v[150:151], v[226:227]
	v_pk_fma_f32 v[18:19], v[18:19], v[150:151], v[162:163] neg_lo:[0,0,1] neg_hi:[0,0,1]
	v_pk_fma_f32 v[16:17], v[16:17], v[148:149], v[164:165] neg_lo:[0,0,1] neg_hi:[0,0,1]
	v_pk_fma_f32 v[36:37], v[36:37], v[150:151], v[42:43]
	v_pk_fma_f32 v[38:39], v[38:39], v[148:149], v[40:41]
.LBB0_286:
	v_lshrrev_b32_e32 v40, 5, v170
	v_lshlrev_b32_e32 v42, 3, v173
	v_lshlrev_b32_e32 v33, 7, v169
	v_and_b32_e32 v42, 8, v42
	v_cvt_pk_bf16_f32 v16, v16, v17
	v_cvt_pk_bf16_f32 v17, v18, v19
	v_bitop3_b32 v18, v40, v172, 7 bitop3:0x78
	v_and_b32_e32 v41, 7, v172
	v_add3_u32 v42, v176, v33, v42
	v_lshlrev_b32_e32 v18, 4, v18
	v_add_u32_e32 v177, v42, v18
	v_bitop3_b32 v18, v40, v41, 2 bitop3:0x36
	v_lshlrev_b32_e32 v18, 4, v18
	v_mov_b32_e32 v35, v34
	ds_write_b64 v177, v[16:17]
	v_cvt_pk_bf16_f32 v16, v38, v39
	v_cvt_pk_bf16_f32 v17, v36, v37
	v_add_u32_e32 v178, v42, v18
	v_mov_b32_e32 v36, v34
	v_mov_b32_e32 v37, v34
	ds_write_b64 v178, v[16:17]
	v_pk_mul_f32 v[16:17], v[216:217], v[36:37]
	v_pk_mul_f32 v[38:39], v[152:153], v[34:35]
	s_waitcnt vmcnt(1)
	v_pk_mul_f32 v[18:19], v[6:7], v[16:17]
	v_pk_mul_f32 v[16:17], v[4:5], v[38:39]
	v_pk_mul_f32 v[36:37], v[146:147], v[36:37]
	v_pk_mul_f32 v[38:39], v[214:215], v[34:35]
	v_cndmask_b32_e64 v33, 0, 1, s[8:9]
	s_waitcnt vmcnt(0)
	v_pk_mul_f32 v[34:35], v[2:3], v[36:37]
	v_cmp_ne_u32_e64 s[4:5], 1, v33
	s_andn2_b64 vcc, exec, s[8:9]
	v_pk_mul_f32 v[36:37], v[0:1], v[38:39]
	s_cbranch_vccnz .LBB0_288
	v_lshlrev_b32_e32 v192, 6, v169
	v_mov_b32_e32 v33, v193
	v_lshl_add_u64 v[38:39], s[18:19], 0, v[192:193]
	v_lshl_add_u64 v[38:39], v[38:39], 0, v[32:33]
	v_lshl_add_u64 v[38:39], s[68:69], 0, v[192:193]
	v_lshl_add_u64 v[38:39], v[38:39], 0, v[32:33]
	v_mov_b64_e32 v[148:149], v[232:233]
	v_mov_b64_e32 v[150:151], v[234:235]
	v_pk_mul_f32 v[38:39], v[34:35], v[150:151]
	v_pk_mul_f32 v[166:167], v[36:37], v[148:149]
	v_pk_mul_f32 v[150:151], v[18:19], v[150:151]
	v_pk_mul_f32 v[148:149], v[16:17], v[148:149]
	v_mov_b64_e32 v[162:163], v[236:237]
	v_mov_b64_e32 v[164:165], v[238:239]
	v_pk_fma_f32 v[18:19], v[18:19], v[164:165], v[38:39] neg_lo:[0,0,1] neg_hi:[0,0,1]
	v_pk_fma_f32 v[16:17], v[16:17], v[162:163], v[166:167] neg_lo:[0,0,1] neg_hi:[0,0,1]
	v_pk_fma_f32 v[34:35], v[34:35], v[164:165], v[150:151]
	v_pk_fma_f32 v[36:37], v[36:37], v[162:163], v[148:149]
; DI unsigned pk2(float a, float b) { f32x2 v = {a, b}; bf2_t r = __builtin_convertvector(v, bf2_t); return __builtin_bit_cast(unsigned, r); }
;     static DI void run(const f32x4 (&acc)[8][4], const TileCtx& tc, const Params& p, ldsp_t wb) {
;     ...
;                 for (int mm = 0; mm < 4; ++mm) { __builtin_amdgcn_sched_barrier(0);
;                     const int m = h * 4 + mm;
;                     const int row = tc.brow + tc.wr * 128 + m * 16 + fr;
;                     float ss = 0.f;
; #pragma unroll
;                     for (int n = 0; n < 4; ++n)
; #pragma unroll
;                         for (int j = 0; j < 4; ++j) ss += acc[m][n][j] * acc[m][n][j];
;                     ss += __shfl_xor(ss, 16);
;                     ss += __shfl_xor(ss, 32);
;                     const float rstd = rsqrtf(ss * (1.f / 64.f) + EPS) * osc;
;                     const int t = row & 4095;
; #pragma unroll
;                     for (int ax = 0; ax < 2; ++ax) {
;                         f32x4 x1 = acc[m][2 * ax] * rstd * gv[2 * ax], x2 = acc[m][2 * ax + 1] * rstd * gv[2 * ax + 1];
;                         if (lat) {
;                             const int pos = ax == 0 ? (t >> 6) : (t & 63);
;                             const f32x4 cs = *(const f32x4*)(p.rope + pos * 16 + fq * 4), sn = *(const f32x4*)(p.rope + 1024 + pos * 16 + fq * 4);
;                             const f32x4 o1 = x1 * cs - x2 * sn, o2 = x2 * cs + x1 * sn;
;                             x1 = o1; x2 = o2;
;                         }
;                         u32x2 w; w[0] = pk2(x1[0], x1[1]); w[1] = pk2(x1[2], x1[3]);
;                         wave_put(wb, mm * 16 + fr, 2 * ax, fq, w);
;                         w[0] = pk2(x2[0], x2[1]); w[1] = pk2(x2[2], x2[3]);
;                         wave_put(wb, mm * 16 + fr, 2 * ax + 1, fq, w);
.LBB0_288:
	v_cvt_pk_bf16_f32 v16, v16, v17
	v_cvt_pk_bf16_f32 v17, v18, v19
	v_bitop3_b32 v18, v40, v41, 4 bitop3:0x36
	v_lshlrev_b32_e32 v18, 4, v18
	v_add_u32_e32 v179, v42, v18
	v_bitop3_b32 v18, v40, v41, 6 bitop3:0x36
	v_lshlrev_b32_e32 v18, 4, v18
	ds_write_b64 v179, v[16:17]
	v_cvt_pk_bf16_f32 v16, v36, v37
	v_cvt_pk_bf16_f32 v17, v34, v35
	v_add_u32_e32 v180, v42, v18
	ds_write_b64 v180, v[16:17]
	v_mul_f32_e32 v33, v145, v145
	v_fmac_f32_e32 v33, v144, v144
	v_fmac_f32_e32 v33, v140, v140
	v_fmac_f32_e32 v33, v141, v141
	v_fmac_f32_e32 v33, v142, v142
	v_fmac_f32_e32 v33, v143, v143
	v_fmac_f32_e32 v33, v138, v138
	v_fmac_f32_e32 v33, v139, v139
	v_pk_mul_f32 v[18:19], v[128:129], v[128:129]
	v_pk_mul_f32 v[16:17], v[126:127], v[126:127]
	v_add_f32_e32 v18, v18, v33
	v_add_f32_e32 v18, v19, v18
	v_add_f32_e32 v16, v16, v18
	v_add_f32_e32 v33, v17, v16
	v_pk_mul_f32 v[18:19], v[124:125], v[124:125]
	v_pk_mul_f32 v[16:17], v[120:121], v[120:121]
	v_add_f32_e32 v18, v18, v33
	v_add_f32_e32 v18, v19, v18
	v_add_f32_e32 v16, v16, v18
	v_add_f32_e32 v16, v17, v16
	ds_bpermute_b32 v17, v113, v16
	s_waitcnt lgkmcnt(0)
	v_add_f32_e32 v16, v16, v17
	ds_bpermute_b32 v17, v168, v16
	s_waitcnt lgkmcnt(0)
	v_add_f32_e32 v16, v16, v17
	v_fmamk_f32 v16, v16, 0x3c800000, v208
	v_cmp_gt_f32_e32 vcc, s92, v16
	v_mul_f32_e32 v17, 0x4b800000, v16
	s_nop 0
	v_cndmask_b32_e32 v16, v16, v17, vcc
	v_rsq_f32_e32 v16, v16
	s_nop 0
	v_mul_f32_e32 v17, 0x45800000, v16
	v_cndmask_b32_e32 v34, v16, v17, vcc
	v_pk_mul_f32 v[16:17], v[144:145], v[34:35] op_sel_hi:[1,0]
	v_pk_mul_f32 v[18:19], v[140:141], v[34:35] op_sel_hi:[1,0]
	v_pk_mul_f32 v[38:39], v[142:143], v[34:35] op_sel_hi:[1,0]
	v_pk_mul_f32 v[36:37], v[138:139], v[34:35] op_sel_hi:[1,0]
	v_pk_mul_f32 v[18:19], v[14:15], v[18:19]
	v_pk_mul_f32 v[16:17], v[12:13], v[16:17]
	v_pk_mul_f32 v[36:37], v[10:11], v[36:37]
	v_pk_mul_f32 v[38:39], v[8:9], v[38:39]
	s_and_b64 vcc, exec, s[4:5]
	s_cbranch_vccnz .LBB0_290
	v_add_u32_e32 v33, s41, v174
	v_and_b32_e32 v192, 0xf80, v33
	v_mov_b32_e32 v33, v193
	v_lshl_add_u64 v[40:41], s[18:19], 0, v[192:193]
	v_lshl_add_u64 v[40:41], v[40:41], 0, v[32:33]
	v_lshl_add_u64 v[148:149], s[68:69], 0, v[192:193]
	v_lshl_add_u64 v[148:149], v[148:149], 0, v[32:33]
	v_mov_b64_e32 v[40:41], v[220:221]
	v_mov_b64_e32 v[42:43], v[222:223]
	v_pk_mul_f32 v[162:163], v[36:37], v[42:43]
	v_pk_mul_f32 v[164:165], v[38:39], v[40:41]
	v_pk_mul_f32 v[42:43], v[18:19], v[42:43]
	v_pk_mul_f32 v[40:41], v[16:17], v[40:41]
	v_mov_b64_e32 v[148:149], v[224:225]
	v_mov_b64_e32 v[150:151], v[226:227]
	v_pk_fma_f32 v[18:19], v[18:19], v[150:151], v[162:163] neg_lo:[0,0,1] neg_hi:[0,0,1]
	v_pk_fma_f32 v[16:17], v[16:17], v[148:149], v[164:165] neg_lo:[0,0,1] neg_hi:[0,0,1]
	v_pk_fma_f32 v[36:37], v[36:37], v[150:151], v[42:43]
	v_pk_fma_f32 v[38:39], v[38:39], v[148:149], v[40:41]
.LBB0_290:
	v_cvt_pk_bf16_f32 v16, v16, v17
	v_cvt_pk_bf16_f32 v17, v18, v19
	v_mov_b32_e32 v35, v34
	ds_write_b64 v177, v[16:17] offset:2048
	v_cvt_pk_bf16_f32 v16, v38, v39
	v_cvt_pk_bf16_f32 v17, v36, v37
	v_mov_b32_e32 v36, v34
	v_mov_b32_e32 v37, v34
	ds_write_b64 v178, v[16:17] offset:2048
	v_pk_mul_f32 v[16:17], v[126:127], v[36:37]
	v_pk_mul_f32 v[38:39], v[128:129], v[34:35]
	v_pk_mul_f32 v[18:19], v[6:7], v[16:17]
	v_pk_mul_f32 v[16:17], v[4:5], v[38:39]
	v_pk_mul_f32 v[36:37], v[120:121], v[36:37]
	v_pk_mul_f32 v[38:39], v[124:125], v[34:35]
	v_pk_mul_f32 v[34:35], v[2:3], v[36:37]
	s_and_b64 vcc, exec, s[4:5]
	v_pk_mul_f32 v[36:37], v[0:1], v[38:39]
	s_cbranch_vccnz .LBB0_292
	v_lshlrev_b32_e32 v192, 6, v169
	v_mov_b32_e32 v33, v193
	v_lshl_add_u64 v[42:43], s[68:69], 0, v[192:193]
	v_lshl_add_u64 v[38:39], s[18:19], 0, v[32:33]
	v_or_b32_e32 v192, 0x400, v192
	v_lshl_add_u64 v[38:39], v[38:39], 0, v[192:193]
	v_lshl_add_u64 v[42:43], v[42:43], 0, v[32:33]
	v_mov_b64_e32 v[38:39], v[240:241]
	v_mov_b64_e32 v[40:41], v[242:243]
	v_pk_mul_f32 v[42:43], v[34:35], v[40:41]
	v_pk_mul_f32 v[162:163], v[36:37], v[38:39]
	v_pk_mul_f32 v[40:41], v[18:19], v[40:41]
	v_pk_mul_f32 v[38:39], v[16:17], v[38:39]
	v_mov_b64_e32 v[148:149], v[244:245]
	v_mov_b64_e32 v[150:151], v[246:247]
	v_pk_fma_f32 v[18:19], v[18:19], v[150:151], v[42:43] neg_lo:[0,0,1] neg_hi:[0,0,1]
	v_pk_fma_f32 v[16:17], v[16:17], v[148:149], v[162:163] neg_lo:[0,0,1] neg_hi:[0,0,1]
	v_pk_fma_f32 v[34:35], v[34:35], v[150:151], v[40:41]
	v_pk_fma_f32 v[36:37], v[36:37], v[148:149], v[38:39]
; DI unsigned pk2(float a, float b) { f32x2 v = {a, b}; bf2_t r = __builtin_convertvector(v, bf2_t); return __builtin_bit_cast(unsigned, r); }
;     static DI void run(const f32x4 (&acc)[8][4], const TileCtx& tc, const Params& p, ldsp_t wb) {
;     ...
;                 for (int mm = 0; mm < 4; ++mm) { __builtin_amdgcn_sched_barrier(0);
;                     const int m = h * 4 + mm;
;                     const int row = tc.brow + tc.wr * 128 + m * 16 + fr;
;                     float ss = 0.f;
; #pragma unroll
;                     for (int n = 0; n < 4; ++n)
; #pragma unroll
;                         for (int j = 0; j < 4; ++j) ss += acc[m][n][j] * acc[m][n][j];
;                     ss += __shfl_xor(ss, 16);
;                     ss += __shfl_xor(ss, 32);
;                     const float rstd = rsqrtf(ss * (1.f / 64.f) + EPS) * osc;
;                     const int t = row & 4095;
; #pragma unroll
;                     for (int ax = 0; ax < 2; ++ax) {
;                         f32x4 x1 = acc[m][2 * ax] * rstd * gv[2 * ax], x2 = acc[m][2 * ax + 1] * rstd * gv[2 * ax + 1];
;                         if (lat) {
;                             const int pos = ax == 0 ? (t >> 6) : (t & 63);
;                             const f32x4 cs = *(const f32x4*)(p.rope + pos * 16 + fq * 4), sn = *(const f32x4*)(p.rope + 1024 + pos * 16 + fq * 4);
;                             const f32x4 o1 = x1 * cs - x2 * sn, o2 = x2 * cs + x1 * sn;
;                             x1 = o1; x2 = o2;
;                         }
;                         u32x2 w; w[0] = pk2(x1[0], x1[1]); w[1] = pk2(x1[2], x1[3]);
;                         wave_put(wb, mm * 16 + fr, 2 * ax, fq, w);
;                         w[0] = pk2(x2[0], x2[1]); w[1] = pk2(x2[2], x2[3]);
;                         wave_put(wb, mm * 16 + fr, 2 * ax + 1, fq, w);
.LBB0_292:
	v_cvt_pk_bf16_f32 v16, v16, v17
	v_cvt_pk_bf16_f32 v17, v18, v19
	ds_write_b64 v179, v[16:17] offset:2048
	v_cvt_pk_bf16_f32 v16, v36, v37
	v_cvt_pk_bf16_f32 v17, v34, v35
	ds_write_b64 v180, v[16:17] offset:2048
	v_mul_f32_e32 v33, v137, v137
	v_fmac_f32_e32 v33, v136, v136
	v_fmac_f32_e32 v33, v132, v132
	v_fmac_f32_e32 v33, v133, v133
	v_fmac_f32_e32 v33, v134, v134
	v_fmac_f32_e32 v33, v135, v135
	v_fmac_f32_e32 v33, v130, v130
	v_fmac_f32_e32 v33, v131, v131
	v_pk_mul_f32 v[18:19], v[122:123], v[122:123]
	v_pk_mul_f32 v[16:17], v[118:119], v[118:119]
	v_add_f32_e32 v18, v18, v33
	v_add_f32_e32 v18, v19, v18
	v_add_f32_e32 v16, v16, v18
	v_add_f32_e32 v33, v17, v16
	v_pk_mul_f32 v[18:19], v[116:117], v[116:117]
	v_pk_mul_f32 v[16:17], v[114:115], v[114:115]
	v_add_f32_e32 v18, v18, v33
	v_add_f32_e32 v18, v19, v18
	v_add_f32_e32 v16, v16, v18
	v_add_f32_e32 v16, v17, v16
	ds_bpermute_b32 v17, v113, v16
	s_waitcnt lgkmcnt(0)
	v_add_f32_e32 v16, v16, v17
	ds_bpermute_b32 v17, v168, v16
	s_waitcnt lgkmcnt(0)
	v_add_f32_e32 v16, v16, v17
	v_fmamk_f32 v16, v16, 0x3c800000, v208
	v_cmp_gt_f32_e32 vcc, s92, v16
	v_mul_f32_e32 v17, 0x4b800000, v16
	s_nop 0
	v_cndmask_b32_e32 v16, v16, v17, vcc
	v_rsq_f32_e32 v16, v16
	s_nop 0
	v_mul_f32_e32 v17, 0x45800000, v16
	v_cndmask_b32_e32 v34, v16, v17, vcc
	v_pk_mul_f32 v[16:17], v[136:137], v[34:35] op_sel_hi:[1,0]
	v_pk_mul_f32 v[18:19], v[132:133], v[34:35] op_sel_hi:[1,0]
	v_pk_mul_f32 v[38:39], v[134:135], v[34:35] op_sel_hi:[1,0]
	v_pk_mul_f32 v[36:37], v[130:131], v[34:35] op_sel_hi:[1,0]
	v_pk_mul_f32 v[18:19], v[14:15], v[18:19]
	v_pk_mul_f32 v[16:17], v[12:13], v[16:17]
	v_pk_mul_f32 v[36:37], v[10:11], v[36:37]
	v_pk_mul_f32 v[38:39], v[8:9], v[38:39]
	s_and_b64 vcc, exec, s[4:5]
	s_cbranch_vccnz .LBB0_294
	v_add_u32_e32 v33, s41, v174
	v_and_b32_e32 v192, 0xf80, v33
	v_mov_b32_e32 v33, v193
	v_lshl_add_u64 v[40:41], s[18:19], 0, v[192:193]
	v_lshl_add_u64 v[40:41], v[40:41], 0, v[32:33]
	v_lshl_add_u64 v[148:149], s[68:69], 0, v[192:193]
	v_lshl_add_u64 v[148:149], v[148:149], 0, v[32:33]
	v_mov_b64_e32 v[40:41], v[220:221]
	v_mov_b64_e32 v[42:43], v[222:223]
	v_pk_mul_f32 v[162:163], v[36:37], v[42:43]
	v_pk_mul_f32 v[164:165], v[38:39], v[40:41]
	v_pk_mul_f32 v[42:43], v[18:19], v[42:43]
	v_pk_mul_f32 v[40:41], v[16:17], v[40:41]
	v_mov_b64_e32 v[148:149], v[224:225]
	v_mov_b64_e32 v[150:151], v[226:227]
	v_pk_fma_f32 v[18:19], v[18:19], v[150:151], v[162:163] neg_lo:[0,0,1] neg_hi:[0,0,1]
	v_pk_fma_f32 v[16:17], v[16:17], v[148:149], v[164:165] neg_lo:[0,0,1] neg_hi:[0,0,1]
	v_pk_fma_f32 v[36:37], v[36:37], v[150:151], v[42:43]
	v_pk_fma_f32 v[38:39], v[38:39], v[148:149], v[40:41]
.LBB0_294:
	v_cvt_pk_bf16_f32 v16, v16, v17
	v_cvt_pk_bf16_f32 v17, v18, v19
	v_mov_b32_e32 v35, v34
	ds_write_b64 v177, v[16:17] offset:4096
	v_cvt_pk_bf16_f32 v16, v38, v39
	v_cvt_pk_bf16_f32 v17, v36, v37
	v_mov_b32_e32 v36, v34
	v_mov_b32_e32 v37, v34
	ds_write_b64 v178, v[16:17] offset:4096
	v_pk_mul_f32 v[16:17], v[118:119], v[36:37]
	v_pk_mul_f32 v[38:39], v[122:123], v[34:35]
	v_pk_mul_f32 v[18:19], v[6:7], v[16:17]
	v_pk_mul_f32 v[16:17], v[4:5], v[38:39]
	v_pk_mul_f32 v[36:37], v[114:115], v[36:37]
	v_pk_mul_f32 v[38:39], v[116:117], v[34:35]
	v_pk_mul_f32 v[34:35], v[2:3], v[36:37]
	s_and_b64 vcc, exec, s[4:5]
	v_pk_mul_f32 v[36:37], v[0:1], v[38:39]
	s_cbranch_vccnz .LBB0_296
	v_lshlrev_b32_e32 v192, 6, v169
	v_mov_b32_e32 v33, v193
	v_lshl_add_u64 v[42:43], s[68:69], 0, v[192:193]
	v_lshl_add_u64 v[38:39], s[18:19], 0, v[32:33]
	v_or_b32_e32 v192, 0x800, v192
	v_lshl_add_u64 v[38:39], v[38:39], 0, v[192:193]
	v_lshl_add_u64 v[42:43], v[42:43], 0, v[32:33]
	v_mov_b64_e32 v[38:39], v[248:249]
	v_mov_b64_e32 v[40:41], v[250:251]
	v_pk_mul_f32 v[42:43], v[34:35], v[40:41]
	v_pk_mul_f32 v[162:163], v[36:37], v[38:39]
	v_pk_mul_f32 v[40:41], v[18:19], v[40:41]
	v_pk_mul_f32 v[38:39], v[16:17], v[38:39]
	v_mov_b64_e32 v[148:149], v[204:205]
	v_mov_b64_e32 v[150:151], v[206:207]
	v_pk_fma_f32 v[18:19], v[18:19], v[150:151], v[42:43] neg_lo:[0,0,1] neg_hi:[0,0,1]
	v_pk_fma_f32 v[16:17], v[16:17], v[148:149], v[162:163] neg_lo:[0,0,1] neg_hi:[0,0,1]
	v_pk_fma_f32 v[34:35], v[34:35], v[150:151], v[40:41]
	v_pk_fma_f32 v[36:37], v[36:37], v[148:149], v[38:39]
; DI unsigned pk2(float a, float b) { f32x2 v = {a, b}; bf2_t r = __builtin_convertvector(v, bf2_t); return __builtin_bit_cast(unsigned, r); }
;     static DI void run(const f32x4 (&acc)[8][4], const TileCtx& tc, const Params& p, ldsp_t wb) {
;     ...
;                 for (int mm = 0; mm < 4; ++mm) { __builtin_amdgcn_sched_barrier(0);
;                     const int m = h * 4 + mm;
;                     const int row = tc.brow + tc.wr * 128 + m * 16 + fr;
;                     float ss = 0.f;
; #pragma unroll
;                     for (int n = 0; n < 4; ++n)
; #pragma unroll
;                         for (int j = 0; j < 4; ++j) ss += acc[m][n][j] * acc[m][n][j];
;                     ss += __shfl_xor(ss, 16);
;                     ss += __shfl_xor(ss, 32);
;                     const float rstd = rsqrtf(ss * (1.f / 64.f) + EPS) * osc;
;                     const int t = row & 4095;
; #pragma unroll
;                     for (int ax = 0; ax < 2; ++ax) {
;                         f32x4 x1 = acc[m][2 * ax] * rstd * gv[2 * ax], x2 = acc[m][2 * ax + 1] * rstd * gv[2 * ax + 1];
;                         if (lat) {
;                             const int pos = ax == 0 ? (t >> 6) : (t & 63);
;                             const f32x4 cs = *(const f32x4*)(p.rope + pos * 16 + fq * 4), sn = *(const f32x4*)(p.rope + 1024 + pos * 16 + fq * 4);
;                             const f32x4 o1 = x1 * cs - x2 * sn, o2 = x2 * cs + x1 * sn;
;                             x1 = o1; x2 = o2;
;                         }
;                         u32x2 w; w[0] = pk2(x1[0], x1[1]); w[1] = pk2(x1[2], x1[3]);
;                         wave_put(wb, mm * 16 + fr, 2 * ax, fq, w);
;                         w[0] = pk2(x2[0], x2[1]); w[1] = pk2(x2[2], x2[3]);
;                         wave_put(wb, mm * 16 + fr, 2 * ax + 1, fq, w);
.LBB0_296:
	v_cvt_pk_bf16_f32 v16, v16, v17
	v_cvt_pk_bf16_f32 v17, v18, v19
	ds_write_b64 v179, v[16:17] offset:4096
	v_cvt_pk_bf16_f32 v16, v36, v37
	v_cvt_pk_bf16_f32 v17, v34, v35
	ds_write_b64 v180, v[16:17] offset:4096
	v_mul_f32_e32 v33, v103, v103
	v_fmac_f32_e32 v33, v102, v102
	v_fmac_f32_e32 v33, v98, v98
	v_fmac_f32_e32 v33, v99, v99
	v_fmac_f32_e32 v33, v100, v100
	v_fmac_f32_e32 v33, v101, v101
	v_fmac_f32_e32 v33, v96, v96
	v_fmac_f32_e32 v33, v97, v97
	v_pk_mul_f32 v[18:19], v[94:95], v[94:95]
	v_pk_mul_f32 v[16:17], v[92:93], v[92:93]
	v_add_f32_e32 v18, v18, v33
	v_add_f32_e32 v18, v19, v18
	v_add_f32_e32 v16, v16, v18
	v_add_f32_e32 v33, v17, v16
	v_pk_mul_f32 v[18:19], v[90:91], v[90:91]
	v_pk_mul_f32 v[16:17], v[88:89], v[88:89]
	v_add_f32_e32 v18, v18, v33
	v_add_f32_e32 v18, v19, v18
	v_add_f32_e32 v16, v16, v18
	v_add_f32_e32 v16, v17, v16
	ds_bpermute_b32 v17, v113, v16
	s_waitcnt lgkmcnt(0)
	v_add_f32_e32 v16, v16, v17
	ds_bpermute_b32 v17, v168, v16
	s_waitcnt lgkmcnt(0)
	v_add_f32_e32 v16, v16, v17
	v_fmamk_f32 v16, v16, 0x3c800000, v208
	v_cmp_gt_f32_e32 vcc, s92, v16
	v_mul_f32_e32 v17, 0x4b800000, v16
	s_nop 0
	v_cndmask_b32_e32 v16, v16, v17, vcc
	v_rsq_f32_e32 v16, v16
	s_nop 0
	v_mul_f32_e32 v17, 0x45800000, v16
	v_cndmask_b32_e32 v34, v16, v17, vcc
	v_pk_mul_f32 v[16:17], v[102:103], v[34:35] op_sel_hi:[1,0]
	v_pk_mul_f32 v[18:19], v[98:99], v[34:35] op_sel_hi:[1,0]
	v_pk_mul_f32 v[38:39], v[100:101], v[34:35] op_sel_hi:[1,0]
	v_pk_mul_f32 v[36:37], v[96:97], v[34:35] op_sel_hi:[1,0]
	v_pk_mul_f32 v[18:19], v[14:15], v[18:19]
	v_pk_mul_f32 v[16:17], v[12:13], v[16:17]
	v_pk_mul_f32 v[36:37], v[10:11], v[36:37]
	v_pk_mul_f32 v[38:39], v[8:9], v[38:39]
	s_and_b64 vcc, exec, s[4:5]
	s_cbranch_vccnz .LBB0_298
	v_add_u32_e32 v33, s41, v174
	v_and_b32_e32 v192, 0xf80, v33
	v_mov_b32_e32 v33, v193
	v_lshl_add_u64 v[40:41], s[18:19], 0, v[192:193]
	v_lshl_add_u64 v[40:41], v[40:41], 0, v[32:33]
	v_lshl_add_u64 v[148:149], s[68:69], 0, v[192:193]
	v_lshl_add_u64 v[148:149], v[148:149], 0, v[32:33]
	v_mov_b64_e32 v[40:41], v[220:221]
	v_mov_b64_e32 v[42:43], v[222:223]
	v_pk_mul_f32 v[162:163], v[36:37], v[42:43]
	v_pk_mul_f32 v[164:165], v[38:39], v[40:41]
	v_pk_mul_f32 v[42:43], v[18:19], v[42:43]
	v_pk_mul_f32 v[40:41], v[16:17], v[40:41]
	v_mov_b64_e32 v[148:149], v[224:225]
	v_mov_b64_e32 v[150:151], v[226:227]
	v_pk_fma_f32 v[18:19], v[18:19], v[150:151], v[162:163] neg_lo:[0,0,1] neg_hi:[0,0,1]
	v_pk_fma_f32 v[16:17], v[16:17], v[148:149], v[164:165] neg_lo:[0,0,1] neg_hi:[0,0,1]
	v_pk_fma_f32 v[36:37], v[36:37], v[150:151], v[42:43]
	v_pk_fma_f32 v[38:39], v[38:39], v[148:149], v[40:41]
.LBB0_298:
	v_cvt_pk_bf16_f32 v16, v16, v17
	v_cvt_pk_bf16_f32 v17, v18, v19
	v_mov_b32_e32 v35, v34
	ds_write_b64 v177, v[16:17] offset:6144
	v_cvt_pk_bf16_f32 v16, v38, v39
	v_cvt_pk_bf16_f32 v17, v36, v37
	v_mov_b32_e32 v36, v34
	v_mov_b32_e32 v37, v34
	ds_write_b64 v178, v[16:17] offset:6144
	v_pk_mul_f32 v[16:17], v[92:93], v[36:37]
	v_pk_mul_f32 v[38:39], v[94:95], v[34:35]
	v_pk_mul_f32 v[18:19], v[6:7], v[16:17]
	v_pk_mul_f32 v[16:17], v[4:5], v[38:39]
	v_pk_mul_f32 v[36:37], v[88:89], v[36:37]
	v_pk_mul_f32 v[38:39], v[90:91], v[34:35]
	v_pk_mul_f32 v[34:35], v[2:3], v[36:37]
	s_and_b64 vcc, exec, s[4:5]
	v_pk_mul_f32 v[36:37], v[0:1], v[38:39]
	s_cbranch_vccnz .LBB0_300
	v_lshlrev_b32_e32 v192, 6, v169
	v_mov_b32_e32 v33, v193
	v_lshl_add_u64 v[42:43], s[68:69], 0, v[192:193]
	v_lshl_add_u64 v[38:39], s[18:19], 0, v[32:33]
	v_or_b32_e32 v192, 0xc00, v192
	v_lshl_add_u64 v[38:39], v[38:39], 0, v[192:193]
	v_lshl_add_u64 v[42:43], v[42:43], 0, v[32:33]
	v_mov_b64_e32 v[38:39], v[210:211]
	v_mov_b64_e32 v[40:41], v[212:213]
	v_pk_mul_f32 v[42:43], v[34:35], v[40:41]
	v_pk_mul_f32 v[162:163], v[36:37], v[38:39]
	v_pk_mul_f32 v[40:41], v[18:19], v[40:41]
	v_pk_mul_f32 v[38:39], v[16:17], v[38:39]
	v_mov_b64_e32 v[148:149], v[194:195]
	v_mov_b64_e32 v[150:151], v[196:197]
	v_pk_fma_f32 v[18:19], v[18:19], v[150:151], v[42:43] neg_lo:[0,0,1] neg_hi:[0,0,1]
	v_pk_fma_f32 v[16:17], v[16:17], v[148:149], v[162:163] neg_lo:[0,0,1] neg_hi:[0,0,1]
	v_pk_fma_f32 v[34:35], v[34:35], v[150:151], v[40:41]
	v_pk_fma_f32 v[36:37], v[36:37], v[148:149], v[38:39]

; DI unsigned pk2(float a, float b) { f32x2 v = {a, b}; bf2_t r = __builtin_convertvector(v, bf2_t); return __builtin_bit_cast(unsigned, r); }
;     static DI void run(const f32x4 (&acc)[8][4], const TileCtx& tc, const Params& p, ldsp_t wb) {
;     ...
; #pragma unroll
;                     for (int ax = 0; ax < 2; ++ax) {
;                         f32x4 x1 = acc[m][2 * ax] * rstd * gv[2 * ax], x2 = acc[m][2 * ax + 1] * rstd * gv[2 * ax + 1];
;                         if (lat) {
;                             const int pos = ax == 0 ? (t >> 6) : (t & 63);
;                             const f32x4 cs = *(const f32x4*)(p.rope + pos * 16 + fq * 4), sn = *(const f32x4*)(p.rope + 1024 + pos * 16 + fq * 4);
;                             const f32x4 o1 = x1 * cs - x2 * sn, o2 = x2 * cs + x1 * sn;
;                             x1 = o1; x2 = o2;
;                         }
;                         u32x2 w; w[0] = pk2(x1[0], x1[1]); w[1] = pk2(x1[2], x1[3]);
;                         wave_put(wb, mm * 16 + fr, 2 * ax, fq, w);
;                         w[0] = pk2(x2[0], x2[1]); w[1] = pk2(x2[2], x2[3]);
;                         wave_put(wb, mm * 16 + fr, 2 * ax + 1, fq, w);
.LBB0_306:
	v_cvt_pk_bf16_f32 v16, v16, v17
	v_cvt_pk_bf16_f32 v17, v18, v19
	v_mov_b32_e32 v163, v162
	ds_write_b64 v177, v[16:17]
	v_cvt_pk_bf16_f32 v16, v166, v167
	v_cvt_pk_bf16_f32 v17, v164, v165
	v_mov_b32_e32 v148, v162
	v_mov_b32_e32 v149, v162
	ds_write_b64 v178, v[16:17]
	v_pk_mul_f32 v[16:17], v[76:77], v[148:149]
	v_pk_mul_f32 v[150:151], v[78:79], v[162:163]
	v_pk_mul_f32 v[18:19], v[6:7], v[16:17]
	v_pk_mul_f32 v[16:17], v[4:5], v[150:151]
	v_pk_mul_f32 v[148:149], v[72:73], v[148:149]
	v_pk_mul_f32 v[150:151], v[74:75], v[162:163]
	v_pk_mul_f32 v[162:163], v[2:3], v[148:149]
	s_and_b64 vcc, exec, s[4:5]
	v_pk_mul_f32 v[164:165], v[0:1], v[150:151]
	s_cbranch_vccnz .LBB0_308
	v_lshlrev_b32_e32 v166, 6, v169
	v_mov_b32_e32 v167, v193
	v_mov_b32_e32 v33, v193
	v_lshl_add_u64 v[148:149], s[18:19], 0, v[166:167]
	v_lshl_add_u64 v[148:149], v[148:149], 0, v[32:33]
	v_lshl_add_u64 v[166:167], s[68:69], 0, v[166:167]
	v_lshl_add_u64 v[166:167], v[166:167], 0, v[32:33]
	v_mov_b64_e32 v[148:149], v[232:233]
	v_mov_b64_e32 v[150:151], v[234:235]
	v_pk_mul_f32 v[166:167], v[162:163], v[150:151]
	v_pk_mul_f32 v[186:187], v[164:165], v[148:149]
	v_pk_mul_f32 v[150:151], v[18:19], v[150:151]
	v_pk_mul_f32 v[148:149], v[16:17], v[148:149]
	v_mov_b64_e32 v[182:183], v[236:237]
	v_mov_b64_e32 v[184:185], v[238:239]
	v_pk_fma_f32 v[18:19], v[18:19], v[184:185], v[166:167] neg_lo:[0,0,1] neg_hi:[0,0,1]
	v_pk_fma_f32 v[16:17], v[16:17], v[182:183], v[186:187] neg_lo:[0,0,1] neg_hi:[0,0,1]
	v_pk_fma_f32 v[162:163], v[162:163], v[184:185], v[150:151]
	v_pk_fma_f32 v[164:165], v[164:165], v[182:183], v[148:149]

; DI unsigned pk2(float a, float b) { f32x2 v = {a, b}; bf2_t r = __builtin_convertvector(v, bf2_t); return __builtin_bit_cast(unsigned, r); }
;     static DI void run(const f32x4 (&acc)[8][4], const TileCtx& tc, const Params& p, ldsp_t wb) {
;     ...
; #pragma unroll
;                     for (int ax = 0; ax < 2; ++ax) {
;                         f32x4 x1 = acc[m][2 * ax] * rstd * gv[2 * ax], x2 = acc[m][2 * ax + 1] * rstd * gv[2 * ax + 1];
;                         if (lat) {
;                             const int pos = ax == 0 ? (t >> 6) : (t & 63);
;                             const f32x4 cs = *(const f32x4*)(p.rope + pos * 16 + fq * 4), sn = *(const f32x4*)(p.rope + 1024 + pos * 16 + fq * 4);
;                             const f32x4 o1 = x1 * cs - x2 * sn, o2 = x2 * cs + x1 * sn;
;                             x1 = o1; x2 = o2;
;                         }
;                         u32x2 w; w[0] = pk2(x1[0], x1[1]); w[1] = pk2(x1[2], x1[3]);
;                         wave_put(wb, mm * 16 + fr, 2 * ax, fq, w);
;                         w[0] = pk2(x2[0], x2[1]); w[1] = pk2(x2[2], x2[3]);
;                         wave_put(wb, mm * 16 + fr, 2 * ax + 1, fq, w);
.LBB0_310:
	v_cvt_pk_bf16_f32 v16, v16, v17
	v_cvt_pk_bf16_f32 v17, v18, v19
	v_mov_b32_e32 v163, v162
	ds_write_b64 v177, v[16:17] offset:2048
	v_cvt_pk_bf16_f32 v16, v166, v167
	v_cvt_pk_bf16_f32 v17, v164, v165
	v_mov_b32_e32 v148, v162
	v_mov_b32_e32 v149, v162
	ds_write_b64 v178, v[16:17] offset:2048
	v_pk_mul_f32 v[16:17], v[60:61], v[148:149]
	v_pk_mul_f32 v[150:151], v[62:63], v[162:163]
	v_pk_mul_f32 v[18:19], v[6:7], v[16:17]
	v_pk_mul_f32 v[16:17], v[4:5], v[150:151]
	v_pk_mul_f32 v[148:149], v[56:57], v[148:149]
	v_pk_mul_f32 v[150:151], v[58:59], v[162:163]
	v_pk_mul_f32 v[162:163], v[2:3], v[148:149]
	s_and_b64 vcc, exec, s[4:5]
	v_pk_mul_f32 v[164:165], v[0:1], v[150:151]
	s_cbranch_vccnz .LBB0_312
	v_lshlrev_b32_e32 v33, 6, v182
	v_and_b32_e32 v166, 0x7c0, v33
	v_mov_b32_e32 v167, v193
	v_mov_b32_e32 v33, v193
	v_lshl_add_u64 v[148:149], s[18:19], 0, v[166:167]
	v_lshl_add_u64 v[148:149], v[148:149], 0, v[32:33]
	v_lshl_add_u64 v[166:167], s[68:69], 0, v[166:167]
	v_lshl_add_u64 v[166:167], v[166:167], 0, v[32:33]
	v_mov_b64_e32 v[148:149], v[240:241]
	v_mov_b64_e32 v[150:151], v[242:243]
	v_pk_mul_f32 v[166:167], v[162:163], v[150:151]
	v_pk_mul_f32 v[186:187], v[164:165], v[148:149]
	v_pk_mul_f32 v[150:151], v[18:19], v[150:151]
	v_pk_mul_f32 v[148:149], v[16:17], v[148:149]
	v_mov_b64_e32 v[182:183], v[244:245]
	v_mov_b64_e32 v[184:185], v[246:247]
	v_pk_fma_f32 v[18:19], v[18:19], v[184:185], v[166:167] neg_lo:[0,0,1] neg_hi:[0,0,1]
	v_pk_fma_f32 v[16:17], v[16:17], v[182:183], v[186:187] neg_lo:[0,0,1] neg_hi:[0,0,1]
	v_pk_fma_f32 v[162:163], v[162:163], v[184:185], v[150:151]
	v_pk_fma_f32 v[164:165], v[164:165], v[182:183], v[148:149]

; DI unsigned pk2(float a, float b) { f32x2 v = {a, b}; bf2_t r = __builtin_convertvector(v, bf2_t); return __builtin_bit_cast(unsigned, r); }
;     static DI void run(const f32x4 (&acc)[8][4], const TileCtx& tc, const Params& p, ldsp_t wb) {
;     ...
; #pragma unroll
;                     for (int ax = 0; ax < 2; ++ax) {
;                         f32x4 x1 = acc[m][2 * ax] * rstd * gv[2 * ax], x2 = acc[m][2 * ax + 1] * rstd * gv[2 * ax + 1];
;                         if (lat) {
;                             const int pos = ax == 0 ? (t >> 6) : (t & 63);
;                             const f32x4 cs = *(const f32x4*)(p.rope + pos * 16 + fq * 4), sn = *(const f32x4*)(p.rope + 1024 + pos * 16 + fq * 4);
;                             const f32x4 o1 = x1 * cs - x2 * sn, o2 = x2 * cs + x1 * sn;
;                             x1 = o1; x2 = o2;
;                         }
;                         u32x2 w; w[0] = pk2(x1[0], x1[1]); w[1] = pk2(x1[2], x1[3]);
;                         wave_put(wb, mm * 16 + fr, 2 * ax, fq, w);
;                         w[0] = pk2(x2[0], x2[1]); w[1] = pk2(x2[2], x2[3]);
;                         wave_put(wb, mm * 16 + fr, 2 * ax + 1, fq, w);
.LBB0_314:
	v_cvt_pk_bf16_f32 v16, v16, v17
	v_cvt_pk_bf16_f32 v17, v18, v19
	v_mov_b32_e32 v163, v162
	ds_write_b64 v177, v[16:17] offset:4096
	v_cvt_pk_bf16_f32 v16, v166, v167
	v_cvt_pk_bf16_f32 v17, v164, v165
	v_mov_b32_e32 v148, v162
	v_mov_b32_e32 v149, v162
	ds_write_b64 v178, v[16:17] offset:4096
	v_pk_mul_f32 v[16:17], v[52:53], v[148:149]
	v_pk_mul_f32 v[150:151], v[54:55], v[162:163]
	v_pk_mul_f32 v[18:19], v[6:7], v[16:17]
	v_pk_mul_f32 v[16:17], v[4:5], v[150:151]
	v_pk_mul_f32 v[148:149], v[48:49], v[148:149]
	v_pk_mul_f32 v[150:151], v[50:51], v[162:163]
	v_pk_mul_f32 v[162:163], v[2:3], v[148:149]
	s_and_b64 vcc, exec, s[4:5]
	v_pk_mul_f32 v[164:165], v[0:1], v[150:151]
	s_cbranch_vccnz .LBB0_316
	v_lshlrev_b32_e32 v33, 6, v182
	v_and_b32_e32 v166, 0xbc0, v33
	v_mov_b32_e32 v167, v193
	v_mov_b32_e32 v33, v193
	v_lshl_add_u64 v[148:149], s[18:19], 0, v[166:167]
	v_lshl_add_u64 v[148:149], v[148:149], 0, v[32:33]
	v_lshl_add_u64 v[166:167], s[68:69], 0, v[166:167]
	v_lshl_add_u64 v[166:167], v[166:167], 0, v[32:33]
	v_mov_b64_e32 v[148:149], v[248:249]
	v_mov_b64_e32 v[150:151], v[250:251]
	v_pk_mul_f32 v[166:167], v[162:163], v[150:151]
	v_pk_mul_f32 v[186:187], v[164:165], v[148:149]
	v_pk_mul_f32 v[150:151], v[18:19], v[150:151]
	v_pk_mul_f32 v[148:149], v[16:17], v[148:149]
	v_mov_b64_e32 v[182:183], v[204:205]
	v_mov_b64_e32 v[184:185], v[206:207]
	v_pk_fma_f32 v[18:19], v[18:19], v[184:185], v[166:167] neg_lo:[0,0,1] neg_hi:[0,0,1]
	v_pk_fma_f32 v[16:17], v[16:17], v[182:183], v[186:187] neg_lo:[0,0,1] neg_hi:[0,0,1]
	v_pk_fma_f32 v[162:163], v[162:163], v[184:185], v[150:151]
	v_pk_fma_f32 v[164:165], v[164:165], v[182:183], v[148:149]

; DI unsigned pk2(float a, float b) { f32x2 v = {a, b}; bf2_t r = __builtin_convertvector(v, bf2_t); return __builtin_bit_cast(unsigned, r); }
;     static DI void run(const f32x4 (&acc)[8][4], const TileCtx& tc, const Params& p, ldsp_t wb) {
;     ...
; #pragma unroll
;                     for (int ax = 0; ax < 2; ++ax) {
;                         f32x4 x1 = acc[m][2 * ax] * rstd * gv[2 * ax], x2 = acc[m][2 * ax + 1] * rstd * gv[2 * ax + 1];
;                         if (lat) {
;                             const int pos = ax == 0 ? (t >> 6) : (t & 63);
;                             const f32x4 cs = *(const f32x4*)(p.rope + pos * 16 + fq * 4), sn = *(const f32x4*)(p.rope + 1024 + pos * 16 + fq * 4);
;                             const f32x4 o1 = x1 * cs - x2 * sn, o2 = x2 * cs + x1 * sn;
;                             x1 = o1; x2 = o2;
;                         }
;                         u32x2 w; w[0] = pk2(x1[0], x1[1]); w[1] = pk2(x1[2], x1[3]);
;                         wave_put(wb, mm * 16 + fr, 2 * ax, fq, w);
;                         w[0] = pk2(x2[0], x2[1]); w[1] = pk2(x2[2], x2[3]);
;                         wave_put(wb, mm * 16 + fr, 2 * ax + 1, fq, w);
.LBB0_318:
	s_nop 0
	v_cvt_pk_bf16_f32 v8, v8, v9
	v_cvt_pk_bf16_f32 v9, v10, v11
	ds_write_b64 v178, v[8:9] offset:6144
	v_mov_b32_e32 v8, v16
	v_mov_b32_e32 v9, v16
	v_mov_b32_e32 v17, v16
	v_cvt_pk_bf16_f32 v12, v12, v13
	v_cvt_pk_bf16_f32 v13, v14, v15
	v_pk_mul_f32 v[10:11], v[24:25], v[8:9]
	ds_write_b64 v177, v[12:13] offset:6144
	v_pk_mul_f32 v[12:13], v[26:27], v[16:17]
	v_pk_mul_f32 v[6:7], v[6:7], v[10:11]
	v_pk_mul_f32 v[8:9], v[20:21], v[8:9]
	v_pk_mul_f32 v[10:11], v[22:23], v[16:17]
	v_pk_mul_f32 v[4:5], v[4:5], v[12:13]
	v_pk_mul_f32 v[2:3], v[2:3], v[8:9]
	s_and_b64 vcc, exec, s[4:5]
	v_pk_mul_f32 v[0:1], v[0:1], v[10:11]
	s_cbranch_vccnz .LBB0_320
	v_lshlrev_b32_e32 v8, 6, v18
	v_and_b32_e32 v12, 0xfc0, v8
	v_mov_b32_e32 v13, v193
	v_mov_b32_e32 v33, v193
	v_lshl_add_u64 v[8:9], s[18:19], 0, v[12:13]
	v_lshl_add_u64 v[8:9], v[8:9], 0, v[32:33]
	v_lshl_add_u64 v[12:13], s[68:69], 0, v[12:13]
	v_lshl_add_u64 v[12:13], v[12:13], 0, v[32:33]
	v_mov_b64_e32 v[8:9], v[210:211]
	v_mov_b64_e32 v[10:11], v[212:213]
	v_pk_mul_f32 v[16:17], v[2:3], v[10:11]
	v_pk_mul_f32 v[18:19], v[0:1], v[8:9]
	v_pk_mul_f32 v[10:11], v[6:7], v[10:11]
	v_pk_mul_f32 v[8:9], v[4:5], v[8:9]
	v_mov_b64_e32 v[12:13], v[194:195]
	v_mov_b64_e32 v[14:15], v[196:197]
	v_pk_fma_f32 v[6:7], v[6:7], v[14:15], v[16:17] neg_lo:[0,0,1] neg_hi:[0,0,1]
	v_pk_fma_f32 v[4:5], v[4:5], v[12:13], v[18:19] neg_lo:[0,0,1] neg_hi:[0,0,1]
	v_pk_fma_f32 v[2:3], v[2:3], v[14:15], v[10:11]
	v_pk_fma_f32 v[0:1], v[0:1], v[12:13], v[8:9]

; DI unsigned pk2(float a, float b) { f32x2 v = {a, b}; bf2_t r = __builtin_convertvector(v, bf2_t); return __builtin_bit_cast(unsigned, r); }
;     static DI void run(const f32x4 (&acc)[8][4], const TileCtx& tc, const Params& p, ldsp_t wb) {
;     ...
;                 for (int mm = 0; mm < 4; ++mm) { __builtin_amdgcn_sched_barrier(0);
;                     const int m = h * 4 + mm;
;                     const int row = tc.brow + tc.wr * 128 + m * 16 + fr;
;                     float ss = 0.f;
; #pragma unroll
;                     for (int n = 0; n < 4; ++n)
; #pragma unroll
;                         for (int j = 0; j < 4; ++j) ss += acc[m][n][j] * acc[m][n][j];
;                     ss += __shfl_xor(ss, 16);
;                     ss += __shfl_xor(ss, 32);
;                     const float rstd = rsqrtf(ss * (1.f / 64.f) + EPS) * osc;
;                     const int t = row & 4095;
; #pragma unroll
;                     for (int ax = 0; ax < 2; ++ax) {
;                         f32x4 x1 = acc[m][2 * ax] * rstd * gv[2 * ax], x2 = acc[m][2 * ax + 1] * rstd * gv[2 * ax + 1];
;                         if (lat) {
;                             const int pos = ax == 0 ? (t >> 6) : (t & 63);
;                             const f32x4 cs = *(const f32x4*)(p.rope + pos * 16 + fq * 4), sn = *(const f32x4*)(p.rope + 1024 + pos * 16 + fq * 4);
;                             const f32x4 o1 = x1 * cs - x2 * sn, o2 = x2 * cs + x1 * sn;
;                             x1 = o1; x2 = o2;
;                         }
;                         u32x2 w; w[0] = pk2(x1[0], x1[1]); w[1] = pk2(x1[2], x1[3]);
;                         wave_put(wb, mm * 16 + fr, 2 * ax, fq, w);
;                         w[0] = pk2(x2[0], x2[1]); w[1] = pk2(x2[2], x2[3]);
;                         wave_put(wb, mm * 16 + fr, 2 * ax + 1, fq, w);
;                     }
.LBB0_327:
	s_andn2_b64 vcc, exec, s[4:5]
	s_cbranch_vccnz .LBB0_256
	v_lshlrev_b32_e32 v32, 2, v175
	global_load_dwordx4 v[12:15], v32, s[12:13]
	global_load_dwordx4 v[8:11], v32, s[12:13] offset:64
	global_load_dwordx4 v[4:7], v32, s[12:13] offset:128
	global_load_dwordx4 v[0:3], v32, s[12:13] offset:192
	v_add_u32_e32 v190, s41, v174
	v_and_b32_e32 v190, 0xf80, v190
	v_add_u32_e32 v190, v190, v32
	v_lshl_add_u32 v191, v169, 6, v32
	global_load_dwordx4 v[220:223], v190, s[18:19]
	global_load_dwordx4 v[224:227], v190, s[68:69]
	global_load_dwordx4 v[232:235], v191, s[18:19]
	global_load_dwordx4 v[236:239], v191, s[68:69]
	global_load_dwordx4 v[240:243], v191, s[18:19] offset:1024
	global_load_dwordx4 v[244:247], v191, s[68:69] offset:1024
	global_load_dwordx4 v[248:251], v191, s[18:19] offset:2048
	global_load_dwordx4 v[178:181], v191, s[68:69] offset:2048
	global_load_dwordx4 v[182:185], v191, s[18:19] offset:3072
	global_load_dwordx4 v[186:189], v191, s[68:69] offset:3072
	global_load_dwordx4 v[204:207], v190, s[18:19] offset:64
	global_load_dwordx4 v[210:213], v190, s[68:69] offset:64
	s_cmp_lt_i32 s31, 64
	s_cselect_b64 s[6:7], -1, 0
	s_cmp_gt_i32 s31, 63
	s_cselect_b64 s[34:35], -1, 0
	v_mul_f32_e32 v33, v161, v161
	v_fmac_f32_e32 v33, v160, v160
	v_fmac_f32_e32 v33, v158, v158
	v_fmac_f32_e32 v33, v159, v159
	v_fmac_f32_e32 v33, v156, v156
	v_fmac_f32_e32 v33, v157, v157
	v_fmac_f32_e32 v33, v154, v154
	v_fmac_f32_e32 v33, v155, v155
	v_pk_mul_f32 v[18:19], v[152:153], v[152:153]
	v_pk_mul_f32 v[16:17], v[216:217], v[216:217]
	v_add_f32_e32 v18, v18, v33
	v_add_f32_e32 v18, v19, v18
	v_add_f32_e32 v16, v16, v18
	v_add_f32_e32 v33, v17, v16
	v_pk_mul_f32 v[18:19], v[214:215], v[214:215]
	v_pk_mul_f32 v[16:17], v[146:147], v[146:147]
	v_add_f32_e32 v18, v18, v33
	v_add_f32_e32 v18, v19, v18
	v_add_f32_e32 v16, v16, v18
	v_add_f32_e32 v16, v17, v16
	ds_bpermute_b32 v17, v113, v16
	v_add_u32_e32 v33, s41, v174
	s_waitcnt lgkmcnt(0)
	v_add_f32_e32 v16, v16, v17
	ds_bpermute_b32 v17, v168, v16
	s_waitcnt lgkmcnt(0)
	v_add_f32_e32 v16, v16, v17
	v_fmamk_f32 v16, v16, 0x3c800000, v208
	v_mul_f32_e32 v17, 0x4b800000, v16
	v_cmp_gt_f32_e32 vcc, s92, v16
	s_nop 1
	v_cndmask_b32_e32 v16, v16, v17, vcc
	v_rsq_f32_e32 v16, v16
	s_nop 0
	v_mul_f32_e32 v17, 0x45800000, v16
	v_cndmask_b32_e32 v16, v16, v17, vcc
	v_mul_f32_e32 v36, 0x3e38aa3b, v16
	v_pk_mul_f32 v[16:17], v[160:161], v[36:37] op_sel_hi:[1,0]
	v_pk_mul_f32 v[18:19], v[158:159], v[36:37] op_sel_hi:[1,0]
	v_pk_mul_f32 v[34:35], v[156:157], v[36:37] op_sel_hi:[1,0]
	v_pk_mul_f32 v[38:39], v[154:155], v[36:37] op_sel_hi:[1,0]
	s_waitcnt vmcnt(15)
	v_pk_mul_f32 v[18:19], v[14:15], v[18:19]
	v_pk_mul_f32 v[16:17], v[12:13], v[16:17]
	s_waitcnt vmcnt(14)
	v_pk_mul_f32 v[38:39], v[10:11], v[38:39]
	v_pk_mul_f32 v[40:41], v[8:9], v[34:35]
	s_and_b64 vcc, exec, s[34:35]
	v_and_b32_e32 v34, 0xf80, v33
	s_cbranch_vccnz .LBB0_330
	v_mov_b32_e32 v35, v193
	v_mov_b32_e32 v33, v193
	v_lshl_add_u64 v[42:43], s[18:19], 0, v[34:35]
	v_lshl_add_u64 v[42:43], v[42:43], 0, v[32:33]
	v_lshl_add_u64 v[42:43], s[68:69], 0, v[34:35]
	v_lshl_add_u64 v[42:43], v[42:43], 0, v[32:33]
	s_waitcnt vmcnt(0)
	v_mov_b64_e32 v[148:149], v[220:221]
	v_mov_b64_e32 v[150:151], v[222:223]
	v_pk_mul_f32 v[42:43], v[38:39], v[150:151]
	v_pk_mul_f32 v[158:159], v[40:41], v[148:149]
	v_pk_mul_f32 v[150:151], v[18:19], v[150:151]
	v_pk_mul_f32 v[148:149], v[16:17], v[148:149]
	v_mov_b64_e32 v[154:155], v[224:225]
	v_mov_b64_e32 v[156:157], v[226:227]
	v_pk_fma_f32 v[18:19], v[18:19], v[156:157], v[42:43] neg_lo:[0,0,1] neg_hi:[0,0,1]
	v_pk_fma_f32 v[16:17], v[16:17], v[154:155], v[158:159] neg_lo:[0,0,1] neg_hi:[0,0,1]
	v_pk_fma_f32 v[38:39], v[38:39], v[156:157], v[150:151]
	v_pk_fma_f32 v[40:41], v[40:41], v[154:155], v[148:149]
.LBB0_330:
	v_lshrrev_b32_e32 v35, 5, v170
	v_lshlrev_b32_e32 v43, 3, v173
	v_lshlrev_b32_e32 v33, 7, v169
	v_and_b32_e32 v43, 8, v43
	v_cvt_pk_bf16_f32 v16, v16, v17
	v_cvt_pk_bf16_f32 v17, v18, v19
	v_bitop3_b32 v18, v35, v172, 7 bitop3:0x78
	v_and_b32_e32 v42, 7, v172
	v_add3_u32 v43, v176, v33, v43
	v_lshlrev_b32_e32 v18, 4, v18
	v_add_u32_e32 v154, v43, v18
	v_bitop3_b32 v18, v35, v42, 2 bitop3:0x36
	v_lshlrev_b32_e32 v18, 4, v18
	v_mov_b32_e32 v37, v36
	ds_write_b64 v154, v[16:17]
	v_cvt_pk_bf16_f32 v16, v40, v41
	v_cvt_pk_bf16_f32 v17, v38, v39
	v_add_u32_e32 v155, v43, v18
	v_mov_b32_e32 v38, v36
	v_mov_b32_e32 v39, v36
	ds_write_b64 v155, v[16:17]
	v_pk_mul_f32 v[16:17], v[216:217], v[38:39]
	v_pk_mul_f32 v[40:41], v[152:153], v[36:37]
	v_pk_mul_f32 v[38:39], v[146:147], v[38:39]
	v_pk_mul_f32 v[36:37], v[214:215], v[36:37]
	v_cndmask_b32_e64 v33, 0, 1, s[6:7]
	s_waitcnt vmcnt(1)
	v_pk_mul_f32 v[18:19], v[6:7], v[16:17]
	v_pk_mul_f32 v[16:17], v[4:5], v[40:41]
	s_waitcnt vmcnt(0)
	v_pk_mul_f32 v[38:39], v[2:3], v[38:39]
	v_pk_mul_f32 v[40:41], v[0:1], v[36:37]
	v_cmp_ne_u32_e64 s[4:5], 1, v33
	s_andn2_b64 vcc, exec, s[6:7]
	v_lshlrev_b32_e32 v36, 6, v169
	s_cbranch_vccnz .LBB0_332
	v_mov_b32_e32 v37, v193
	v_mov_b32_e32 v33, v193
	v_lshl_add_u64 v[146:147], s[18:19], 0, v[36:37]
	v_lshl_add_u64 v[146:147], v[146:147], 0, v[32:33]
	v_lshl_add_u64 v[150:151], s[68:69], 0, v[36:37]
	v_lshl_add_u64 v[150:151], v[150:151], 0, v[32:33]
	v_mov_b64_e32 v[146:147], v[232:233]
	v_mov_b64_e32 v[148:149], v[234:235]
	v_pk_mul_f32 v[156:157], v[38:39], v[148:149]
	v_pk_mul_f32 v[158:159], v[40:41], v[146:147]
	v_pk_mul_f32 v[148:149], v[18:19], v[148:149]
	v_pk_mul_f32 v[146:147], v[16:17], v[146:147]
	v_mov_b64_e32 v[150:151], v[236:237]
	v_mov_b64_e32 v[152:153], v[238:239]
	v_pk_fma_f32 v[18:19], v[18:19], v[152:153], v[156:157] neg_lo:[0,0,1] neg_hi:[0,0,1]
	v_pk_fma_f32 v[16:17], v[16:17], v[150:151], v[158:159] neg_lo:[0,0,1] neg_hi:[0,0,1]
	v_pk_fma_f32 v[38:39], v[38:39], v[152:153], v[148:149]
	v_pk_fma_f32 v[40:41], v[40:41], v[150:151], v[146:147]
; DI unsigned pk2(float a, float b) { f32x2 v = {a, b}; bf2_t r = __builtin_convertvector(v, bf2_t); return __builtin_bit_cast(unsigned, r); }
;     static DI void run(const f32x4 (&acc)[8][4], const TileCtx& tc, const Params& p, ldsp_t wb) {
;     ...
;                 for (int mm = 0; mm < 4; ++mm) { __builtin_amdgcn_sched_barrier(0);
;                     const int m = h * 4 + mm;
;                     const int row = tc.brow + tc.wr * 128 + m * 16 + fr;
;                     float ss = 0.f;
; #pragma unroll
;                     for (int n = 0; n < 4; ++n)
; #pragma unroll
;                         for (int j = 0; j < 4; ++j) ss += acc[m][n][j] * acc[m][n][j];
;                     ss += __shfl_xor(ss, 16);
;                     ss += __shfl_xor(ss, 32);
;                     const float rstd = rsqrtf(ss * (1.f / 64.f) + EPS) * osc;
;                     const int t = row & 4095;
; #pragma unroll
;                     for (int ax = 0; ax < 2; ++ax) {
;                         f32x4 x1 = acc[m][2 * ax] * rstd * gv[2 * ax], x2 = acc[m][2 * ax + 1] * rstd * gv[2 * ax + 1];
;                         if (lat) {
;                             const int pos = ax == 0 ? (t >> 6) : (t & 63);
;                             const f32x4 cs = *(const f32x4*)(p.rope + pos * 16 + fq * 4), sn = *(const f32x4*)(p.rope + 1024 + pos * 16 + fq * 4);
;                             const f32x4 o1 = x1 * cs - x2 * sn, o2 = x2 * cs + x1 * sn;
;                             x1 = o1; x2 = o2;
;                         }
;                         u32x2 w; w[0] = pk2(x1[0], x1[1]); w[1] = pk2(x1[2], x1[3]);
;                         wave_put(wb, mm * 16 + fr, 2 * ax, fq, w);
;                         w[0] = pk2(x2[0], x2[1]); w[1] = pk2(x2[2], x2[3]);
;                         wave_put(wb, mm * 16 + fr, 2 * ax + 1, fq, w);
;                     }
.LBB0_332:
	v_cvt_pk_bf16_f32 v16, v16, v17
	v_cvt_pk_bf16_f32 v17, v18, v19
	v_bitop3_b32 v18, v35, v42, 4 bitop3:0x36
	v_lshlrev_b32_e32 v18, 4, v18
	v_add_u32_e32 v146, v43, v18
	v_bitop3_b32 v18, v35, v42, 6 bitop3:0x36
	v_lshlrev_b32_e32 v18, 4, v18
	ds_write_b64 v146, v[16:17]
	v_cvt_pk_bf16_f32 v16, v40, v41
	v_cvt_pk_bf16_f32 v17, v38, v39
	v_add_u32_e32 v147, v43, v18
	ds_write_b64 v147, v[16:17]
	v_mul_f32_e32 v33, v145, v145
	v_fmac_f32_e32 v33, v144, v144
	v_fmac_f32_e32 v33, v140, v140
	v_fmac_f32_e32 v33, v141, v141
	v_fmac_f32_e32 v33, v142, v142
	v_fmac_f32_e32 v33, v143, v143
	v_fmac_f32_e32 v33, v138, v138
	v_fmac_f32_e32 v33, v139, v139
	v_pk_mul_f32 v[18:19], v[128:129], v[128:129]
	v_pk_mul_f32 v[16:17], v[126:127], v[126:127]
	v_add_f32_e32 v18, v18, v33
	v_add_f32_e32 v18, v19, v18
	v_add_f32_e32 v16, v16, v18
	v_add_f32_e32 v33, v17, v16
	v_pk_mul_f32 v[18:19], v[124:125], v[124:125]
	v_pk_mul_f32 v[16:17], v[120:121], v[120:121]
	v_add_f32_e32 v18, v18, v33
	v_add_f32_e32 v18, v19, v18
	v_add_f32_e32 v16, v16, v18
	v_add_f32_e32 v16, v17, v16
	ds_bpermute_b32 v17, v113, v16
	s_and_b64 vcc, exec, s[4:5]
	s_waitcnt lgkmcnt(0)
	v_add_f32_e32 v16, v16, v17
	ds_bpermute_b32 v17, v168, v16
	s_waitcnt lgkmcnt(0)
	v_add_f32_e32 v16, v16, v17
	v_fmamk_f32 v16, v16, 0x3c800000, v208
	v_mul_f32_e32 v17, 0x4b800000, v16
	v_cmp_gt_f32_e64 s[6:7], s92, v16
	s_nop 1
	v_cndmask_b32_e64 v16, v16, v17, s[6:7]
	v_rsq_f32_e32 v16, v16
	s_nop 0
	v_mul_f32_e32 v17, 0x45800000, v16
	v_cndmask_b32_e64 v16, v16, v17, s[6:7]
	v_mul_f32_e32 v38, 0x3e38aa3b, v16
	v_pk_mul_f32 v[16:17], v[144:145], v[38:39] op_sel_hi:[1,0]
	v_pk_mul_f32 v[18:19], v[140:141], v[38:39] op_sel_hi:[1,0]
	v_pk_mul_f32 v[42:43], v[142:143], v[38:39] op_sel_hi:[1,0]
	v_pk_mul_f32 v[40:41], v[138:139], v[38:39] op_sel_hi:[1,0]
	v_pk_mul_f32 v[18:19], v[14:15], v[18:19]
	v_pk_mul_f32 v[16:17], v[12:13], v[16:17]
	v_pk_mul_f32 v[40:41], v[10:11], v[40:41]
	v_pk_mul_f32 v[42:43], v[8:9], v[42:43]
	s_cbranch_vccnz .LBB0_334
	v_mov_b32_e32 v35, v193
	v_mov_b32_e32 v33, v193
	v_lshl_add_u64 v[138:139], s[18:19], 0, v[34:35]
	v_lshl_add_u64 v[138:139], v[138:139], 0, v[32:33]
	v_lshl_add_u64 v[142:143], s[68:69], 0, v[34:35]
	v_lshl_add_u64 v[142:143], v[142:143], 0, v[32:33]
	v_mov_b64_e32 v[138:139], v[220:221]
	v_mov_b64_e32 v[140:141], v[222:223]
	v_pk_mul_f32 v[148:149], v[40:41], v[140:141]
	v_pk_mul_f32 v[150:151], v[42:43], v[138:139]
	v_pk_mul_f32 v[140:141], v[18:19], v[140:141]
	v_pk_mul_f32 v[138:139], v[16:17], v[138:139]
	v_mov_b64_e32 v[142:143], v[224:225]
	v_mov_b64_e32 v[144:145], v[226:227]
	v_pk_fma_f32 v[18:19], v[18:19], v[144:145], v[148:149] neg_lo:[0,0,1] neg_hi:[0,0,1]
	v_pk_fma_f32 v[16:17], v[16:17], v[142:143], v[150:151] neg_lo:[0,0,1] neg_hi:[0,0,1]
	v_pk_fma_f32 v[40:41], v[40:41], v[144:145], v[140:141]
	v_pk_fma_f32 v[42:43], v[42:43], v[142:143], v[138:139]
.LBB0_334:
	v_cvt_pk_bf16_f32 v16, v16, v17
	v_cvt_pk_bf16_f32 v17, v18, v19
	v_mov_b32_e32 v39, v38
	ds_write_b64 v154, v[16:17] offset:2048
	v_cvt_pk_bf16_f32 v16, v42, v43
	v_cvt_pk_bf16_f32 v17, v40, v41
	v_mov_b32_e32 v40, v38
	v_mov_b32_e32 v41, v38
	ds_write_b64 v155, v[16:17] offset:2048
	v_pk_mul_f32 v[16:17], v[126:127], v[40:41]
	v_pk_mul_f32 v[42:43], v[128:129], v[38:39]
	v_pk_mul_f32 v[18:19], v[6:7], v[16:17]
	v_pk_mul_f32 v[16:17], v[4:5], v[42:43]
	v_pk_mul_f32 v[40:41], v[120:121], v[40:41]
	v_pk_mul_f32 v[42:43], v[124:125], v[38:39]
	v_pk_mul_f32 v[38:39], v[2:3], v[40:41]
	s_and_b64 vcc, exec, s[4:5]
	v_pk_mul_f32 v[40:41], v[0:1], v[42:43]
	s_cbranch_vccnz .LBB0_336
	v_mov_b32_e32 v33, v193
	v_lshl_add_u64 v[42:43], s[18:19], 0, v[32:33]
	v_or_b32_e32 v192, 0x400, v36
	v_lshl_add_u64 v[42:43], v[42:43], 0, v[192:193]
	v_mov_b32_e32 v37, v193
	v_lshl_add_u64 v[42:43], s[68:69], 0, v[36:37]
	v_lshl_add_u64 v[42:43], v[42:43], 0, v[32:33]
	v_mov_b64_e32 v[124:125], v[240:241]
	v_mov_b64_e32 v[126:127], v[242:243]
	v_pk_mul_f32 v[42:43], v[38:39], v[126:127]
	v_pk_mul_f32 v[120:121], v[40:41], v[124:125]
	v_pk_mul_f32 v[126:127], v[18:19], v[126:127]
	v_pk_mul_f32 v[124:125], v[16:17], v[124:125]
	v_mov_b64_e32 v[138:139], v[244:245]
	v_mov_b64_e32 v[140:141], v[246:247]
	v_pk_fma_f32 v[18:19], v[18:19], v[140:141], v[42:43] neg_lo:[0,0,1] neg_hi:[0,0,1]
	v_pk_fma_f32 v[16:17], v[16:17], v[138:139], v[120:121] neg_lo:[0,0,1] neg_hi:[0,0,1]
	v_pk_fma_f32 v[38:39], v[38:39], v[140:141], v[126:127]
	v_pk_fma_f32 v[40:41], v[40:41], v[138:139], v[124:125]
; DI unsigned pk2(float a, float b) { f32x2 v = {a, b}; bf2_t r = __builtin_convertvector(v, bf2_t); return __builtin_bit_cast(unsigned, r); }
;     static DI void run(const f32x4 (&acc)[8][4], const TileCtx& tc, const Params& p, ldsp_t wb) {
;     ...
;                 for (int mm = 0; mm < 4; ++mm) { __builtin_amdgcn_sched_barrier(0);
;                     const int m = h * 4 + mm;
;                     const int row = tc.brow + tc.wr * 128 + m * 16 + fr;
;                     float ss = 0.f;
; #pragma unroll
;                     for (int n = 0; n < 4; ++n)
; #pragma unroll
;                         for (int j = 0; j < 4; ++j) ss += acc[m][n][j] * acc[m][n][j];
;                     ss += __shfl_xor(ss, 16);
;                     ss += __shfl_xor(ss, 32);
;                     const float rstd = rsqrtf(ss * (1.f / 64.f) + EPS) * osc;
;                     const int t = row & 4095;
; #pragma unroll
;                     for (int ax = 0; ax < 2; ++ax) {
;                         f32x4 x1 = acc[m][2 * ax] * rstd * gv[2 * ax], x2 = acc[m][2 * ax + 1] * rstd * gv[2 * ax + 1];
;                         if (lat) {
;                             const int pos = ax == 0 ? (t >> 6) : (t & 63);
;                             const f32x4 cs = *(const f32x4*)(p.rope + pos * 16 + fq * 4), sn = *(const f32x4*)(p.rope + 1024 + pos * 16 + fq * 4);
;                             const f32x4 o1 = x1 * cs - x2 * sn, o2 = x2 * cs + x1 * sn;
;                             x1 = o1; x2 = o2;
;                         }
;                         u32x2 w; w[0] = pk2(x1[0], x1[1]); w[1] = pk2(x1[2], x1[3]);
;                         wave_put(wb, mm * 16 + fr, 2 * ax, fq, w);
;                         w[0] = pk2(x2[0], x2[1]); w[1] = pk2(x2[2], x2[3]);
;                         wave_put(wb, mm * 16 + fr, 2 * ax + 1, fq, w);
;                     }
.LBB0_336:
	v_cvt_pk_bf16_f32 v16, v16, v17
	v_cvt_pk_bf16_f32 v17, v18, v19
	ds_write_b64 v146, v[16:17] offset:2048
	v_cvt_pk_bf16_f32 v16, v40, v41
	v_cvt_pk_bf16_f32 v17, v38, v39
	ds_write_b64 v147, v[16:17] offset:2048
	v_mul_f32_e32 v33, v137, v137
	v_fmac_f32_e32 v33, v136, v136
	v_fmac_f32_e32 v33, v132, v132
	v_fmac_f32_e32 v33, v133, v133
	v_fmac_f32_e32 v33, v134, v134
	v_fmac_f32_e32 v33, v135, v135
	v_fmac_f32_e32 v33, v130, v130
	v_fmac_f32_e32 v33, v131, v131
	v_pk_mul_f32 v[18:19], v[122:123], v[122:123]
	v_pk_mul_f32 v[16:17], v[118:119], v[118:119]
	v_add_f32_e32 v18, v18, v33
	v_add_f32_e32 v18, v19, v18
	v_add_f32_e32 v16, v16, v18
	v_add_f32_e32 v33, v17, v16
	v_pk_mul_f32 v[18:19], v[116:117], v[116:117]
	v_pk_mul_f32 v[16:17], v[114:115], v[114:115]
	v_add_f32_e32 v18, v18, v33
	v_add_f32_e32 v18, v19, v18
	v_add_f32_e32 v16, v16, v18
	v_add_f32_e32 v16, v17, v16
	ds_bpermute_b32 v17, v113, v16
	s_and_b64 vcc, exec, s[4:5]
	s_waitcnt lgkmcnt(0)
	v_add_f32_e32 v16, v16, v17
	ds_bpermute_b32 v17, v168, v16
	s_waitcnt lgkmcnt(0)
	v_add_f32_e32 v16, v16, v17
	v_fmamk_f32 v16, v16, 0x3c800000, v208
	v_mul_f32_e32 v17, 0x4b800000, v16
	v_cmp_gt_f32_e64 s[6:7], s92, v16
	s_nop 1
	v_cndmask_b32_e64 v16, v16, v17, s[6:7]
	v_rsq_f32_e32 v16, v16
	s_nop 0
	v_mul_f32_e32 v17, 0x45800000, v16
	v_cndmask_b32_e64 v16, v16, v17, s[6:7]
	v_mul_f32_e32 v38, 0x3e38aa3b, v16
	v_pk_mul_f32 v[16:17], v[136:137], v[38:39] op_sel_hi:[1,0]
	v_pk_mul_f32 v[18:19], v[132:133], v[38:39] op_sel_hi:[1,0]
	v_pk_mul_f32 v[42:43], v[134:135], v[38:39] op_sel_hi:[1,0]
	v_pk_mul_f32 v[40:41], v[130:131], v[38:39] op_sel_hi:[1,0]
	v_pk_mul_f32 v[18:19], v[14:15], v[18:19]
	v_pk_mul_f32 v[16:17], v[12:13], v[16:17]
	v_pk_mul_f32 v[40:41], v[10:11], v[40:41]
	v_pk_mul_f32 v[42:43], v[8:9], v[42:43]
	s_cbranch_vccnz .LBB0_338
	v_mov_b32_e32 v35, v193
	v_mov_b32_e32 v33, v193
	v_lshl_add_u64 v[120:121], s[18:19], 0, v[34:35]
	v_lshl_add_u64 v[120:121], v[120:121], 0, v[32:33]
	v_lshl_add_u64 v[120:121], s[68:69], 0, v[34:35]
	v_lshl_add_u64 v[120:121], v[120:121], 0, v[32:33]
	v_mov_b64_e32 v[124:125], v[220:221]
	v_mov_b64_e32 v[126:127], v[222:223]
	v_pk_mul_f32 v[120:121], v[40:41], v[126:127]
	v_pk_mul_f32 v[132:133], v[42:43], v[124:125]
	v_pk_mul_f32 v[126:127], v[18:19], v[126:127]
	v_pk_mul_f32 v[124:125], v[16:17], v[124:125]
	v_mov_b64_e32 v[128:129], v[224:225]
	v_mov_b64_e32 v[130:131], v[226:227]
	v_pk_fma_f32 v[18:19], v[18:19], v[130:131], v[120:121] neg_lo:[0,0,1] neg_hi:[0,0,1]
	v_pk_fma_f32 v[16:17], v[16:17], v[128:129], v[132:133] neg_lo:[0,0,1] neg_hi:[0,0,1]
	v_pk_fma_f32 v[40:41], v[40:41], v[130:131], v[126:127]
	v_pk_fma_f32 v[42:43], v[42:43], v[128:129], v[124:125]
.LBB0_338:
	v_cvt_pk_bf16_f32 v16, v16, v17
	v_cvt_pk_bf16_f32 v17, v18, v19
	v_mov_b32_e32 v39, v38
	ds_write_b64 v154, v[16:17] offset:4096
	v_cvt_pk_bf16_f32 v16, v42, v43
	v_cvt_pk_bf16_f32 v17, v40, v41
	v_mov_b32_e32 v40, v38
	v_mov_b32_e32 v41, v38
	ds_write_b64 v155, v[16:17] offset:4096
	v_pk_mul_f32 v[16:17], v[118:119], v[40:41]
	v_pk_mul_f32 v[42:43], v[122:123], v[38:39]
	v_pk_mul_f32 v[18:19], v[6:7], v[16:17]
	v_pk_mul_f32 v[16:17], v[4:5], v[42:43]
	v_pk_mul_f32 v[40:41], v[114:115], v[40:41]
	v_pk_mul_f32 v[42:43], v[116:117], v[38:39]
	v_pk_mul_f32 v[38:39], v[2:3], v[40:41]
	s_and_b64 vcc, exec, s[4:5]
	v_pk_mul_f32 v[40:41], v[0:1], v[42:43]
	s_cbranch_vccnz .LBB0_340
	v_mov_b32_e32 v33, v193
	v_lshl_add_u64 v[42:43], s[18:19], 0, v[32:33]
	v_or_b32_e32 v192, 0x800, v36
	v_lshl_add_u64 v[42:43], v[42:43], 0, v[192:193]
	v_mov_b32_e32 v37, v193
	v_lshl_add_u64 v[42:43], s[68:69], 0, v[36:37]
	v_lshl_add_u64 v[42:43], v[42:43], 0, v[32:33]
	v_mov_b64_e32 v[114:115], v[248:249]
	v_mov_b64_e32 v[116:117], v[250:251]
	v_pk_mul_f32 v[42:43], v[38:39], v[116:117]
	v_pk_mul_f32 v[122:123], v[40:41], v[114:115]
	v_pk_mul_f32 v[116:117], v[18:19], v[116:117]
	v_pk_mul_f32 v[114:115], v[16:17], v[114:115]
	v_mov_b64_e32 v[118:119], v[178:179]
	v_mov_b64_e32 v[120:121], v[180:181]
	v_pk_fma_f32 v[18:19], v[18:19], v[120:121], v[42:43] neg_lo:[0,0,1] neg_hi:[0,0,1]
	v_pk_fma_f32 v[16:17], v[16:17], v[118:119], v[122:123] neg_lo:[0,0,1] neg_hi:[0,0,1]
	v_pk_fma_f32 v[38:39], v[38:39], v[120:121], v[116:117]
	v_pk_fma_f32 v[40:41], v[40:41], v[118:119], v[114:115]
; DI unsigned pk2(float a, float b) { f32x2 v = {a, b}; bf2_t r = __builtin_convertvector(v, bf2_t); return __builtin_bit_cast(unsigned, r); }
;     static DI void run(const f32x4 (&acc)[8][4], const TileCtx& tc, const Params& p, ldsp_t wb) {
;     ...
;                 for (int mm = 0; mm < 4; ++mm) { __builtin_amdgcn_sched_barrier(0);
;                     const int m = h * 4 + mm;
;                     const int row = tc.brow + tc.wr * 128 + m * 16 + fr;
;                     float ss = 0.f;
; #pragma unroll
;                     for (int n = 0; n < 4; ++n)
; #pragma unroll
;                         for (int j = 0; j < 4; ++j) ss += acc[m][n][j] * acc[m][n][j];
;                     ss += __shfl_xor(ss, 16);
;                     ss += __shfl_xor(ss, 32);
;                     const float rstd = rsqrtf(ss * (1.f / 64.f) + EPS) * osc;
;                     const int t = row & 4095;
; #pragma unroll
;                     for (int ax = 0; ax < 2; ++ax) {
;                         f32x4 x1 = acc[m][2 * ax] * rstd * gv[2 * ax], x2 = acc[m][2 * ax + 1] * rstd * gv[2 * ax + 1];
;                         if (lat) {
;                             const int pos = ax == 0 ? (t >> 6) : (t & 63);
;                             const f32x4 cs = *(const f32x4*)(p.rope + pos * 16 + fq * 4), sn = *(const f32x4*)(p.rope + 1024 + pos * 16 + fq * 4);
;                             const f32x4 o1 = x1 * cs - x2 * sn, o2 = x2 * cs + x1 * sn;
;                             x1 = o1; x2 = o2;
;                         }
;                         u32x2 w; w[0] = pk2(x1[0], x1[1]); w[1] = pk2(x1[2], x1[3]);
;                         wave_put(wb, mm * 16 + fr, 2 * ax, fq, w);
;                         w[0] = pk2(x2[0], x2[1]); w[1] = pk2(x2[2], x2[3]);
;                         wave_put(wb, mm * 16 + fr, 2 * ax + 1, fq, w);
;                     }
.LBB0_340:
	v_cvt_pk_bf16_f32 v16, v16, v17
	v_cvt_pk_bf16_f32 v17, v18, v19
	ds_write_b64 v146, v[16:17] offset:4096
	v_cvt_pk_bf16_f32 v16, v40, v41
	v_cvt_pk_bf16_f32 v17, v38, v39
	ds_write_b64 v147, v[16:17] offset:4096
	v_mul_f32_e32 v33, v103, v103
	v_fmac_f32_e32 v33, v102, v102
	v_fmac_f32_e32 v33, v98, v98
	v_fmac_f32_e32 v33, v99, v99
	v_fmac_f32_e32 v33, v100, v100
	v_fmac_f32_e32 v33, v101, v101
	v_fmac_f32_e32 v33, v96, v96
	v_fmac_f32_e32 v33, v97, v97
	v_pk_mul_f32 v[18:19], v[94:95], v[94:95]
	v_pk_mul_f32 v[16:17], v[92:93], v[92:93]
	v_add_f32_e32 v18, v18, v33
	v_add_f32_e32 v18, v19, v18
	v_add_f32_e32 v16, v16, v18
	v_add_f32_e32 v33, v17, v16
	v_pk_mul_f32 v[18:19], v[90:91], v[90:91]
	v_pk_mul_f32 v[16:17], v[88:89], v[88:89]
	v_add_f32_e32 v18, v18, v33
	v_add_f32_e32 v18, v19, v18
	v_add_f32_e32 v16, v16, v18
	v_add_f32_e32 v16, v17, v16
	ds_bpermute_b32 v17, v113, v16
	s_and_b64 vcc, exec, s[4:5]
	s_waitcnt lgkmcnt(0)
	v_add_f32_e32 v16, v16, v17
	ds_bpermute_b32 v17, v168, v16
	s_waitcnt lgkmcnt(0)
	v_add_f32_e32 v16, v16, v17
	v_fmamk_f32 v16, v16, 0x3c800000, v208
	v_mul_f32_e32 v17, 0x4b800000, v16
	v_cmp_gt_f32_e64 s[6:7], s92, v16
	s_nop 1
	v_cndmask_b32_e64 v16, v16, v17, s[6:7]
	v_rsq_f32_e32 v16, v16
	s_nop 0
	v_mul_f32_e32 v17, 0x45800000, v16
	v_cndmask_b32_e64 v16, v16, v17, s[6:7]
	v_mul_f32_e32 v38, 0x3e38aa3b, v16
	v_pk_mul_f32 v[16:17], v[102:103], v[38:39] op_sel_hi:[1,0]
	v_pk_mul_f32 v[18:19], v[98:99], v[38:39] op_sel_hi:[1,0]
	v_pk_mul_f32 v[42:43], v[100:101], v[38:39] op_sel_hi:[1,0]
	v_pk_mul_f32 v[40:41], v[96:97], v[38:39] op_sel_hi:[1,0]
	v_pk_mul_f32 v[18:19], v[14:15], v[18:19]
	v_pk_mul_f32 v[16:17], v[12:13], v[16:17]
	v_pk_mul_f32 v[40:41], v[10:11], v[40:41]
	v_pk_mul_f32 v[42:43], v[8:9], v[42:43]
	s_cbranch_vccnz .LBB0_342
	v_mov_b32_e32 v35, v193
	v_mov_b32_e32 v33, v193
	v_lshl_add_u64 v[96:97], s[18:19], 0, v[34:35]
	v_lshl_add_u64 v[96:97], v[96:97], 0, v[32:33]
	v_lshl_add_u64 v[100:101], s[68:69], 0, v[34:35]
	v_lshl_add_u64 v[100:101], v[100:101], 0, v[32:33]
	v_mov_b64_e32 v[96:97], v[220:221]
	v_mov_b64_e32 v[98:99], v[222:223]
	v_pk_mul_f32 v[114:115], v[40:41], v[98:99]
	v_pk_mul_f32 v[116:117], v[42:43], v[96:97]
	v_pk_mul_f32 v[98:99], v[18:19], v[98:99]
	v_pk_mul_f32 v[96:97], v[16:17], v[96:97]
	v_mov_b64_e32 v[100:101], v[224:225]
	v_mov_b64_e32 v[102:103], v[226:227]
	v_pk_fma_f32 v[18:19], v[18:19], v[102:103], v[114:115] neg_lo:[0,0,1] neg_hi:[0,0,1]
	v_pk_fma_f32 v[16:17], v[16:17], v[100:101], v[116:117] neg_lo:[0,0,1] neg_hi:[0,0,1]
	v_pk_fma_f32 v[40:41], v[40:41], v[102:103], v[98:99]
	v_pk_fma_f32 v[42:43], v[42:43], v[100:101], v[96:97]
.LBB0_342:
	v_cvt_pk_bf16_f32 v16, v16, v17
	v_cvt_pk_bf16_f32 v17, v18, v19
	v_mov_b32_e32 v39, v38
	ds_write_b64 v154, v[16:17] offset:6144
	v_cvt_pk_bf16_f32 v16, v42, v43
	v_cvt_pk_bf16_f32 v17, v40, v41
	v_mov_b32_e32 v40, v38
	v_mov_b32_e32 v41, v38
	ds_write_b64 v155, v[16:17] offset:6144
	v_pk_mul_f32 v[16:17], v[92:93], v[40:41]
	v_pk_mul_f32 v[42:43], v[94:95], v[38:39]
	v_pk_mul_f32 v[18:19], v[6:7], v[16:17]
	v_pk_mul_f32 v[16:17], v[4:5], v[42:43]
	v_pk_mul_f32 v[40:41], v[88:89], v[40:41]
	v_pk_mul_f32 v[42:43], v[90:91], v[38:39]
	v_pk_mul_f32 v[38:39], v[2:3], v[40:41]
	s_and_b64 vcc, exec, s[4:5]
	v_pk_mul_f32 v[40:41], v[0:1], v[42:43]
	s_cbranch_vccnz .LBB0_344
	v_mov_b32_e32 v33, v193
	v_lshl_add_u64 v[42:43], s[18:19], 0, v[32:33]
	v_or_b32_e32 v192, 0xc00, v36
	v_lshl_add_u64 v[42:43], v[42:43], 0, v[192:193]
	v_mov_b32_e32 v37, v193
	v_lshl_add_u64 v[42:43], s[68:69], 0, v[36:37]
	v_lshl_add_u64 v[42:43], v[42:43], 0, v[32:33]
	v_mov_b64_e32 v[88:89], v[182:183]
	v_mov_b64_e32 v[90:91], v[184:185]
	v_pk_mul_f32 v[42:43], v[38:39], v[90:91]
	v_pk_mul_f32 v[96:97], v[40:41], v[88:89]
	v_pk_mul_f32 v[90:91], v[18:19], v[90:91]
	v_pk_mul_f32 v[88:89], v[16:17], v[88:89]
	v_mov_b64_e32 v[92:93], v[186:187]
	v_mov_b64_e32 v[94:95], v[188:189]
	v_pk_fma_f32 v[18:19], v[18:19], v[94:95], v[42:43] neg_lo:[0,0,1] neg_hi:[0,0,1]
	v_pk_fma_f32 v[16:17], v[16:17], v[92:93], v[96:97] neg_lo:[0,0,1] neg_hi:[0,0,1]
	v_pk_fma_f32 v[38:39], v[38:39], v[94:95], v[90:91]
	v_pk_fma_f32 v[40:41], v[40:41], v[92:93], v[88:89]

; #define LDSP __attribute__((address_space(3)))
; DI unsigned pk2(float a, float b) { f32x2 v = {a, b}; bf2_t r = __builtin_convertvector(v, bf2_t); return __builtin_bit_cast(unsigned, r); }
; DI void wave_rows_store(ldsp_t wb, int lane, bf16_t* dst0, size_t ld) {
; #pragma unroll
;     for (int i = 0; i < 8; ++i) {
;         const int row = i * 8 + (lane >> 3), ch = lane & 7;
;         const u32x4 v = *(const LDSP u32x4*)(wb + row * 128 + ((ch ^ (row & 7)) << 4));
;         *(u32x4*)(dst0 + (size_t)row * ld + ch * 8) = v;
;     }
; }
;     static DI void run(const f32x4 (&acc)[8][4], const TileCtx& tc, const Params& p, ldsp_t wb) {
;     ...
;                 for (int mm = 0; mm < 4; ++mm) { __builtin_amdgcn_sched_barrier(0);
;                     const int m = h * 4 + mm;
;                     const int row = tc.brow + tc.wr * 128 + m * 16 + fr;
;                     float ss = 0.f;
; #pragma unroll
;                     for (int n = 0; n < 4; ++n)
; #pragma unroll
;                         for (int j = 0; j < 4; ++j) ss += acc[m][n][j] * acc[m][n][j];
;                     ss += __shfl_xor(ss, 16);
;                     ss += __shfl_xor(ss, 32);
;                     const float rstd = rsqrtf(ss * (1.f / 64.f) + EPS) * osc;
;                     const int t = row & 4095;
; #pragma unroll
;                     for (int ax = 0; ax < 2; ++ax) {
;                         f32x4 x1 = acc[m][2 * ax] * rstd * gv[2 * ax], x2 = acc[m][2 * ax + 1] * rstd * gv[2 * ax + 1];
;                         if (lat) {
;                             const int pos = ax == 0 ? (t >> 6) : (t & 63);
;                             const f32x4 cs = *(const f32x4*)(p.rope + pos * 16 + fq * 4), sn = *(const f32x4*)(p.rope + 1024 + pos * 16 + fq * 4);
;                             const f32x4 o1 = x1 * cs - x2 * sn, o2 = x2 * cs + x1 * sn;
;                             x1 = o1; x2 = o2;
;                         }
;                         u32x2 w; w[0] = pk2(x1[0], x1[1]); w[1] = pk2(x1[2], x1[3]);
;                         wave_put(wb, mm * 16 + fr, 2 * ax, fq, w);
;                         w[0] = pk2(x2[0], x2[1]); w[1] = pk2(x2[2], x2[3]);
;                         wave_put(wb, mm * 16 + fr, 2 * ax + 1, fq, w);
;                     }
.LBB0_349:
	v_lshl_or_b32 v94, s98, 2, v171
	v_and_b32_e32 v17, -8, v17
	v_add_u32_e32 v18, v17, v94
	v_ashrrev_i32_e32 v19, 31, v18
	v_lshlrev_b64 v[18:19], s8, v[18:19]
	v_lshl_add_u64 v[18:19], s[6:7], 0, v[18:19]
	s_lshl_b32 s6, s9, 1
	v_lshlrev_b32_e32 v16, 7, v16
	v_and_b32_e32 v192, s6, v16
	v_lshl_add_u64 v[16:17], v[18:19], 0, v[192:193]
	v_lshrrev_b32_e32 v18, 3, v170
	v_xor_b32_e32 v19, v18, v170
	v_lshlrev_b32_e32 v19, 4, v19
	v_and_b32_e32 v19, 0x70, v19
	v_add_u32_e32 v95, v176, v19
	v_lshlrev_b32_e32 v19, 3, v170
	v_and_b32_e32 v19, 56, v19
	v_lshlrev_b32_e32 v192, 7, v18
	v_lshlrev_b32_e32 v40, 1, v19
	v_mov_b32_e32 v41, v193
	v_add_u32_e32 v33, v95, v192
	v_lshl_add_u64 v[92:93], v[16:17], 0, v[40:41]
	ds_read_b128 v[16:19], v33
	v_lshl_add_u64 v[38:39], v[92:93], 0, v[192:193]
	v_or_b32_e32 v88, 0x1400, v192
	v_mov_b32_e32 v89, v193
	v_or_b32_e32 v90, 0x1800, v192
	s_waitcnt lgkmcnt(0)
	global_store_dwordx4 v[38:39], v[16:19], off
	ds_read_b128 v[16:19], v33 offset:1024
	v_mov_b32_e32 v91, v193
	s_waitcnt lgkmcnt(0)
	global_store_dwordx4 v[38:39], v[16:19], off offset:1024
	ds_read_b128 v[16:19], v33 offset:2048
	s_waitcnt lgkmcnt(0)
	global_store_dwordx4 v[38:39], v[16:19], off offset:2048
	ds_read_b128 v[16:19], v33 offset:3072
	s_waitcnt lgkmcnt(0)
	global_store_dwordx4 v[38:39], v[16:19], off offset:3072
	ds_read_b128 v[16:19], v33 offset:4096
	v_or_b32_e32 v38, 0x1000, v192
	v_mov_b32_e32 v39, v193
	v_lshl_add_u64 v[42:43], v[92:93], 0, v[38:39]
	s_waitcnt lgkmcnt(0)
	global_store_dwordx4 v[42:43], v[16:19], off
	ds_read_b128 v[16:19], v33 offset:5120
	v_lshl_add_u64 v[42:43], v[92:93], 0, v[88:89]
	s_waitcnt lgkmcnt(0)
	global_store_dwordx4 v[42:43], v[16:19], off
	ds_read_b128 v[16:19], v33 offset:6144
	v_lshl_add_u64 v[42:43], v[92:93], 0, v[90:91]
	s_waitcnt lgkmcnt(0)
	global_store_dwordx4 v[42:43], v[16:19], off
	ds_read_b128 v[16:19], v33 offset:7168
	v_or_b32_e32 v42, 0x1c00, v192
	v_mov_b32_e32 v43, v193
	v_lshl_add_u64 v[92:93], v[92:93], 0, v[42:43]
	s_waitcnt lgkmcnt(0)
	global_store_dwordx4 v[92:93], v[16:19], off
	v_mul_f32_e32 v33, v87, v87
	v_fmac_f32_e32 v33, v86, v86
	v_fmac_f32_e32 v33, v82, v82
	v_fmac_f32_e32 v33, v83, v83
	v_fmac_f32_e32 v33, v84, v84
	v_fmac_f32_e32 v33, v85, v85
	v_fmac_f32_e32 v33, v80, v80
	v_fmac_f32_e32 v33, v81, v81
	v_pk_mul_f32 v[18:19], v[78:79], v[78:79]
	v_pk_mul_f32 v[16:17], v[76:77], v[76:77]
	v_add_f32_e32 v18, v18, v33
	v_add_f32_e32 v18, v19, v18
	v_add_f32_e32 v16, v16, v18
	v_add_f32_e32 v33, v17, v16
	v_pk_mul_f32 v[18:19], v[74:75], v[74:75]
	v_pk_mul_f32 v[16:17], v[72:73], v[72:73]
	v_add_f32_e32 v18, v18, v33
	v_add_f32_e32 v18, v19, v18
	v_add_f32_e32 v16, v16, v18
	v_add_f32_e32 v16, v17, v16
	ds_bpermute_b32 v17, v113, v16
	s_and_b64 vcc, exec, s[4:5]
	s_waitcnt lgkmcnt(0)
	v_add_f32_e32 v16, v16, v17
	ds_bpermute_b32 v17, v168, v16
	s_waitcnt lgkmcnt(0)
	v_add_f32_e32 v16, v16, v17
	v_fmamk_f32 v16, v16, 0x3c800000, v208
	v_mul_f32_e32 v17, 0x4b800000, v16
	v_cmp_gt_f32_e64 s[6:7], s92, v16
	s_nop 1
	v_cndmask_b32_e64 v16, v16, v17, s[6:7]
	v_rsq_f32_e32 v16, v16
	s_nop 0
	v_mul_f32_e32 v17, 0x45800000, v16
	v_cndmask_b32_e64 v16, v16, v17, s[6:7]
	v_mul_f32_e32 v92, 0x3e38aa3b, v16
	v_pk_mul_f32 v[16:17], v[86:87], v[92:93] op_sel_hi:[1,0]
	v_pk_mul_f32 v[18:19], v[82:83], v[92:93] op_sel_hi:[1,0]
	v_pk_mul_f32 v[82:83], v[84:85], v[92:93] op_sel_hi:[1,0]
	v_pk_mul_f32 v[80:81], v[80:81], v[92:93] op_sel_hi:[1,0]
	v_pk_mul_f32 v[18:19], v[14:15], v[18:19]
	v_pk_mul_f32 v[16:17], v[12:13], v[16:17]
	v_pk_mul_f32 v[80:81], v[10:11], v[80:81]
	v_pk_mul_f32 v[82:83], v[8:9], v[82:83]
	s_cbranch_vccnz .LBB0_351
	v_mov_b32_e32 v33, v193
	v_lshl_add_u64 v[84:85], s[18:19], 0, v[32:33]
	v_or_b32_e32 v86, 64, v34
	v_mov_b32_e32 v87, v193
	v_mov_b32_e32 v35, v193
	v_lshl_add_u64 v[84:85], v[84:85], 0, v[86:87]
	v_lshl_add_u64 v[34:35], s[68:69], 0, v[34:35]
	v_lshl_add_u64 v[34:35], v[34:35], 0, v[32:33]
	v_mov_b64_e32 v[84:85], v[204:205]
	v_mov_b64_e32 v[86:87], v[206:207]
	v_pk_mul_f32 v[34:35], v[80:81], v[86:87]
	v_pk_mul_f32 v[100:101], v[82:83], v[84:85]
	v_pk_mul_f32 v[86:87], v[18:19], v[86:87]
	v_pk_mul_f32 v[84:85], v[16:17], v[84:85]
	v_mov_b64_e32 v[96:97], v[210:211]
	v_mov_b64_e32 v[98:99], v[212:213]
	v_pk_fma_f32 v[18:19], v[18:19], v[98:99], v[34:35] neg_lo:[0,0,1] neg_hi:[0,0,1]
	v_pk_fma_f32 v[16:17], v[16:17], v[96:97], v[100:101] neg_lo:[0,0,1] neg_hi:[0,0,1]
	v_pk_fma_f32 v[80:81], v[80:81], v[98:99], v[86:87]
	v_pk_fma_f32 v[82:83], v[82:83], v[96:97], v[84:85]
.LBB0_351:
	v_cvt_pk_bf16_f32 v16, v16, v17
	v_cvt_pk_bf16_f32 v17, v18, v19
	v_mov_b32_e32 v93, v92
	ds_write_b64 v154, v[16:17]
	v_cvt_pk_bf16_f32 v16, v82, v83
	v_cvt_pk_bf16_f32 v17, v80, v81
	v_mov_b32_e32 v34, v92
	v_mov_b32_e32 v35, v92
	ds_write_b64 v155, v[16:17]
	v_pk_mul_f32 v[16:17], v[76:77], v[34:35]
	v_pk_mul_f32 v[76:77], v[78:79], v[92:93]
	v_pk_mul_f32 v[34:35], v[72:73], v[34:35]
	v_pk_mul_f32 v[72:73], v[74:75], v[92:93]
	v_pk_mul_f32 v[18:19], v[6:7], v[16:17]
	v_pk_mul_f32 v[16:17], v[4:5], v[76:77]
	v_pk_mul_f32 v[34:35], v[2:3], v[34:35]
	s_and_b64 vcc, exec, s[4:5]
	v_pk_mul_f32 v[72:73], v[0:1], v[72:73]
	s_cbranch_vccnz .LBB0_353
	v_mov_b32_e32 v37, v193
	v_mov_b32_e32 v33, v193
	v_lshl_add_u64 v[74:75], s[18:19], 0, v[36:37]
	v_lshl_add_u64 v[74:75], v[74:75], 0, v[32:33]
	v_lshl_add_u64 v[36:37], s[68:69], 0, v[36:37]
	v_lshl_add_u64 v[36:37], v[36:37], 0, v[32:33]
	v_mov_b64_e32 v[74:75], v[232:233]
	v_mov_b64_e32 v[76:77], v[234:235]
	v_pk_mul_f32 v[36:37], v[34:35], v[76:77]
	v_pk_mul_f32 v[82:83], v[72:73], v[74:75]
	v_pk_mul_f32 v[76:77], v[18:19], v[76:77]
	v_pk_mul_f32 v[74:75], v[16:17], v[74:75]
	v_mov_b64_e32 v[78:79], v[236:237]
	v_mov_b64_e32 v[80:81], v[238:239]
	v_pk_fma_f32 v[18:19], v[18:19], v[80:81], v[36:37] neg_lo:[0,0,1] neg_hi:[0,0,1]
	v_pk_fma_f32 v[16:17], v[16:17], v[78:79], v[82:83] neg_lo:[0,0,1] neg_hi:[0,0,1]
	v_pk_fma_f32 v[34:35], v[34:35], v[80:81], v[76:77]
	v_pk_fma_f32 v[72:73], v[72:73], v[78:79], v[74:75]
; DI unsigned pk2(float a, float b) { f32x2 v = {a, b}; bf2_t r = __builtin_convertvector(v, bf2_t); return __builtin_bit_cast(unsigned, r); }
;     static DI void run(const f32x4 (&acc)[8][4], const TileCtx& tc, const Params& p, ldsp_t wb) {
;     ...
;                 for (int mm = 0; mm < 4; ++mm) { __builtin_amdgcn_sched_barrier(0);
;                     const int m = h * 4 + mm;
;                     const int row = tc.brow + tc.wr * 128 + m * 16 + fr;
;                     float ss = 0.f;
; #pragma unroll
;                     for (int n = 0; n < 4; ++n)
; #pragma unroll
;                         for (int j = 0; j < 4; ++j) ss += acc[m][n][j] * acc[m][n][j];
;                     ss += __shfl_xor(ss, 16);
;                     ss += __shfl_xor(ss, 32);
;                     const float rstd = rsqrtf(ss * (1.f / 64.f) + EPS) * osc;
;                     const int t = row & 4095;
; #pragma unroll
;                     for (int ax = 0; ax < 2; ++ax) {
;                         f32x4 x1 = acc[m][2 * ax] * rstd * gv[2 * ax], x2 = acc[m][2 * ax + 1] * rstd * gv[2 * ax + 1];
;                         if (lat) {
;                             const int pos = ax == 0 ? (t >> 6) : (t & 63);
;                             const f32x4 cs = *(const f32x4*)(p.rope + pos * 16 + fq * 4), sn = *(const f32x4*)(p.rope + 1024 + pos * 16 + fq * 4);
;                             const f32x4 o1 = x1 * cs - x2 * sn, o2 = x2 * cs + x1 * sn;
;                             x1 = o1; x2 = o2;
;                         }
;                         u32x2 w; w[0] = pk2(x1[0], x1[1]); w[1] = pk2(x1[2], x1[3]);
;                         wave_put(wb, mm * 16 + fr, 2 * ax, fq, w);
;                         w[0] = pk2(x2[0], x2[1]); w[1] = pk2(x2[2], x2[3]);
;                         wave_put(wb, mm * 16 + fr, 2 * ax + 1, fq, w);
;                     }
.LBB0_353:
	v_cvt_pk_bf16_f32 v16, v16, v17
	v_cvt_pk_bf16_f32 v17, v18, v19
	ds_write_b64 v146, v[16:17]
	v_cvt_pk_bf16_f32 v16, v72, v73
	v_cvt_pk_bf16_f32 v17, v34, v35
	ds_write_b64 v147, v[16:17]
	v_mul_f32_e32 v33, v71, v71
	v_fmac_f32_e32 v33, v70, v70
	v_fmac_f32_e32 v33, v68, v68
	v_fmac_f32_e32 v33, v69, v69
	v_fmac_f32_e32 v33, v66, v66
	v_fmac_f32_e32 v33, v67, v67
	v_fmac_f32_e32 v33, v64, v64
	v_fmac_f32_e32 v33, v65, v65
	v_pk_mul_f32 v[18:19], v[62:63], v[62:63]
	v_pk_mul_f32 v[16:17], v[60:61], v[60:61]
	v_add_f32_e32 v18, v18, v33
	v_add_f32_e32 v18, v19, v18
	v_add_f32_e32 v16, v16, v18
	v_add_f32_e32 v33, v17, v16
	v_pk_mul_f32 v[18:19], v[58:59], v[58:59]
	v_pk_mul_f32 v[16:17], v[56:57], v[56:57]
	v_add_f32_e32 v18, v18, v33
	v_add_f32_e32 v18, v19, v18
	v_add_f32_e32 v16, v16, v18
	v_add_f32_e32 v16, v17, v16
	ds_bpermute_b32 v17, v113, v16
	v_or_b32_e32 v41, s41, v169
	v_or_b32_e32 v72, 0x50, v41
	s_waitcnt lgkmcnt(0)
	v_add_f32_e32 v16, v16, v17
	ds_bpermute_b32 v17, v168, v16
	s_waitcnt lgkmcnt(0)
	v_add_f32_e32 v16, v16, v17
	v_fmamk_f32 v16, v16, 0x3c800000, v208
	v_mul_f32_e32 v17, 0x4b800000, v16
	v_cmp_gt_f32_e32 vcc, s92, v16
	s_nop 1
	v_cndmask_b32_e32 v16, v16, v17, vcc
	v_rsq_f32_e32 v16, v16
	s_nop 0
	v_mul_f32_e32 v17, 0x45800000, v16
	v_cndmask_b32_e32 v16, v16, v17, vcc
	v_mul_f32_e32 v34, 0x3e38aa3b, v16
	v_pk_mul_f32 v[16:17], v[70:71], v[34:35] op_sel_hi:[1,0]
	v_pk_mul_f32 v[18:19], v[68:69], v[34:35] op_sel_hi:[1,0]
	v_pk_mul_f32 v[66:67], v[66:67], v[34:35] op_sel_hi:[1,0]
	v_pk_mul_f32 v[36:37], v[64:65], v[34:35] op_sel_hi:[1,0]
	v_pk_mul_f32 v[18:19], v[14:15], v[18:19]
	v_pk_mul_f32 v[16:17], v[12:13], v[16:17]
	v_pk_mul_f32 v[36:37], v[10:11], v[36:37]
	s_and_b64 vcc, exec, s[4:5]
	v_pk_mul_f32 v[64:65], v[8:9], v[66:67]
	s_cbranch_vccnz .LBB0_355
	v_add_u32_e32 v33, v72, v112
	v_and_b32_e32 v70, 0xfc0, v33
	v_mov_b32_e32 v71, v193
	v_mov_b32_e32 v33, v193
	v_lshl_add_u64 v[66:67], s[18:19], 0, v[70:71]
	v_lshl_add_u64 v[66:67], v[66:67], 0, v[32:33]
	v_lshl_add_u64 v[70:71], s[68:69], 0, v[70:71]
	v_lshl_add_u64 v[70:71], v[70:71], 0, v[32:33]
	v_mov_b64_e32 v[66:67], v[204:205]
	v_mov_b64_e32 v[68:69], v[206:207]
	v_pk_mul_f32 v[70:71], v[36:37], v[68:69]
	v_pk_mul_f32 v[78:79], v[64:65], v[66:67]
	v_pk_mul_f32 v[68:69], v[18:19], v[68:69]
	v_pk_mul_f32 v[66:67], v[16:17], v[66:67]
	v_mov_b64_e32 v[74:75], v[210:211]
	v_mov_b64_e32 v[76:77], v[212:213]
	v_pk_fma_f32 v[18:19], v[18:19], v[76:77], v[70:71] neg_lo:[0,0,1] neg_hi:[0,0,1]
	v_pk_fma_f32 v[16:17], v[16:17], v[74:75], v[78:79] neg_lo:[0,0,1] neg_hi:[0,0,1]
	v_pk_fma_f32 v[36:37], v[36:37], v[76:77], v[68:69]
	v_pk_fma_f32 v[64:65], v[64:65], v[74:75], v[66:67]
.LBB0_355:
	v_cvt_pk_bf16_f32 v16, v16, v17
	v_cvt_pk_bf16_f32 v17, v18, v19
	v_mov_b32_e32 v35, v34
	ds_write_b64 v154, v[16:17] offset:2048
	v_cvt_pk_bf16_f32 v16, v64, v65
	v_cvt_pk_bf16_f32 v17, v36, v37
	v_mov_b32_e32 v36, v34
	v_mov_b32_e32 v37, v34
	ds_write_b64 v155, v[16:17] offset:2048
	v_pk_mul_f32 v[16:17], v[60:61], v[36:37]
	v_pk_mul_f32 v[60:61], v[62:63], v[34:35]
	v_pk_mul_f32 v[36:37], v[56:57], v[36:37]
	v_pk_mul_f32 v[56:57], v[58:59], v[34:35]
	v_pk_mul_f32 v[18:19], v[6:7], v[16:17]
	v_pk_mul_f32 v[16:17], v[4:5], v[60:61]
	v_pk_mul_f32 v[34:35], v[2:3], v[36:37]
	s_and_b64 vcc, exec, s[4:5]
	v_pk_mul_f32 v[36:37], v[0:1], v[56:57]
	s_cbranch_vccnz .LBB0_357
	v_lshlrev_b32_e32 v33, 6, v72
	v_and_b32_e32 v60, 0x7c0, v33
	v_mov_b32_e32 v61, v193
	v_mov_b32_e32 v33, v193
	v_lshl_add_u64 v[56:57], s[18:19], 0, v[60:61]
	v_lshl_add_u64 v[56:57], v[56:57], 0, v[32:33]
	v_lshl_add_u64 v[60:61], s[68:69], 0, v[60:61]
	v_lshl_add_u64 v[60:61], v[60:61], 0, v[32:33]
	v_mov_b64_e32 v[56:57], v[240:241]
	v_mov_b64_e32 v[58:59], v[242:243]
	v_pk_mul_f32 v[64:65], v[34:35], v[58:59]
	v_pk_mul_f32 v[66:67], v[36:37], v[56:57]
	v_pk_mul_f32 v[58:59], v[18:19], v[58:59]
	v_pk_mul_f32 v[56:57], v[16:17], v[56:57]
	v_mov_b64_e32 v[60:61], v[244:245]
	v_mov_b64_e32 v[62:63], v[246:247]
	v_pk_fma_f32 v[18:19], v[18:19], v[62:63], v[64:65] neg_lo:[0,0,1] neg_hi:[0,0,1]
	v_pk_fma_f32 v[16:17], v[16:17], v[60:61], v[66:67] neg_lo:[0,0,1] neg_hi:[0,0,1]
	v_pk_fma_f32 v[34:35], v[34:35], v[62:63], v[58:59]
	v_pk_fma_f32 v[36:37], v[36:37], v[60:61], v[56:57]
; DI unsigned pk2(float a, float b) { f32x2 v = {a, b}; bf2_t r = __builtin_convertvector(v, bf2_t); return __builtin_bit_cast(unsigned, r); }
;     static DI void run(const f32x4 (&acc)[8][4], const TileCtx& tc, const Params& p, ldsp_t wb) {
;     ...
;                 for (int mm = 0; mm < 4; ++mm) { __builtin_amdgcn_sched_barrier(0);
;                     const int m = h * 4 + mm;
;                     const int row = tc.brow + tc.wr * 128 + m * 16 + fr;
;                     float ss = 0.f;
; #pragma unroll
;                     for (int n = 0; n < 4; ++n)
; #pragma unroll
;                         for (int j = 0; j < 4; ++j) ss += acc[m][n][j] * acc[m][n][j];
;                     ss += __shfl_xor(ss, 16);
;                     ss += __shfl_xor(ss, 32);
;                     const float rstd = rsqrtf(ss * (1.f / 64.f) + EPS) * osc;
;                     const int t = row & 4095;
; #pragma unroll
;                     for (int ax = 0; ax < 2; ++ax) {
;                         f32x4 x1 = acc[m][2 * ax] * rstd * gv[2 * ax], x2 = acc[m][2 * ax + 1] * rstd * gv[2 * ax + 1];
;                         if (lat) {
;                             const int pos = ax == 0 ? (t >> 6) : (t & 63);
;                             const f32x4 cs = *(const f32x4*)(p.rope + pos * 16 + fq * 4), sn = *(const f32x4*)(p.rope + 1024 + pos * 16 + fq * 4);
;                             const f32x4 o1 = x1 * cs - x2 * sn, o2 = x2 * cs + x1 * sn;
;                             x1 = o1; x2 = o2;
;                         }
;                         u32x2 w; w[0] = pk2(x1[0], x1[1]); w[1] = pk2(x1[2], x1[3]);
;                         wave_put(wb, mm * 16 + fr, 2 * ax, fq, w);
;                         w[0] = pk2(x2[0], x2[1]); w[1] = pk2(x2[2], x2[3]);
;                         wave_put(wb, mm * 16 + fr, 2 * ax + 1, fq, w);
;                     }
.LBB0_357:
	v_cvt_pk_bf16_f32 v16, v16, v17
	v_cvt_pk_bf16_f32 v17, v18, v19
	ds_write_b64 v146, v[16:17] offset:2048
	v_cvt_pk_bf16_f32 v16, v36, v37
	v_cvt_pk_bf16_f32 v17, v34, v35
	ds_write_b64 v147, v[16:17] offset:2048
	v_mul_f32_e32 v33, v111, v111
	v_fmac_f32_e32 v33, v110, v110
	v_fmac_f32_e32 v33, v108, v108
	v_fmac_f32_e32 v33, v109, v109
	v_fmac_f32_e32 v33, v106, v106
	v_fmac_f32_e32 v33, v107, v107
	v_fmac_f32_e32 v33, v104, v104
	v_fmac_f32_e32 v33, v105, v105
	v_pk_mul_f32 v[18:19], v[54:55], v[54:55]
	v_pk_mul_f32 v[16:17], v[52:53], v[52:53]
	v_add_f32_e32 v18, v18, v33
	v_add_f32_e32 v18, v19, v18
	v_add_f32_e32 v16, v16, v18
	v_add_f32_e32 v33, v17, v16
	v_pk_mul_f32 v[18:19], v[50:51], v[50:51]
	v_pk_mul_f32 v[16:17], v[48:49], v[48:49]
	v_add_f32_e32 v18, v18, v33
	v_add_f32_e32 v18, v19, v18
	v_add_f32_e32 v16, v16, v18
	v_add_f32_e32 v16, v17, v16
	ds_bpermute_b32 v17, v113, v16
	v_or_b32_e32 v58, 0x60, v41
	s_waitcnt lgkmcnt(0)
	v_add_f32_e32 v16, v16, v17
	ds_bpermute_b32 v17, v168, v16
	s_waitcnt lgkmcnt(0)
	v_add_f32_e32 v16, v16, v17
	v_fmamk_f32 v16, v16, 0x3c800000, v208
	v_mul_f32_e32 v17, 0x4b800000, v16
	v_cmp_gt_f32_e32 vcc, s92, v16
	s_nop 1
	v_cndmask_b32_e32 v16, v16, v17, vcc
	v_rsq_f32_e32 v16, v16
	s_nop 0
	v_mul_f32_e32 v17, 0x45800000, v16
	v_cndmask_b32_e32 v16, v16, v17, vcc
	v_mul_f32_e32 v34, 0x3e38aa3b, v16
	v_pk_mul_f32 v[16:17], v[110:111], v[34:35] op_sel_hi:[1,0]
	v_pk_mul_f32 v[18:19], v[108:109], v[34:35] op_sel_hi:[1,0]
	v_pk_mul_f32 v[56:57], v[106:107], v[34:35] op_sel_hi:[1,0]
	v_pk_mul_f32 v[36:37], v[104:105], v[34:35] op_sel_hi:[1,0]
	v_pk_mul_f32 v[18:19], v[14:15], v[18:19]
	v_pk_mul_f32 v[16:17], v[12:13], v[16:17]
	v_pk_mul_f32 v[36:37], v[10:11], v[36:37]
	s_and_b64 vcc, exec, s[4:5]
	v_pk_mul_f32 v[56:57], v[8:9], v[56:57]
	s_cbranch_vccnz .LBB0_359
	v_add_u32_e32 v33, v58, v112
	v_and_b32_e32 v64, 0xfc0, v33
	v_mov_b32_e32 v65, v193
	v_mov_b32_e32 v33, v193
	v_lshl_add_u64 v[60:61], s[18:19], 0, v[64:65]
	v_lshl_add_u64 v[60:61], v[60:61], 0, v[32:33]
	v_lshl_add_u64 v[64:65], s[68:69], 0, v[64:65]
	v_lshl_add_u64 v[64:65], v[64:65], 0, v[32:33]
	v_mov_b64_e32 v[60:61], v[204:205]
	v_mov_b64_e32 v[62:63], v[206:207]
	v_pk_mul_f32 v[68:69], v[36:37], v[62:63]
	v_pk_mul_f32 v[70:71], v[56:57], v[60:61]
	v_pk_mul_f32 v[62:63], v[18:19], v[62:63]
	v_pk_mul_f32 v[60:61], v[16:17], v[60:61]
	v_mov_b64_e32 v[64:65], v[210:211]
	v_mov_b64_e32 v[66:67], v[212:213]
	v_pk_fma_f32 v[18:19], v[18:19], v[66:67], v[68:69] neg_lo:[0,0,1] neg_hi:[0,0,1]
	v_pk_fma_f32 v[16:17], v[16:17], v[64:65], v[70:71] neg_lo:[0,0,1] neg_hi:[0,0,1]
	v_pk_fma_f32 v[36:37], v[36:37], v[66:67], v[62:63]
	v_pk_fma_f32 v[56:57], v[56:57], v[64:65], v[60:61]
.LBB0_359:
	v_cvt_pk_bf16_f32 v16, v16, v17
	v_cvt_pk_bf16_f32 v17, v18, v19
	v_mov_b32_e32 v35, v34
	ds_write_b64 v154, v[16:17] offset:4096
	v_cvt_pk_bf16_f32 v16, v56, v57
	v_cvt_pk_bf16_f32 v17, v36, v37
	v_mov_b32_e32 v36, v34
	v_mov_b32_e32 v37, v34
	ds_write_b64 v155, v[16:17] offset:4096
	v_pk_mul_f32 v[16:17], v[52:53], v[36:37]
	v_pk_mul_f32 v[52:53], v[54:55], v[34:35]
	v_pk_mul_f32 v[36:37], v[48:49], v[36:37]
	v_pk_mul_f32 v[48:49], v[50:51], v[34:35]
	v_pk_mul_f32 v[18:19], v[6:7], v[16:17]
	v_pk_mul_f32 v[16:17], v[4:5], v[52:53]
	v_pk_mul_f32 v[34:35], v[2:3], v[36:37]
	s_and_b64 vcc, exec, s[4:5]
	v_pk_mul_f32 v[36:37], v[0:1], v[48:49]
	s_cbranch_vccnz .LBB0_361
	v_lshlrev_b32_e32 v33, 6, v58
	v_and_b32_e32 v52, 0xbc0, v33
	v_mov_b32_e32 v53, v193
	v_mov_b32_e32 v33, v193
	v_lshl_add_u64 v[48:49], s[18:19], 0, v[52:53]
	v_lshl_add_u64 v[48:49], v[48:49], 0, v[32:33]
	v_lshl_add_u64 v[52:53], s[68:69], 0, v[52:53]
	v_lshl_add_u64 v[52:53], v[52:53], 0, v[32:33]
	v_mov_b64_e32 v[48:49], v[248:249]
	v_mov_b64_e32 v[50:51], v[250:251]
	v_pk_mul_f32 v[56:57], v[34:35], v[50:51]
	v_pk_mul_f32 v[58:59], v[36:37], v[48:49]
	v_pk_mul_f32 v[50:51], v[18:19], v[50:51]
	v_pk_mul_f32 v[48:49], v[16:17], v[48:49]
	v_mov_b64_e32 v[52:53], v[178:179]
	v_mov_b64_e32 v[54:55], v[180:181]
	v_pk_fma_f32 v[18:19], v[18:19], v[54:55], v[56:57] neg_lo:[0,0,1] neg_hi:[0,0,1]
	v_pk_fma_f32 v[16:17], v[16:17], v[52:53], v[58:59] neg_lo:[0,0,1] neg_hi:[0,0,1]
	v_pk_fma_f32 v[34:35], v[34:35], v[54:55], v[50:51]
	v_pk_fma_f32 v[36:37], v[36:37], v[52:53], v[48:49]
; DI unsigned pk2(float a, float b) { f32x2 v = {a, b}; bf2_t r = __builtin_convertvector(v, bf2_t); return __builtin_bit_cast(unsigned, r); }
;     static DI void run(const f32x4 (&acc)[8][4], const TileCtx& tc, const Params& p, ldsp_t wb) {
;     ...
;                 for (int mm = 0; mm < 4; ++mm) { __builtin_amdgcn_sched_barrier(0);
;                     const int m = h * 4 + mm;
;                     const int row = tc.brow + tc.wr * 128 + m * 16 + fr;
;                     float ss = 0.f;
; #pragma unroll
;                     for (int n = 0; n < 4; ++n)
; #pragma unroll
;                         for (int j = 0; j < 4; ++j) ss += acc[m][n][j] * acc[m][n][j];
;                     ss += __shfl_xor(ss, 16);
;                     ss += __shfl_xor(ss, 32);
;                     const float rstd = rsqrtf(ss * (1.f / 64.f) + EPS) * osc;
;                     const int t = row & 4095;
; #pragma unroll
;                     for (int ax = 0; ax < 2; ++ax) {
;                         f32x4 x1 = acc[m][2 * ax] * rstd * gv[2 * ax], x2 = acc[m][2 * ax + 1] * rstd * gv[2 * ax + 1];
;                         if (lat) {
;                             const int pos = ax == 0 ? (t >> 6) : (t & 63);
;                             const f32x4 cs = *(const f32x4*)(p.rope + pos * 16 + fq * 4), sn = *(const f32x4*)(p.rope + 1024 + pos * 16 + fq * 4);
;                             const f32x4 o1 = x1 * cs - x2 * sn, o2 = x2 * cs + x1 * sn;
;                             x1 = o1; x2 = o2;
;                         }
;                         u32x2 w; w[0] = pk2(x1[0], x1[1]); w[1] = pk2(x1[2], x1[3]);
;                         wave_put(wb, mm * 16 + fr, 2 * ax, fq, w);
;                         w[0] = pk2(x2[0], x2[1]); w[1] = pk2(x2[2], x2[3]);
;                         wave_put(wb, mm * 16 + fr, 2 * ax + 1, fq, w);
;                     }
.LBB0_361:
	v_cvt_pk_bf16_f32 v16, v16, v17
	v_cvt_pk_bf16_f32 v17, v18, v19
	ds_write_b64 v146, v[16:17] offset:4096
	v_cvt_pk_bf16_f32 v16, v36, v37
	v_cvt_pk_bf16_f32 v17, v34, v35
	ds_write_b64 v147, v[16:17] offset:4096
	v_mul_f32_e32 v33, v45, v45
	v_fmac_f32_e32 v33, v44, v44
	v_fmac_f32_e32 v33, v46, v46
	v_fmac_f32_e32 v33, v47, v47
	v_fmac_f32_e32 v33, v30, v30
	v_fmac_f32_e32 v33, v31, v31
	v_fmac_f32_e32 v33, v28, v28
	v_fmac_f32_e32 v33, v29, v29
	v_pk_mul_f32 v[18:19], v[26:27], v[26:27]
	v_pk_mul_f32 v[16:17], v[24:25], v[24:25]
	v_add_f32_e32 v18, v18, v33
	v_add_f32_e32 v18, v19, v18
	v_add_f32_e32 v16, v16, v18
	v_add_f32_e32 v33, v17, v16
	v_pk_mul_f32 v[18:19], v[22:23], v[22:23]
	v_pk_mul_f32 v[16:17], v[20:21], v[20:21]
	v_add_f32_e32 v18, v18, v33
	v_add_f32_e32 v18, v19, v18
	v_add_f32_e32 v16, v16, v18
	v_add_f32_e32 v16, v17, v16
	ds_bpermute_b32 v17, v113, v16
	v_or_b32_e32 v18, 0x70, v41
	s_waitcnt lgkmcnt(0)
	v_add_f32_e32 v16, v16, v17
	ds_bpermute_b32 v17, v168, v16
	s_waitcnt lgkmcnt(0)
	v_add_f32_e32 v16, v16, v17
	v_fmamk_f32 v16, v16, 0x3c800000, v208
	v_mul_f32_e32 v17, 0x4b800000, v16
	v_cmp_gt_f32_e32 vcc, s92, v16
	s_nop 1
	v_cndmask_b32_e32 v16, v16, v17, vcc
	v_rsq_f32_e32 v16, v16
	s_nop 0
	v_mul_f32_e32 v17, 0x45800000, v16
	v_cndmask_b32_e32 v16, v16, v17, vcc
	v_mul_f32_e32 v16, 0x3e38aa3b, v16
	v_pk_mul_f32 v[34:35], v[44:45], v[16:17] op_sel_hi:[1,0]
	v_pk_mul_f32 v[36:37], v[46:47], v[16:17] op_sel_hi:[1,0]
	v_pk_mul_f32 v[30:31], v[30:31], v[16:17] op_sel_hi:[1,0]
	v_pk_mul_f32 v[28:29], v[28:29], v[16:17] op_sel_hi:[1,0]
	v_pk_mul_f32 v[14:15], v[14:15], v[36:37]
	v_pk_mul_f32 v[12:13], v[12:13], v[34:35]
	v_pk_mul_f32 v[10:11], v[10:11], v[28:29]
	s_and_b64 vcc, exec, s[4:5]
	v_pk_mul_f32 v[8:9], v[8:9], v[30:31]
	s_cbranch_vccnz .LBB0_363
	v_add_u32_e32 v17, v18, v112
	v_and_b32_e32 v34, 0xfc0, v17
	v_mov_b32_e32 v35, v193
	v_mov_b32_e32 v33, v193
	v_lshl_add_u64 v[28:29], s[18:19], 0, v[34:35]
	v_lshl_add_u64 v[28:29], v[28:29], 0, v[32:33]
	v_lshl_add_u64 v[34:35], s[68:69], 0, v[34:35]
	v_lshl_add_u64 v[34:35], v[34:35], 0, v[32:33]
	v_mov_b64_e32 v[28:29], v[204:205]
	v_mov_b64_e32 v[30:31], v[206:207]
	v_pk_mul_f32 v[44:45], v[10:11], v[30:31]
	v_pk_mul_f32 v[46:47], v[8:9], v[28:29]
	v_pk_mul_f32 v[30:31], v[14:15], v[30:31]
	v_pk_mul_f32 v[28:29], v[12:13], v[28:29]
	v_mov_b64_e32 v[34:35], v[210:211]
	v_mov_b64_e32 v[36:37], v[212:213]
	v_pk_fma_f32 v[14:15], v[14:15], v[36:37], v[44:45] neg_lo:[0,0,1] neg_hi:[0,0,1]
	v_pk_fma_f32 v[12:13], v[12:13], v[34:35], v[46:47] neg_lo:[0,0,1] neg_hi:[0,0,1]
	v_pk_fma_f32 v[10:11], v[10:11], v[36:37], v[30:31]
	v_pk_fma_f32 v[8:9], v[8:9], v[34:35], v[28:29]
.LBB0_363:
	s_nop 0
	v_cvt_pk_bf16_f32 v8, v8, v9
	v_cvt_pk_bf16_f32 v9, v10, v11
	ds_write_b64 v155, v[8:9] offset:6144
	v_mov_b32_e32 v8, v16
	v_mov_b32_e32 v9, v16
	v_mov_b32_e32 v17, v16
	v_cvt_pk_bf16_f32 v12, v12, v13
	v_cvt_pk_bf16_f32 v13, v14, v15
	v_pk_mul_f32 v[10:11], v[24:25], v[8:9]
	ds_write_b64 v154, v[12:13] offset:6144
	v_pk_mul_f32 v[12:13], v[26:27], v[16:17]
	v_pk_mul_f32 v[6:7], v[6:7], v[10:11]
	v_pk_mul_f32 v[8:9], v[20:21], v[8:9]
	v_pk_mul_f32 v[10:11], v[22:23], v[16:17]
	v_pk_mul_f32 v[4:5], v[4:5], v[12:13]
	v_pk_mul_f32 v[2:3], v[2:3], v[8:9]
	s_and_b64 vcc, exec, s[4:5]
	v_pk_mul_f32 v[0:1], v[0:1], v[10:11]
	s_cbranch_vccnz .LBB0_365
	v_lshlrev_b32_e32 v8, 6, v18
	v_and_b32_e32 v12, 0xfc0, v8
	v_mov_b32_e32 v13, v193
	v_mov_b32_e32 v33, v193
	v_lshl_add_u64 v[8:9], s[18:19], 0, v[12:13]
	v_lshl_add_u64 v[8:9], v[8:9], 0, v[32:33]
	v_lshl_add_u64 v[12:13], s[68:69], 0, v[12:13]
	v_lshl_add_u64 v[12:13], v[12:13], 0, v[32:33]
	v_mov_b64_e32 v[8:9], v[182:183]
	v_mov_b64_e32 v[10:11], v[184:185]
	v_pk_mul_f32 v[16:17], v[2:3], v[10:11]
	v_pk_mul_f32 v[18:19], v[0:1], v[8:9]
	v_pk_mul_f32 v[10:11], v[6:7], v[10:11]
	v_pk_mul_f32 v[8:9], v[4:5], v[8:9]
	v_mov_b64_e32 v[12:13], v[186:187]
	v_mov_b64_e32 v[14:15], v[188:189]
	v_pk_fma_f32 v[6:7], v[6:7], v[14:15], v[16:17] neg_lo:[0,0,1] neg_hi:[0,0,1]
	v_pk_fma_f32 v[4:5], v[4:5], v[12:13], v[18:19] neg_lo:[0,0,1] neg_hi:[0,0,1]
	v_pk_fma_f32 v[2:3], v[2:3], v[14:15], v[10:11]
	v_pk_fma_f32 v[0:1], v[0:1], v[12:13], v[8:9]
